# large GEMM-epilogue output stores marked non-temporal (cache-policy lever)
# baseline (speedup 1.0000x reference)
;     __device__ __forceinline__ void operator()(f32x4 (&acc)[2][2][4][2], const Unit& u, int ui, int wr, int wc, int fr_, int fq_) const {
;     ...
;             for (int m = 0; m < 4; ++m) { const float r = rtab[ui * 256 + ai * HALF + wr * 64 + m * 16 + fr];
; #pragma unroll
;                 for (int bj = 0; bj < 2; ++bj)
; #pragma unroll
;                     for (int n = 0; n < 2; ++n) acc[ai][bj][m][n] = acc[ai][bj][m][n] * r; }
.LBB0_289:
	s_lshl_b32 s17, s51, 10
	v_mov_b32_e32 v154, v144
	v_mov_b32_e32 v155, v145
	s_add_i32 s17, s47, s17
	s_lshl_b32 s21, s49, 8
	v_lshl_add_u32 v156, v154, 2, s17
	ds_read2_b32 v[148:149], v156 offset1:16
	s_lshl_b32 s17, s50, 8
	s_add_i32 s17, s17, s43
	s_or_b32 s21, s21, s44
	s_mov_b64 s[26:27], 0x40000
	s_waitcnt lgkmcnt(0)
	v_pk_mul_f32 v[142:143], v[128:129], v[148:149] op_sel_hi:[1,0]
	v_pk_mul_f32 v[150:151], v[126:127], v[148:149] op_sel_hi:[1,0]
	v_pk_mul_f32 v[140:141], v[124:125], v[148:149] op_sel_hi:[1,0]
	v_pk_mul_f32 v[152:153], v[122:123], v[148:149] op_sel_hi:[1,0]
	v_pk_mul_f32 v[124:125], v[112:113], v[148:149] op_sel_hi:[1,0]
	v_pk_mul_f32 v[128:129], v[110:111], v[148:149] op_sel_hi:[1,0]
	v_pk_mul_f32 v[122:123], v[108:109], v[148:149] op_sel_hi:[1,0]
	v_pk_mul_f32 v[126:127], v[106:107], v[148:149] op_sel_hi:[1,0]
	v_mov_b32_e32 v148, v149
	v_pk_mul_f32 v[108:109], v[120:121], v[148:149] op_sel_hi:[1,0]
	v_pk_mul_f32 v[112:113], v[118:119], v[148:149] op_sel_hi:[1,0]
	v_pk_mul_f32 v[106:107], v[116:117], v[148:149] op_sel_hi:[1,0]
	v_pk_mul_f32 v[110:111], v[114:115], v[148:149] op_sel_hi:[1,0]
	v_pk_mul_f32 v[104:105], v[104:105], v[148:149] op_sel_hi:[1,0]
	v_pk_mul_f32 v[102:103], v[102:103], v[148:149] op_sel_hi:[1,0]
	v_pk_mul_f32 v[100:101], v[100:101], v[148:149] op_sel_hi:[1,0]
	v_pk_mul_f32 v[98:99], v[98:99], v[148:149] op_sel_hi:[1,0]
	ds_read2_b32 v[148:149], v156 offset0:32 offset1:48
	s_waitcnt lgkmcnt(0)
	v_pk_mul_f32 v[116:117], v[96:97], v[148:149] op_sel_hi:[1,0]
	v_pk_mul_f32 v[120:121], v[94:95], v[148:149] op_sel_hi:[1,0]
	v_pk_mul_f32 v[114:115], v[92:93], v[148:149] op_sel_hi:[1,0]
	v_pk_mul_f32 v[118:119], v[90:91], v[148:149] op_sel_hi:[1,0]
	v_pk_mul_f32 v[92:93], v[80:81], v[148:149] op_sel_hi:[1,0]
	v_pk_mul_f32 v[96:97], v[78:79], v[148:149] op_sel_hi:[1,0]
	v_pk_mul_f32 v[90:91], v[76:77], v[148:149] op_sel_hi:[1,0]
	v_pk_mul_f32 v[94:95], v[74:75], v[148:149] op_sel_hi:[1,0]
	v_mov_b32_e32 v148, v149
	v_pk_mul_f32 v[76:77], v[88:89], v[148:149] op_sel_hi:[1,0]
	v_pk_mul_f32 v[80:81], v[86:87], v[148:149] op_sel_hi:[1,0]
	v_pk_mul_f32 v[74:75], v[84:85], v[148:149] op_sel_hi:[1,0]
	v_pk_mul_f32 v[78:79], v[82:83], v[148:149] op_sel_hi:[1,0]
	v_pk_mul_f32 v[72:73], v[72:73], v[148:149] op_sel_hi:[1,0]
	v_pk_mul_f32 v[70:71], v[70:71], v[148:149] op_sel_hi:[1,0]
	v_pk_mul_f32 v[68:69], v[68:69], v[148:149] op_sel_hi:[1,0]
	v_pk_mul_f32 v[66:67], v[66:67], v[148:149] op_sel_hi:[1,0]
	ds_read2_b32 v[148:149], v156 offset0:128 offset1:144
	s_waitcnt lgkmcnt(0)
	v_pk_mul_f32 v[84:85], v[64:65], v[148:149] op_sel_hi:[1,0]
	v_pk_mul_f32 v[88:89], v[62:63], v[148:149] op_sel_hi:[1,0]
	v_pk_mul_f32 v[82:83], v[60:61], v[148:149] op_sel_hi:[1,0]
	v_pk_mul_f32 v[86:87], v[58:59], v[148:149] op_sel_hi:[1,0]
	v_pk_mul_f32 v[60:61], v[48:49], v[148:149] op_sel_hi:[1,0]
	v_pk_mul_f32 v[64:65], v[46:47], v[148:149] op_sel_hi:[1,0]
	v_pk_mul_f32 v[58:59], v[44:45], v[148:149] op_sel_hi:[1,0]
	v_pk_mul_f32 v[62:63], v[42:43], v[148:149] op_sel_hi:[1,0]
	v_mov_b32_e32 v148, v149
	v_pk_mul_f32 v[44:45], v[56:57], v[148:149] op_sel_hi:[1,0]
	v_pk_mul_f32 v[48:49], v[54:55], v[148:149] op_sel_hi:[1,0]
	v_pk_mul_f32 v[42:43], v[52:53], v[148:149] op_sel_hi:[1,0]
	v_pk_mul_f32 v[46:47], v[50:51], v[148:149] op_sel_hi:[1,0]
	v_pk_mul_f32 v[40:41], v[40:41], v[148:149] op_sel_hi:[1,0]
	v_pk_mul_f32 v[38:39], v[38:39], v[148:149] op_sel_hi:[1,0]
	v_pk_mul_f32 v[36:37], v[36:37], v[148:149] op_sel_hi:[1,0]
	v_pk_mul_f32 v[34:35], v[34:35], v[148:149] op_sel_hi:[1,0]
	ds_read2_b32 v[148:149], v156 offset0:160 offset1:176
	s_waitcnt lgkmcnt(0)
; __device__ __forceinline__ unsigned cvt_pk_bf16(float lo, float hi) { unsigned r; asm volatile("v_cvt_pk_bf16_f32 %0, %1, %2" : "=v"(r) : "v"(lo), "v"(hi)); return r; }
;     __device__ __forceinline__ void operator()(f32x4 (&acc)[2][2][4][2], const Unit& u, int ui, int wr, int wc, int fr_, int fq_) const {
;     ...
;             for (int m = 0; m < 4; ++m) { const float r = rtab[ui * 256 + ai * HALF + wr * 64 + m * 16 + fr];
; #pragma unroll
;                 for (int bj = 0; bj < 2; ++bj)
; #pragma unroll
;                     for (int n = 0; n < 2; ++n) acc[ai][bj][m][n] = acc[ai][bj][m][n] * r; }
;     ...
;         const int row0 = u.pm * BM + wr * 64 + fr, col0 = u.pn * BM + wc * 32 + 8 * fq;
; #pragma unroll
;         for (int ai = 0; ai < 2; ++ai)
; #pragma unroll
;             for (int m = 0; m < 4; ++m) {
; #pragma unroll
;                 for (int bj = 0; bj < 2; ++bj) { const f32x4 v0 = acc[ai][bj][m][0], v1 = acc[ai][bj][m][1]; u32x4 w;
;                     w.x = cvt_pk_bf16(v0[0], v0[1]); w.y = cvt_pk_bf16(v0[2], v0[3]); w.z = cvt_pk_bf16(v1[0], v1[1]); w.w = cvt_pk_bf16(v1[2], v1[3]);
;                     const int row = row0 + ai * HALF + m * 16;
;                     if (MODE == 0) {
;                         const int hd = (u.pn & 1) * 4 + bj * 2 + (wc >> 1), d = (wc & 1) * 32 + 8 * fq;
;                         *(u32x4*)(O + (size_t)(u.pn >> 1) * ((size_t)32768 * 512) + ((size_t)((row >> 13) * 8 + hd) * 8192 + (row & 8191)) * 64 + d) = w;
;                     } else *(u32x4*)(O + (size_t)row * ldc + col0 + bj * HALF) = w; } }
	v_pk_mul_f32 v[52:53], v[32:33], v[148:149] op_sel_hi:[1,0]
	v_pk_mul_f32 v[56:57], v[30:31], v[148:149] op_sel_hi:[1,0]
	v_pk_mul_f32 v[50:51], v[28:29], v[148:149] op_sel_hi:[1,0]
	v_pk_mul_f32 v[54:55], v[26:27], v[148:149] op_sel_hi:[1,0]
	v_pk_mul_f32 v[28:29], v[16:17], v[148:149] op_sel_hi:[1,0]
	v_pk_mul_f32 v[32:33], v[14:15], v[148:149] op_sel_hi:[1,0]
	v_pk_mul_f32 v[26:27], v[12:13], v[148:149] op_sel_hi:[1,0]
	v_pk_mul_f32 v[30:31], v[10:11], v[148:149] op_sel_hi:[1,0]
	v_mov_b32_e32 v148, v149
	v_pk_mul_f32 v[12:13], v[24:25], v[148:149] op_sel_hi:[1,0]
	v_add_u32_e32 v24, s17, v154
	v_ashrrev_i32_e32 v25, 31, v24
	v_pk_mul_f32 v[14:15], v[18:19], v[148:149] op_sel_hi:[1,0]
	v_lshl_add_u32 v18, v155, 3, s21
	v_lshlrev_b64 v[24:25], 13, v[24:25]
	v_ashrrev_i32_e32 v19, 31, v18
	v_lshl_add_u64 v[24:25], s[4:5], 0, v[24:25]
	v_pk_mul_f32 v[16:17], v[22:23], v[148:149] op_sel_hi:[1,0]
	v_pk_mul_f32 v[10:11], v[20:21], v[148:149] op_sel_hi:[1,0]
	v_cvt_pk_bf16_f32 v20, v150, v151
	v_cvt_pk_bf16_f32 v21, v142, v143
	v_cvt_pk_bf16_f32 v22, v152, v153
	v_cvt_pk_bf16_f32 v23, v140, v141
	v_lshl_add_u64 v[18:19], v[18:19], 1, v[24:25]
	global_store_dwordx4 v[18:19], v[20:23], off nt
	s_mov_b32 s17, 0x40000
	v_lshl_add_u64 v[24:25], v[18:19], 0, s[94:95]
	v_cvt_pk_bf16_f32 v20, v128, v129
	v_cvt_pk_bf16_f32 v21, v124, v125
	v_cvt_pk_bf16_f32 v22, v126, v127
	v_cvt_pk_bf16_f32 v23, v122, v123
	global_store_dwordx4 v[18:19], v[20:23], off offset:256 nt
	v_pk_mul_f32 v[8:9], v[8:9], v[148:149] op_sel_hi:[1,0]
	v_pk_mul_f32 v[6:7], v[6:7], v[148:149] op_sel_hi:[1,0]
	v_cvt_pk_bf16_f32 v20, v112, v113
	v_cvt_pk_bf16_f32 v21, v108, v109
	v_cvt_pk_bf16_f32 v22, v110, v111
	v_cvt_pk_bf16_f32 v23, v106, v107
	v_add_co_u32_e32 v106, vcc, s88, v18
	v_pk_mul_f32 v[4:5], v[4:5], v[148:149] op_sel_hi:[1,0]
	s_nop 0
	v_addc_co_u32_e32 v107, vcc, 0, v19, vcc
	global_store_dwordx4 v[106:107], v[20:23], off nt
	v_pk_mul_f32 v[2:3], v[2:3], v[148:149] op_sel_hi:[1,0]
	s_nop 0
	v_cvt_pk_bf16_f32 v20, v102, v103
	v_cvt_pk_bf16_f32 v21, v104, v105
	v_cvt_pk_bf16_f32 v22, v98, v99
	v_cvt_pk_bf16_f32 v23, v100, v101
	v_add_co_u32_e32 v98, vcc, s17, v18
	global_store_dwordx4 v[24:25], v[20:23], off offset:256 nt
	s_nop 0
	v_addc_co_u32_e32 v99, vcc, 0, v19, vcc
	v_cvt_pk_bf16_f32 v20, v120, v121
	v_cvt_pk_bf16_f32 v21, v116, v117
	v_cvt_pk_bf16_f32 v22, v118, v119
	v_cvt_pk_bf16_f32 v23, v114, v115
	v_lshl_add_u64 v[24:25], v[18:19], 0, s[26:27]
	global_store_dwordx4 v[98:99], v[20:23], off nt
	s_mov_b32 s17, 0x60000
	s_mov_b64 s[26:27], 0x60000
	v_cvt_pk_bf16_f32 v20, v96, v97
	v_cvt_pk_bf16_f32 v21, v92, v93
	v_cvt_pk_bf16_f32 v22, v94, v95
	v_cvt_pk_bf16_f32 v23, v90, v91
	global_store_dwordx4 v[24:25], v[20:23], off offset:256 nt
	v_lshl_add_u64 v[24:25], v[18:19], 0, s[26:27]
	s_mov_b64 s[26:27], 0x100000
	v_cvt_pk_bf16_f32 v20, v80, v81
	v_cvt_pk_bf16_f32 v21, v76, v77
	v_cvt_pk_bf16_f32 v22, v78, v79
	v_cvt_pk_bf16_f32 v23, v74, v75
	v_add_co_u32_e32 v74, vcc, s17, v18
	s_mov_b32 s17, 0x100000
	s_nop 0
	v_addc_co_u32_e32 v75, vcc, 0, v19, vcc
	global_store_dwordx4 v[74:75], v[20:23], off nt
	s_nop 1
	v_cvt_pk_bf16_f32 v20, v70, v71
	v_cvt_pk_bf16_f32 v21, v72, v73
	v_cvt_pk_bf16_f32 v22, v66, v67
	v_cvt_pk_bf16_f32 v23, v68, v69
	v_add_co_u32_e32 v66, vcc, s17, v18
	global_store_dwordx4 v[24:25], v[20:23], off offset:256 nt
	s_nop 0
	v_addc_co_u32_e32 v67, vcc, 0, v19, vcc
	v_cvt_pk_bf16_f32 v20, v88, v89
	v_cvt_pk_bf16_f32 v21, v84, v85
	v_cvt_pk_bf16_f32 v22, v86, v87
	v_cvt_pk_bf16_f32 v23, v82, v83
	v_lshl_add_u64 v[24:25], v[18:19], 0, s[26:27]
	global_store_dwordx4 v[66:67], v[20:23], off nt
	s_mov_b32 s17, 0x120000
	s_mov_b64 s[26:27], 0x120000
	v_cvt_pk_bf16_f32 v20, v64, v65
	v_cvt_pk_bf16_f32 v21, v60, v61
	v_cvt_pk_bf16_f32 v22, v62, v63
	v_cvt_pk_bf16_f32 v23, v58, v59
	global_store_dwordx4 v[24:25], v[20:23], off offset:256 nt
	v_lshl_add_u64 v[24:25], v[18:19], 0, s[26:27]
	s_mov_b64 s[26:27], 0x140000
	v_cvt_pk_bf16_f32 v20, v48, v49
	v_cvt_pk_bf16_f32 v21, v44, v45
	v_cvt_pk_bf16_f32 v22, v46, v47
	v_cvt_pk_bf16_f32 v23, v42, v43
	v_add_co_u32_e32 v42, vcc, s17, v18
	s_mov_b32 s17, 0x140000
	s_nop 0
	v_addc_co_u32_e32 v43, vcc, 0, v19, vcc
	global_store_dwordx4 v[42:43], v[20:23], off nt
	s_nop 1
	v_cvt_pk_bf16_f32 v20, v38, v39
	v_cvt_pk_bf16_f32 v21, v40, v41
	v_cvt_pk_bf16_f32 v22, v34, v35
	v_add_co_u32_e32 v34, vcc, s17, v18
	v_cvt_pk_bf16_f32 v23, v36, v37
	global_store_dwordx4 v[24:25], v[20:23], off offset:256 nt
	s_nop 0
	v_addc_co_u32_e32 v35, vcc, 0, v19, vcc
	v_cvt_pk_bf16_f32 v20, v56, v57
	v_cvt_pk_bf16_f32 v21, v52, v53
	v_cvt_pk_bf16_f32 v22, v54, v55
	v_cvt_pk_bf16_f32 v23, v50, v51
	v_lshl_add_u64 v[24:25], v[18:19], 0, s[26:27]
	global_store_dwordx4 v[34:35], v[20:23], off nt
	s_mov_b32 s17, 0x160000
	s_mov_b64 s[26:27], 0x160000
	v_cvt_pk_bf16_f32 v20, v32, v33
	v_cvt_pk_bf16_f32 v21, v28, v29
	v_cvt_pk_bf16_f32 v22, v30, v31
	v_cvt_pk_bf16_f32 v23, v26, v27
	global_store_dwordx4 v[24:25], v[20:23], off offset:256 nt
	s_nop 1
	v_cvt_pk_bf16_f32 v20, v16, v17
	v_cvt_pk_bf16_f32 v21, v12, v13
	v_add_co_u32_e32 v12, vcc, s17, v18
	v_cvt_pk_bf16_f32 v22, v14, v15
	v_cvt_pk_bf16_f32 v23, v10, v11
	v_lshl_add_u64 v[10:11], v[18:19], 0, s[26:27]
	s_nop 0
	v_addc_co_u32_e32 v13, vcc, 0, v19, vcc
	s_mov_b64 s[26:27], -1
	s_andn2_b64 vcc, exec, s[12:13]
	global_store_dwordx4 v[12:13], v[20:23], off nt
	v_cvt_pk_bf16_f32 v6, v6, v7
	v_cvt_pk_bf16_f32 v7, v8, v9
	v_cvt_pk_bf16_f32 v8, v2, v3
	v_cvt_pk_bf16_f32 v9, v4, v5
	global_store_dwordx4 v[10:11], v[6:9], off offset:256 nt
	s_cbranch_vccnz .LBB0_278
	s_andn2_b64 vcc, exec, s[0:1]
	s_cbranch_vccnz .LBB0_277
	s_barrier
	s_branch .LBB0_277

; __device__ __forceinline__ unsigned cvt_pk_bf16(float lo, float hi) { unsigned r; asm volatile("v_cvt_pk_bf16_f32 %0, %1, %2" : "=v"(r) : "v"(lo), "v"(hi)); return r; }
;     __device__ __forceinline__ void operator()(f32x4 (&acc)[2][2][4][2], const Unit& u, int ui, int wr, int wc, int fr_, int fq_) const {
;     ...
;         const int row0 = u.pm * BM + wr * 64 + fr, col0 = u.pn * BM + wc * 32 + 8 * fq;
; #pragma unroll
;         for (int ai = 0; ai < 2; ++ai)
; #pragma unroll
;             for (int m = 0; m < 4; ++m) {
; #pragma unroll
;                 for (int bj = 0; bj < 2; ++bj) { const f32x4 v0 = acc[ai][bj][m][0], v1 = acc[ai][bj][m][1]; u32x4 w;
;                     w.x = cvt_pk_bf16(v0[0], v0[1]); w.y = cvt_pk_bf16(v0[2], v0[3]); w.z = cvt_pk_bf16(v1[0], v1[1]); w.w = cvt_pk_bf16(v1[2], v1[3]);
;                     const int row = row0 + ai * HALF + m * 16;
;                     if (MODE == 0) {
;                         const int hd = (u.pn & 1) * 4 + bj * 2 + (wc >> 1), d = (wc & 1) * 32 + 8 * fq;
;                         *(u32x4*)(O + (size_t)(u.pn >> 1) * ((size_t)32768 * 512) + ((size_t)((row >> 13) * 8 + hd) * 8192 + (row & 8191)) * 64 + d) = w;
;                     } else *(u32x4*)(O + (size_t)row * ldc + col0 + bj * HALF) = w; } }
.LBB0_369:
	s_lshl_b32 s17, s68, 8
	s_add_i32 s17, s17, s51
	v_add_u32_e32 v150, s17, v182
	s_lshl_b32 s17, s57, 8
	s_or_b32 s17, s17, s52
	v_add_u32_e32 v4, s17, v183
	v_ashrrev_i32_e32 v5, 31, v4
	v_mov_b64_e32 v[2:3], s[6:7]
	v_cvt_pk_bf16_f32 v6, v146, v147
	v_cvt_pk_bf16_f32 v7, v128, v129
	v_mad_i64_i32 v[128:129], s[20:21], v150, s72, v[2:3]
	v_lshlrev_b64 v[4:5], 1, v[4:5]
	v_cvt_pk_bf16_f32 v8, v148, v149
	v_cvt_pk_bf16_f32 v9, v142, v143
	v_lshl_add_u64 v[128:129], v[128:129], 0, v[4:5]
	global_store_dwordx4 v[128:129], v[6:9], off nt
	s_andn2_b64 vcc, exec, s[4:5]
	s_mov_b64 s[4:5], -1
	v_cvt_pk_bf16_f32 v6, v124, v125
	v_cvt_pk_bf16_f32 v7, v116, v117
	v_cvt_pk_bf16_f32 v8, v144, v145
	v_cvt_pk_bf16_f32 v9, v114, v115
	v_add_u32_e32 v114, 16, v150
	global_store_dwordx4 v[128:129], v[6:9], off offset:256 nt
	s_nop 1
	v_cvt_pk_bf16_f32 v6, v122, v123
	v_cvt_pk_bf16_f32 v7, v106, v107
	v_mad_i64_i32 v[106:107], s[20:21], v114, s72, v[2:3]
	v_cvt_pk_bf16_f32 v8, v126, v127
	v_cvt_pk_bf16_f32 v9, v112, v113
	v_lshl_add_u64 v[106:107], v[106:107], 0, v[4:5]
	global_store_dwordx4 v[106:107], v[6:9], off nt
	s_nop 1
	v_cvt_pk_bf16_f32 v6, v110, v111
	v_cvt_pk_bf16_f32 v7, v100, v101
	v_cvt_pk_bf16_f32 v8, v120, v121
	v_cvt_pk_bf16_f32 v9, v98, v99
	v_add_u32_e32 v98, 32, v150
	global_store_dwordx4 v[106:107], v[6:9], off offset:256 nt
	s_nop 1
	v_cvt_pk_bf16_f32 v6, v108, v109
	v_cvt_pk_bf16_f32 v7, v90, v91
	v_mad_i64_i32 v[90:91], s[20:21], v98, s72, v[2:3]
	v_cvt_pk_bf16_f32 v8, v118, v119
	v_cvt_pk_bf16_f32 v9, v96, v97
	v_lshl_add_u64 v[90:91], v[90:91], 0, v[4:5]
	global_store_dwordx4 v[90:91], v[6:9], off nt
	s_nop 1
	v_cvt_pk_bf16_f32 v6, v94, v95
	v_cvt_pk_bf16_f32 v7, v84, v85
	v_cvt_pk_bf16_f32 v8, v104, v105
	v_cvt_pk_bf16_f32 v9, v82, v83
	v_add_u32_e32 v82, 48, v150
	global_store_dwordx4 v[90:91], v[6:9], off offset:256 nt
	s_nop 1
	v_cvt_pk_bf16_f32 v6, v92, v93
	v_cvt_pk_bf16_f32 v7, v74, v75
	v_mad_i64_i32 v[74:75], s[20:21], v82, s72, v[2:3]
	v_cvt_pk_bf16_f32 v8, v102, v103
	v_cvt_pk_bf16_f32 v9, v80, v81
	v_lshl_add_u64 v[74:75], v[74:75], 0, v[4:5]
	global_store_dwordx4 v[74:75], v[6:9], off nt
	s_nop 1
	v_cvt_pk_bf16_f32 v6, v78, v79
	v_cvt_pk_bf16_f32 v7, v72, v73
	v_cvt_pk_bf16_f32 v8, v88, v89
	v_cvt_pk_bf16_f32 v9, v68, v69
	v_add_u32_e32 v68, 0x80, v150
	global_store_dwordx4 v[74:75], v[6:9], off offset:256 nt
	s_nop 1
	v_cvt_pk_bf16_f32 v6, v76, v77
	v_cvt_pk_bf16_f32 v7, v64, v65
	v_cvt_pk_bf16_f32 v8, v86, v87
	v_cvt_pk_bf16_f32 v9, v60, v61
	v_mad_i64_i32 v[60:61], s[20:21], v68, s72, v[2:3]
	v_lshl_add_u64 v[60:61], v[60:61], 0, v[4:5]
	global_store_dwordx4 v[60:61], v[6:9], off nt
	s_nop 1
	v_cvt_pk_bf16_f32 v6, v58, v59
	v_cvt_pk_bf16_f32 v7, v52, v53
	v_cvt_pk_bf16_f32 v8, v70, v71
	v_cvt_pk_bf16_f32 v9, v50, v51
	v_add_u32_e32 v50, 0x90, v150
	global_store_dwordx4 v[60:61], v[6:9], off offset:256 nt
	s_nop 1
	v_cvt_pk_bf16_f32 v6, v56, v57
	v_cvt_pk_bf16_f32 v7, v42, v43
	v_mad_i64_i32 v[42:43], s[20:21], v50, s72, v[2:3]
	v_cvt_pk_bf16_f32 v8, v66, v67
	v_cvt_pk_bf16_f32 v9, v44, v45
	v_lshl_add_u64 v[42:43], v[42:43], 0, v[4:5]
	global_store_dwordx4 v[42:43], v[6:9], off nt
	s_nop 1
	v_cvt_pk_bf16_f32 v6, v46, v47
	v_cvt_pk_bf16_f32 v7, v36, v37
	v_cvt_pk_bf16_f32 v8, v54, v55
	v_cvt_pk_bf16_f32 v9, v34, v35
	v_add_u32_e32 v34, 0xa0, v150
	global_store_dwordx4 v[42:43], v[6:9], off offset:256 nt
	s_nop 1
	v_cvt_pk_bf16_f32 v6, v40, v41
	v_cvt_pk_bf16_f32 v7, v28, v29
	v_mad_i64_i32 v[28:29], s[20:21], v34, s72, v[2:3]
	v_lshl_add_u64 v[28:29], v[28:29], 0, v[4:5]
	v_cvt_pk_bf16_f32 v8, v48, v49
	v_cvt_pk_bf16_f32 v9, v32, v33
	global_store_dwordx4 v[28:29], v[6:9], off nt
	s_nop 1
	v_cvt_pk_bf16_f32 v6, v30, v31
	v_cvt_pk_bf16_f32 v7, v20, v21
	v_add_u32_e32 v20, 0xb0, v150
	v_cvt_pk_bf16_f32 v8, v38, v39
	v_cvt_pk_bf16_f32 v9, v26, v27
	v_mad_i64_i32 v[2:3], s[20:21], v20, s72, v[2:3]
	global_store_dwordx4 v[28:29], v[6:9], off offset:256 nt
	s_nop 1
	v_cvt_pk_bf16_f32 v6, v22, v23
	v_cvt_pk_bf16_f32 v7, v18, v19
	v_cvt_pk_bf16_f32 v8, v24, v25
	v_cvt_pk_bf16_f32 v9, v16, v17
	v_lshl_add_u64 v[16:17], v[2:3], 0, v[4:5]
	global_store_dwordx4 v[16:17], v[6:9], off nt
	v_cvt_pk_bf16_f32 v2, v14, v15
	v_cvt_pk_bf16_f32 v3, v10, v11
	v_cvt_pk_bf16_f32 v4, v62, v63
	v_cvt_pk_bf16_f32 v5, v12, v13
	global_store_dwordx4 v[16:17], v[2:5], off offset:256 nt
	s_cbranch_vccnz .LBB0_322
	s_andn2_b64 vcc, exec, s[0:1]
	s_cbranch_vccnz .LBB0_321
	s_barrier
	s_branch .LBB0_321

;     __device__ __forceinline__ void operator()(f32x4 (&acc)[2][2][4][2], const Unit& u, int ui, int wr, int wc, int fr_, int fq_) const {
;     ...
;         if (MODE == 0) { if ((u.pn >> 1) == 4) {
; #pragma unroll
;             for (int bj = 0; bj < 2; ++bj)
; #pragma unroll
;                 for (int n = 0; n < 2; ++n) { f32x4 cs = (f32x4){0.f, 0.f, 0.f, 0.f};
; #pragma unroll
;                     for (int ai = 0; ai < 2; ++ai)
; #pragma unroll
;                         for (int m = 0; m < 4; ++m) cs = cs + acc[ai][bj][m][n];
;                     cs[0] = row16_sum(cs[0]); cs[1] = row16_sum(cs[1]); cs[2] = row16_sum(cs[2]); cs[3] = row16_sum(cs[3]);
;                     if (fr == 0) *(f32x4*)(km2 + (size_t)(u.pm * 2 + wr) * 512 + (u.pn - 8) * 256 + bj * HALF + wc * 32 + 8 * fq + 4 * n) = cs; }
.LBB0_452:
	s_andn2_b64 vcc, exec, s[6:7]
	s_cbranch_vccnz .LBB0_462
	v_pk_add_f32 v[2:3], v[142:143], 0 op_sel_hi:[1,0]
	v_pk_add_f32 v[4:5], v[146:147], 0 op_sel_hi:[1,0]
	v_pk_add_f32 v[2:3], v[114:115], v[2:3]
	v_pk_add_f32 v[4:5], v[118:119], v[4:5]
	v_pk_add_f32 v[2:3], v[98:99], v[2:3]
	v_pk_add_f32 v[4:5], v[102:103], v[4:5]
	v_pk_add_f32 v[2:3], v[82:83], v[2:3]
	v_pk_add_f32 v[4:5], v[86:87], v[4:5]
	s_lshl_b32 s21, s57, 1
	v_pk_add_f32 v[2:3], v[66:67], v[2:3]
	v_pk_add_f32 v[4:5], v[70:71], v[4:5]
	s_add_i32 s22, s21, s40
	v_pk_add_f32 v[2:3], v[50:51], v[2:3]
	v_pk_add_f32 v[4:5], v[54:55], v[4:5]
	s_ashr_i32 s23, s22, 31
	v_pk_add_f32 v[2:3], v[34:35], v[2:3]
	v_pk_add_f32 v[8:9], v[38:39], v[4:5]
	v_cmp_eq_u32_e64 s[6:7], 0, v185
	s_lshl_b64 s[22:23], s[22:23], 11
	s_lshl_b32 s86, s71, 8
	v_ashrrev_i32_e32 v7, 31, v6
	v_pk_add_f32 v[4:5], v[18:19], v[2:3]
	v_pk_add_f32 v[2:3], v[22:23], v[8:9]
	s_nop 0
	s_nop 1
	v_add_f32_dpp v2, v2, v2 row_ror:8 row_mask:0xf bank_mask:0xf
	s_nop 1
	v_add_f32_dpp v2, v2, v2 row_ror:4 row_mask:0xf bank_mask:0xf
	s_nop 1
	v_add_f32_dpp v2, v2, v2 row_ror:2 row_mask:0xf bank_mask:0xf
	s_nop 1
	v_add_f32_dpp v2, v2, v2 row_ror:1 row_mask:0xf bank_mask:0xf
	s_nop 1
	v_add_f32_dpp v3, v3, v3 row_ror:8 row_mask:0xf bank_mask:0xf
	s_nop 1
	v_add_f32_dpp v3, v3, v3 row_ror:4 row_mask:0xf bank_mask:0xf
	s_nop 1
	v_add_f32_dpp v3, v3, v3 row_ror:2 row_mask:0xf bank_mask:0xf
	s_nop 1
	v_add_f32_dpp v3, v3, v3 row_ror:1 row_mask:0xf bank_mask:0xf
	s_nop 1
	v_add_f32_dpp v4, v4, v4 row_ror:8 row_mask:0xf bank_mask:0xf
	s_nop 1
	v_add_f32_dpp v4, v4, v4 row_ror:4 row_mask:0xf bank_mask:0xf
	s_nop 1
	v_add_f32_dpp v4, v4, v4 row_ror:2 row_mask:0xf bank_mask:0xf
	s_nop 1
	v_add_f32_dpp v4, v4, v4 row_ror:1 row_mask:0xf bank_mask:0xf
	s_nop 1
	v_add_f32_dpp v5, v5, v5 row_ror:8 row_mask:0xf bank_mask:0xf
	s_nop 1
	v_add_f32_dpp v5, v5, v5 row_ror:4 row_mask:0xf bank_mask:0xf
	s_nop 1
	v_add_f32_dpp v5, v5, v5 row_ror:2 row_mask:0xf bank_mask:0xf
	s_nop 1
	v_add_f32_dpp v5, v5, v5 row_ror:1 row_mask:0xf bank_mask:0xf
	s_and_saveexec_b64 s[24:25], s[6:7]
	s_cbranch_execz .LBB0_455
	s_add_u32 s21, s14, s22
	s_addc_u32 s37, s15, s23
	s_lshl_b64 s[30:31], s[86:87], 2
	s_add_u32 s21, s21, s30
	s_addc_u32 s31, s37, s31
	s_lshl_b32 s30, s59, 2
	s_add_u32 s30, s21, s30
	s_addc_u32 s31, s31, 0
	v_lshl_add_u64 v[8:9], v[6:7], 2, s[30:31]
	v_add_co_u32_e32 v8, vcc, 0xffffe000, v8
	s_nop 1
	v_addc_co_u32_e32 v9, vcc, -1, v9, vcc
	global_store_dwordx4 v[8:9], v[2:5], off nt
.LBB0_455:
	s_or_b64 exec, exec, s[24:25]
	s_nop 0
	v_pk_add_f32 v[2:3], v[144:145], 0 op_sel_hi:[1,0]
	v_pk_add_f32 v[4:5], v[148:149], 0 op_sel_hi:[1,0]
	v_pk_add_f32 v[2:3], v[116:117], v[2:3]
	v_pk_add_f32 v[4:5], v[120:121], v[4:5]
	v_pk_add_f32 v[2:3], v[100:101], v[2:3]
	v_pk_add_f32 v[4:5], v[104:105], v[4:5]
	v_pk_add_f32 v[2:3], v[84:85], v[2:3]
	v_pk_add_f32 v[4:5], v[88:89], v[4:5]
	v_pk_add_f32 v[2:3], v[68:69], v[2:3]
	v_pk_add_f32 v[4:5], v[72:73], v[4:5]
	v_pk_add_f32 v[2:3], v[52:53], v[2:3]
	v_pk_add_f32 v[4:5], v[56:57], v[4:5]
	v_pk_add_f32 v[2:3], v[36:37], v[2:3]
	v_pk_add_f32 v[8:9], v[40:41], v[4:5]
	v_pk_add_f32 v[4:5], v[16:17], v[2:3]
	v_pk_add_f32 v[2:3], v[24:25], v[8:9]
	s_nop 0
	s_nop 1
	v_add_f32_dpp v2, v2, v2 row_ror:8 row_mask:0xf bank_mask:0xf
	s_nop 1
	v_add_f32_dpp v2, v2, v2 row_ror:4 row_mask:0xf bank_mask:0xf
	s_nop 1
	v_add_f32_dpp v2, v2, v2 row_ror:2 row_mask:0xf bank_mask:0xf
	s_nop 1
	v_add_f32_dpp v2, v2, v2 row_ror:1 row_mask:0xf bank_mask:0xf
	s_nop 1
	v_add_f32_dpp v3, v3, v3 row_ror:8 row_mask:0xf bank_mask:0xf
	s_nop 1
	v_add_f32_dpp v3, v3, v3 row_ror:4 row_mask:0xf bank_mask:0xf
	s_nop 1
	v_add_f32_dpp v3, v3, v3 row_ror:2 row_mask:0xf bank_mask:0xf
	s_nop 1
	v_add_f32_dpp v3, v3, v3 row_ror:1 row_mask:0xf bank_mask:0xf
	s_nop 1
	v_add_f32_dpp v4, v4, v4 row_ror:8 row_mask:0xf bank_mask:0xf
	s_nop 1
	v_add_f32_dpp v4, v4, v4 row_ror:4 row_mask:0xf bank_mask:0xf
	s_nop 1
	v_add_f32_dpp v4, v4, v4 row_ror:2 row_mask:0xf bank_mask:0xf
	s_nop 1
	v_add_f32_dpp v4, v4, v4 row_ror:1 row_mask:0xf bank_mask:0xf
	s_nop 1
	v_add_f32_dpp v5, v5, v5 row_ror:8 row_mask:0xf bank_mask:0xf
	s_nop 1
	v_add_f32_dpp v5, v5, v5 row_ror:4 row_mask:0xf bank_mask:0xf
	s_nop 1
	v_add_f32_dpp v5, v5, v5 row_ror:2 row_mask:0xf bank_mask:0xf
	s_nop 1
	v_add_f32_dpp v5, v5, v5 row_ror:1 row_mask:0xf bank_mask:0xf
	s_and_saveexec_b64 s[24:25], s[6:7]
	s_cbranch_execz .LBB0_457
	s_add_u32 s21, s14, s22
	s_addc_u32 s37, s15, s23
	s_lshl_b64 s[30:31], s[86:87], 2
	s_add_u32 s21, s21, s30
	s_addc_u32 s31, s37, s31
	s_lshl_b32 s30, s59, 2
	s_add_u32 s30, s21, s30
	s_addc_u32 s31, s31, 0
	v_lshl_add_u64 v[8:9], v[6:7], 2, s[30:31]
	v_add_co_u32_e32 v8, vcc, 0xfffff000, v8
	s_nop 1
	v_addc_co_u32_e32 v9, vcc, -1, v9, vcc
	global_store_dwordx4 v[8:9], v[2:5], off offset:-4080 nt
;     __device__ __forceinline__ void operator()(f32x4 (&acc)[2][2][4][2], const Unit& u, int ui, int wr, int wc, int fr_, int fq_) const {
;     ...
;                 for (int n = 0; n < 2; ++n) { f32x4 cs = (f32x4){0.f, 0.f, 0.f, 0.f};
; #pragma unroll
;                     for (int ai = 0; ai < 2; ++ai)
; #pragma unroll
;                         for (int m = 0; m < 4; ++m) cs = cs + acc[ai][bj][m][n];
;                     cs[0] = row16_sum(cs[0]); cs[1] = row16_sum(cs[1]); cs[2] = row16_sum(cs[2]); cs[3] = row16_sum(cs[3]);
;                     if (fr == 0) *(f32x4*)(km2 + (size_t)(u.pm * 2 + wr) * 512 + (u.pn - 8) * 256 + bj * HALF + wc * 32 + 8 * fq + 4 * n) = cs; }
.LBB0_457:
	s_or_b64 exec, exec, s[24:25]
	s_nop 0
	v_pk_add_f32 v[2:3], v[122:123], 0 op_sel_hi:[1,0]
	v_pk_add_f32 v[4:5], v[126:127], 0 op_sel_hi:[1,0]
	v_pk_add_f32 v[2:3], v[106:107], v[2:3]
	v_pk_add_f32 v[4:5], v[110:111], v[4:5]
	v_pk_add_f32 v[2:3], v[90:91], v[2:3]
	v_pk_add_f32 v[4:5], v[94:95], v[4:5]
	v_pk_add_f32 v[2:3], v[74:75], v[2:3]
	v_pk_add_f32 v[4:5], v[78:79], v[4:5]
	v_pk_add_f32 v[2:3], v[58:59], v[2:3]
	v_pk_add_f32 v[4:5], v[62:63], v[4:5]
	v_pk_add_f32 v[2:3], v[42:43], v[2:3]
	v_pk_add_f32 v[4:5], v[46:47], v[4:5]
	v_pk_add_f32 v[2:3], v[26:27], v[2:3]
	v_pk_add_f32 v[8:9], v[30:31], v[4:5]
	v_pk_add_f32 v[4:5], v[10:11], v[2:3]
	v_pk_add_f32 v[2:3], v[14:15], v[8:9]
	s_nop 0
	s_nop 1
	v_add_f32_dpp v2, v2, v2 row_ror:8 row_mask:0xf bank_mask:0xf
	s_nop 1
	v_add_f32_dpp v2, v2, v2 row_ror:4 row_mask:0xf bank_mask:0xf
	s_nop 1
	v_add_f32_dpp v2, v2, v2 row_ror:2 row_mask:0xf bank_mask:0xf
	s_nop 1
	v_add_f32_dpp v2, v2, v2 row_ror:1 row_mask:0xf bank_mask:0xf
	s_nop 1
	v_add_f32_dpp v3, v3, v3 row_ror:8 row_mask:0xf bank_mask:0xf
	s_nop 1
	v_add_f32_dpp v3, v3, v3 row_ror:4 row_mask:0xf bank_mask:0xf
	s_nop 1
	v_add_f32_dpp v3, v3, v3 row_ror:2 row_mask:0xf bank_mask:0xf
	s_nop 1
	v_add_f32_dpp v3, v3, v3 row_ror:1 row_mask:0xf bank_mask:0xf
	s_nop 1
	v_add_f32_dpp v4, v4, v4 row_ror:8 row_mask:0xf bank_mask:0xf
	s_nop 1
	v_add_f32_dpp v4, v4, v4 row_ror:4 row_mask:0xf bank_mask:0xf
	s_nop 1
	v_add_f32_dpp v4, v4, v4 row_ror:2 row_mask:0xf bank_mask:0xf
	s_nop 1
	v_add_f32_dpp v4, v4, v4 row_ror:1 row_mask:0xf bank_mask:0xf
	s_nop 1
	v_add_f32_dpp v5, v5, v5 row_ror:8 row_mask:0xf bank_mask:0xf
	s_nop 1
	v_add_f32_dpp v5, v5, v5 row_ror:4 row_mask:0xf bank_mask:0xf
	s_nop 1
	v_add_f32_dpp v5, v5, v5 row_ror:2 row_mask:0xf bank_mask:0xf
	s_nop 1
	v_add_f32_dpp v5, v5, v5 row_ror:1 row_mask:0xf bank_mask:0xf
	s_and_saveexec_b64 s[24:25], s[6:7]
	s_cbranch_execz .LBB0_459
	s_add_u32 s21, s14, s22
	s_addc_u32 s37, s15, s23
	s_lshl_b64 s[30:31], s[86:87], 2
	s_add_u32 s21, s21, s30
	s_addc_u32 s31, s37, s31
	s_lshl_b32 s30, s59, 2
	s_add_u32 s30, s21, s30
	s_addc_u32 s31, s31, 0
	v_lshl_add_u64 v[8:9], v[6:7], 2, s[30:31]
	v_add_co_u32_e32 v8, vcc, 0xfffff000, v8
	s_nop 1
	v_addc_co_u32_e32 v9, vcc, -1, v9, vcc
	global_store_dwordx4 v[8:9], v[2:5], off offset:-3584 nt
.LBB0_459:
	s_or_b64 exec, exec, s[24:25]
	s_nop 0
	v_pk_add_f32 v[2:3], v[124:125], 0 op_sel_hi:[1,0]
	v_pk_add_f32 v[4:5], v[128:129], 0 op_sel_hi:[1,0]
	v_pk_add_f32 v[2:3], v[108:109], v[2:3]
	v_pk_add_f32 v[4:5], v[112:113], v[4:5]
	v_pk_add_f32 v[2:3], v[92:93], v[2:3]
	v_pk_add_f32 v[4:5], v[96:97], v[4:5]
	v_pk_add_f32 v[2:3], v[76:77], v[2:3]
	v_pk_add_f32 v[4:5], v[80:81], v[4:5]
	v_pk_add_f32 v[2:3], v[60:61], v[2:3]
	v_pk_add_f32 v[4:5], v[64:65], v[4:5]
	v_pk_add_f32 v[2:3], v[44:45], v[2:3]
	v_pk_add_f32 v[4:5], v[48:49], v[4:5]
	v_pk_add_f32 v[2:3], v[28:29], v[2:3]
	v_pk_add_f32 v[8:9], v[32:33], v[4:5]
	v_pk_add_f32 v[4:5], v[12:13], v[2:3]
	v_pk_add_f32 v[2:3], v[20:21], v[8:9]
	s_nop 0
	s_nop 1
	v_add_f32_dpp v2, v2, v2 row_ror:8 row_mask:0xf bank_mask:0xf
	s_nop 1
	v_add_f32_dpp v2, v2, v2 row_ror:4 row_mask:0xf bank_mask:0xf
	s_nop 1
	v_add_f32_dpp v2, v2, v2 row_ror:2 row_mask:0xf bank_mask:0xf
	s_nop 1
	v_add_f32_dpp v2, v2, v2 row_ror:1 row_mask:0xf bank_mask:0xf
	s_nop 1
	v_add_f32_dpp v3, v3, v3 row_ror:8 row_mask:0xf bank_mask:0xf
	s_nop 1
	v_add_f32_dpp v3, v3, v3 row_ror:4 row_mask:0xf bank_mask:0xf
	s_nop 1
	v_add_f32_dpp v3, v3, v3 row_ror:2 row_mask:0xf bank_mask:0xf
	s_nop 1
	v_add_f32_dpp v3, v3, v3 row_ror:1 row_mask:0xf bank_mask:0xf
	s_nop 1
	v_add_f32_dpp v4, v4, v4 row_ror:8 row_mask:0xf bank_mask:0xf
	s_nop 1
	v_add_f32_dpp v4, v4, v4 row_ror:4 row_mask:0xf bank_mask:0xf
	s_nop 1
	v_add_f32_dpp v4, v4, v4 row_ror:2 row_mask:0xf bank_mask:0xf
	s_nop 1
	v_add_f32_dpp v4, v4, v4 row_ror:1 row_mask:0xf bank_mask:0xf
	s_nop 1
	v_add_f32_dpp v5, v5, v5 row_ror:8 row_mask:0xf bank_mask:0xf
	s_nop 1
	v_add_f32_dpp v5, v5, v5 row_ror:4 row_mask:0xf bank_mask:0xf
	s_nop 1
	v_add_f32_dpp v5, v5, v5 row_ror:2 row_mask:0xf bank_mask:0xf
	s_nop 1
	v_add_f32_dpp v5, v5, v5 row_ror:1 row_mask:0xf bank_mask:0xf
	s_and_saveexec_b64 s[24:25], s[6:7]
	s_cbranch_execz .LBB0_461
	s_add_u32 s21, s14, s22
	s_addc_u32 s22, s15, s23
	s_lshl_b64 s[6:7], s[86:87], 2
	s_add_u32 s6, s21, s6
	s_addc_u32 s7, s22, s7
	s_lshl_b32 s21, s59, 2
	s_add_u32 s6, s6, s21
	s_addc_u32 s7, s7, 0
	v_lshl_add_u64 v[8:9], v[6:7], 2, s[6:7]
	v_add_co_u32_e32 v8, vcc, 0xfffff000, v8
	s_nop 1
	v_addc_co_u32_e32 v9, vcc, -1, v9, vcc
	global_store_dwordx4 v[8:9], v[2:5], off offset:-3568 nt

; __device__ __forceinline__ unsigned cvt_pk_bf16(float lo, float hi) { unsigned r; asm volatile("v_cvt_pk_bf16_f32 %0, %1, %2" : "=v"(r) : "v"(lo), "v"(hi)); return r; }
;     __device__ __forceinline__ void operator()(f32x4 (&acc)[2][2][4][2], const Unit& u, int ui, int wr, int wc, int fr_, int fq_) const {
;     ...
;         const int row0 = u.pm * BM + wr * 64 + fr, col0 = u.pn * BM + wc * 32 + 8 * fq;
; #pragma unroll
;         for (int ai = 0; ai < 2; ++ai)
; #pragma unroll
;             for (int m = 0; m < 4; ++m) {
; #pragma unroll
;                 for (int bj = 0; bj < 2; ++bj) { const f32x4 v0 = acc[ai][bj][m][0], v1 = acc[ai][bj][m][1]; u32x4 w;
;                     w.x = cvt_pk_bf16(v0[0], v0[1]); w.y = cvt_pk_bf16(v0[2], v0[3]); w.z = cvt_pk_bf16(v1[0], v1[1]); w.w = cvt_pk_bf16(v1[2], v1[3]);
;                     const int row = row0 + ai * HALF + m * 16;
;                     if (MODE == 0) {
;                         const int hd = (u.pn & 1) * 4 + bj * 2 + (wc >> 1), d = (wc & 1) * 32 + 8 * fq;
;                         *(u32x4*)(O + (size_t)(u.pn >> 1) * ((size_t)32768 * 512) + ((size_t)((row >> 13) * 8 + hd) * 8192 + (row & 8191)) * 64 + d) = w;
.LBB0_462:
	s_lshl_b32 s6, s57, 8
	s_add_i32 s6, s6, s55
	v_add_u32_e32 v150, s6, v185
	s_lshl_b32 s6, s71, 2
	s_and_b32 s6, s6, 4
	s_or_b32 s22, s6, s36
	v_add_u32_e32 v2, s11, v0
	v_ashrrev_i32_e32 v0, 10, v150
	s_ashr_i32 s21, s20, 31
	v_and_or_b32 v8, v0, -8, s22
	s_lshl_b64 s[6:7], s[20:21], 25
	v_ashrrev_i32_e32 v9, 31, v8
	v_cvt_pk_bf16_f32 v4, v146, v147
	v_cvt_pk_bf16_f32 v5, v142, v143
	s_add_u32 s6, s70, s6
	v_lshlrev_b64 v[142:143], 20, v[8:9]
	v_or_b32_e32 v8, 2, v8
	s_addc_u32 s7, s78, s7
	v_lshlrev_b32_e32 v0, 7, v150
	v_ashrrev_i32_e32 v9, 31, v8
	v_ashrrev_i32_e32 v3, 31, v2
	v_lshl_add_u64 v[142:143], s[6:7], 0, v[142:143]
	v_and_b32_e32 v0, 0xfff80, v0
	v_lshlrev_b64 v[8:9], 20, v[8:9]
	v_lshl_add_u64 v[142:143], v[142:143], 0, v[0:1]
	v_lshlrev_b64 v[2:3], 1, v[2:3]
	v_lshl_add_u64 v[8:9], s[6:7], 0, v[8:9]
	v_lshl_add_u64 v[142:143], v[142:143], 0, v[2:3]
	v_lshl_add_u64 v[8:9], v[8:9], 0, v[0:1]
	v_cvt_pk_bf16_f32 v6, v148, v149
	v_cvt_pk_bf16_f32 v7, v144, v145
	global_store_dwordx4 v[142:143], v[4:7], off nt
	v_lshl_add_u64 v[8:9], v[8:9], 0, v[2:3]
	v_add_u32_e32 v0, 16, v150
	v_cvt_pk_bf16_f32 v4, v126, v127
	v_cvt_pk_bf16_f32 v5, v122, v123
	v_cvt_pk_bf16_f32 v6, v128, v129
	v_cvt_pk_bf16_f32 v7, v124, v125
	global_store_dwordx4 v[8:9], v[4:7], off nt
	s_andn2_b64 vcc, exec, s[4:5]
	s_mov_b64 s[4:5], -1
	v_ashrrev_i32_e32 v4, 10, v0
	v_and_or_b32 v8, v4, -8, s22
	v_ashrrev_i32_e32 v9, 31, v8
	v_cvt_pk_bf16_f32 v4, v118, v119
	v_cvt_pk_bf16_f32 v5, v114, v115
	v_lshlrev_b64 v[114:115], 20, v[8:9]
	v_or_b32_e32 v8, 2, v8
	v_lshlrev_b32_e32 v0, 7, v0
	v_ashrrev_i32_e32 v9, 31, v8
	v_lshl_add_u64 v[114:115], s[6:7], 0, v[114:115]
	v_and_b32_e32 v0, 0xfff80, v0
	v_lshlrev_b64 v[8:9], 20, v[8:9]
	v_lshl_add_u64 v[114:115], v[114:115], 0, v[0:1]
	v_lshl_add_u64 v[8:9], s[6:7], 0, v[8:9]
	v_lshl_add_u64 v[114:115], v[114:115], 0, v[2:3]
	v_lshl_add_u64 v[8:9], v[8:9], 0, v[0:1]
	v_cvt_pk_bf16_f32 v6, v120, v121
	v_cvt_pk_bf16_f32 v7, v116, v117
	global_store_dwordx4 v[114:115], v[4:7], off nt
	v_lshl_add_u64 v[8:9], v[8:9], 0, v[2:3]
	v_add_u32_e32 v0, 32, v150
	v_cvt_pk_bf16_f32 v4, v110, v111
	v_cvt_pk_bf16_f32 v5, v106, v107
	v_cvt_pk_bf16_f32 v6, v112, v113
	v_cvt_pk_bf16_f32 v7, v108, v109
	global_store_dwordx4 v[8:9], v[4:7], off nt
	s_nop 1
	v_ashrrev_i32_e32 v4, 10, v0
	v_and_or_b32 v8, v4, -8, s22
	v_ashrrev_i32_e32 v9, 31, v8
	v_cvt_pk_bf16_f32 v4, v102, v103
	v_cvt_pk_bf16_f32 v5, v98, v99
	v_lshlrev_b64 v[98:99], 20, v[8:9]
	v_or_b32_e32 v8, 2, v8
	v_lshlrev_b32_e32 v0, 7, v0
	v_ashrrev_i32_e32 v9, 31, v8
	v_lshl_add_u64 v[98:99], s[6:7], 0, v[98:99]
	v_and_b32_e32 v0, 0xfff80, v0
	v_lshlrev_b64 v[8:9], 20, v[8:9]
	v_lshl_add_u64 v[98:99], v[98:99], 0, v[0:1]
	v_lshl_add_u64 v[8:9], s[6:7], 0, v[8:9]
	v_lshl_add_u64 v[98:99], v[98:99], 0, v[2:3]
	v_lshl_add_u64 v[8:9], v[8:9], 0, v[0:1]
	v_cvt_pk_bf16_f32 v6, v104, v105
	v_cvt_pk_bf16_f32 v7, v100, v101
	global_store_dwordx4 v[98:99], v[4:7], off nt
	v_lshl_add_u64 v[8:9], v[8:9], 0, v[2:3]
	v_add_u32_e32 v0, 48, v150
	v_cvt_pk_bf16_f32 v4, v94, v95
	v_cvt_pk_bf16_f32 v5, v90, v91
	v_cvt_pk_bf16_f32 v6, v96, v97
	v_cvt_pk_bf16_f32 v7, v92, v93
	global_store_dwordx4 v[8:9], v[4:7], off nt
	s_nop 1
	v_ashrrev_i32_e32 v4, 10, v0
	v_and_or_b32 v8, v4, -8, s22
	v_ashrrev_i32_e32 v9, 31, v8
	v_cvt_pk_bf16_f32 v4, v86, v87
	v_cvt_pk_bf16_f32 v5, v82, v83
	v_lshlrev_b64 v[82:83], 20, v[8:9]
	v_or_b32_e32 v8, 2, v8
	v_lshlrev_b32_e32 v0, 7, v0
	v_ashrrev_i32_e32 v9, 31, v8
	v_lshl_add_u64 v[82:83], s[6:7], 0, v[82:83]
	v_and_b32_e32 v0, 0xfff80, v0
	v_lshlrev_b64 v[8:9], 20, v[8:9]
	v_lshl_add_u64 v[82:83], v[82:83], 0, v[0:1]
	v_lshl_add_u64 v[8:9], s[6:7], 0, v[8:9]
	v_lshl_add_u64 v[82:83], v[82:83], 0, v[2:3]
	v_lshl_add_u64 v[8:9], v[8:9], 0, v[0:1]
	v_cvt_pk_bf16_f32 v6, v88, v89
	v_cvt_pk_bf16_f32 v7, v84, v85
	global_store_dwordx4 v[82:83], v[4:7], off nt
	v_lshl_add_u64 v[8:9], v[8:9], 0, v[2:3]
	v_add_u32_e32 v0, 0x80, v150
; __device__ __forceinline__ unsigned cvt_pk_bf16(float lo, float hi) { unsigned r; asm volatile("v_cvt_pk_bf16_f32 %0, %1, %2" : "=v"(r) : "v"(lo), "v"(hi)); return r; }
;     __device__ __forceinline__ void operator()(f32x4 (&acc)[2][2][4][2], const Unit& u, int ui, int wr, int wc, int fr_, int fq_) const {
;     ...
;         const int row0 = u.pm * BM + wr * 64 + fr, col0 = u.pn * BM + wc * 32 + 8 * fq;
; #pragma unroll
;         for (int ai = 0; ai < 2; ++ai)
; #pragma unroll
;             for (int m = 0; m < 4; ++m) {
; #pragma unroll
;                 for (int bj = 0; bj < 2; ++bj) { const f32x4 v0 = acc[ai][bj][m][0], v1 = acc[ai][bj][m][1]; u32x4 w;
;                     w.x = cvt_pk_bf16(v0[0], v0[1]); w.y = cvt_pk_bf16(v0[2], v0[3]); w.z = cvt_pk_bf16(v1[0], v1[1]); w.w = cvt_pk_bf16(v1[2], v1[3]);
;                     const int row = row0 + ai * HALF + m * 16;
;                     if (MODE == 0) {
;                         const int hd = (u.pn & 1) * 4 + bj * 2 + (wc >> 1), d = (wc & 1) * 32 + 8 * fq;
;                         *(u32x4*)(O + (size_t)(u.pn >> 1) * ((size_t)32768 * 512) + ((size_t)((row >> 13) * 8 + hd) * 8192 + (row & 8191)) * 64 + d) = w;
	v_cvt_pk_bf16_f32 v4, v78, v79
	v_cvt_pk_bf16_f32 v5, v74, v75
	v_cvt_pk_bf16_f32 v6, v80, v81
	v_cvt_pk_bf16_f32 v7, v76, v77
	global_store_dwordx4 v[8:9], v[4:7], off nt
	s_nop 1
	v_ashrrev_i32_e32 v4, 10, v0
	v_and_or_b32 v8, v4, -8, s22
	v_ashrrev_i32_e32 v9, 31, v8
	v_cvt_pk_bf16_f32 v4, v70, v71
	v_cvt_pk_bf16_f32 v5, v66, v67
	v_lshlrev_b64 v[66:67], 20, v[8:9]
	v_or_b32_e32 v8, 2, v8
	v_lshlrev_b32_e32 v0, 7, v0
	v_ashrrev_i32_e32 v9, 31, v8
	v_lshl_add_u64 v[66:67], s[6:7], 0, v[66:67]
	v_and_b32_e32 v0, 0xfff80, v0
	v_lshlrev_b64 v[8:9], 20, v[8:9]
	v_lshl_add_u64 v[66:67], v[66:67], 0, v[0:1]
	v_lshl_add_u64 v[8:9], s[6:7], 0, v[8:9]
	v_lshl_add_u64 v[66:67], v[66:67], 0, v[2:3]
	v_lshl_add_u64 v[8:9], v[8:9], 0, v[0:1]
	v_cvt_pk_bf16_f32 v6, v72, v73
	v_cvt_pk_bf16_f32 v7, v68, v69
	global_store_dwordx4 v[66:67], v[4:7], off nt
	v_lshl_add_u64 v[8:9], v[8:9], 0, v[2:3]
	v_add_u32_e32 v0, 0x90, v150
	v_cvt_pk_bf16_f32 v4, v62, v63
	v_cvt_pk_bf16_f32 v5, v58, v59
	v_cvt_pk_bf16_f32 v6, v64, v65
	v_cvt_pk_bf16_f32 v7, v60, v61
	global_store_dwordx4 v[8:9], v[4:7], off nt
	s_nop 1
	v_ashrrev_i32_e32 v4, 10, v0
	v_and_or_b32 v8, v4, -8, s22
	v_ashrrev_i32_e32 v9, 31, v8
	v_cvt_pk_bf16_f32 v4, v54, v55
	v_cvt_pk_bf16_f32 v5, v50, v51
	v_lshlrev_b64 v[50:51], 20, v[8:9]
	v_or_b32_e32 v8, 2, v8
	v_lshlrev_b32_e32 v0, 7, v0
	v_ashrrev_i32_e32 v9, 31, v8
	v_lshl_add_u64 v[50:51], s[6:7], 0, v[50:51]
	v_and_b32_e32 v0, 0xfff80, v0
	v_lshlrev_b64 v[8:9], 20, v[8:9]
	v_lshl_add_u64 v[50:51], v[50:51], 0, v[0:1]
	v_lshl_add_u64 v[8:9], s[6:7], 0, v[8:9]
	v_lshl_add_u64 v[50:51], v[50:51], 0, v[2:3]
	v_lshl_add_u64 v[8:9], v[8:9], 0, v[0:1]
	v_cvt_pk_bf16_f32 v6, v56, v57
	v_cvt_pk_bf16_f32 v7, v52, v53
	global_store_dwordx4 v[50:51], v[4:7], off nt
	v_lshl_add_u64 v[8:9], v[8:9], 0, v[2:3]
	v_add_u32_e32 v0, 0xa0, v150
	v_cvt_pk_bf16_f32 v4, v46, v47
	v_cvt_pk_bf16_f32 v5, v42, v43
	v_cvt_pk_bf16_f32 v6, v48, v49
	v_cvt_pk_bf16_f32 v7, v44, v45
	global_store_dwordx4 v[8:9], v[4:7], off nt
	s_nop 1
	v_ashrrev_i32_e32 v4, 10, v0
	v_and_or_b32 v8, v4, -8, s22
	v_ashrrev_i32_e32 v9, 31, v8
	v_cvt_pk_bf16_f32 v4, v38, v39
	v_cvt_pk_bf16_f32 v5, v34, v35
	v_lshlrev_b64 v[34:35], 20, v[8:9]
	v_or_b32_e32 v8, 2, v8
	v_lshlrev_b32_e32 v0, 7, v0
	v_ashrrev_i32_e32 v9, 31, v8
	v_lshl_add_u64 v[34:35], s[6:7], 0, v[34:35]
	v_and_b32_e32 v0, 0xfff80, v0
	v_lshlrev_b64 v[8:9], 20, v[8:9]
	v_lshl_add_u64 v[34:35], v[34:35], 0, v[0:1]
	v_lshl_add_u64 v[8:9], s[6:7], 0, v[8:9]
	v_lshl_add_u64 v[34:35], v[34:35], 0, v[2:3]
	v_lshl_add_u64 v[8:9], v[8:9], 0, v[0:1]
	v_cvt_pk_bf16_f32 v6, v40, v41
	v_cvt_pk_bf16_f32 v7, v36, v37
	global_store_dwordx4 v[34:35], v[4:7], off nt
	v_lshl_add_u64 v[8:9], v[8:9], 0, v[2:3]
	v_add_u32_e32 v0, 0xb0, v150
	v_cvt_pk_bf16_f32 v4, v30, v31
	v_cvt_pk_bf16_f32 v5, v26, v27
	v_cvt_pk_bf16_f32 v6, v32, v33
	v_cvt_pk_bf16_f32 v7, v28, v29
	global_store_dwordx4 v[8:9], v[4:7], off nt
	s_nop 1
	v_ashrrev_i32_e32 v4, 10, v0
	v_and_or_b32 v8, v4, -8, s22
	v_ashrrev_i32_e32 v9, 31, v8
	v_cvt_pk_bf16_f32 v4, v22, v23
	v_cvt_pk_bf16_f32 v5, v18, v19
	v_cvt_pk_bf16_f32 v6, v24, v25
	v_cvt_pk_bf16_f32 v7, v16, v17
	v_lshlrev_b64 v[16:17], 20, v[8:9]
	v_or_b32_e32 v8, 2, v8
	v_ashrrev_i32_e32 v9, 31, v8
	v_lshlrev_b32_e32 v0, 7, v0
	v_lshlrev_b64 v[8:9], 20, v[8:9]
	v_lshl_add_u64 v[16:17], s[6:7], 0, v[16:17]
	v_and_b32_e32 v0, 0xfff80, v0
	v_lshl_add_u64 v[8:9], s[6:7], 0, v[8:9]
	v_lshl_add_u64 v[16:17], v[16:17], 0, v[0:1]
	v_lshl_add_u64 v[8:9], v[8:9], 0, v[0:1]
	v_lshl_add_u64 v[16:17], v[16:17], 0, v[2:3]
	v_lshl_add_u64 v[2:3], v[8:9], 0, v[2:3]
	global_store_dwordx4 v[16:17], v[4:7], off nt
	s_nop 1
	v_cvt_pk_bf16_f32 v4, v14, v15
	v_cvt_pk_bf16_f32 v5, v10, v11
	v_cvt_pk_bf16_f32 v6, v20, v21
	v_cvt_pk_bf16_f32 v7, v12, v13
	global_store_dwordx4 v[2:3], v[4:7], off nt
	s_cbranch_vccnz .LBB0_403
	s_andn2_b64 vcc, exec, s[0:1]
	s_cbranch_vccnz .LBB0_402
	s_barrier
	s_branch .LBB0_402

;     __device__ __forceinline__ void operator()(f32x4 (&acc)[2][2][4][2], const Unit& u, int ui, int wr, int wc, int fr_, int fq_) const {
;     ...
;         const int row0 = u.pm * BM + wr * 64 + fr, col0 = u.pn * BM + wc * 32 + 8 * fq;
; #pragma unroll
;         for (int ai = 0; ai < 2; ++ai)
; #pragma unroll
;             for (int m = 0; m < 4; ++m) { const size_t off = (size_t)(row0 + ai * HALF + m * 16) * 1024 + col0; float s = 0.f;
; #pragma unroll
;                 for (int bj = 0; bj < 2; ++bj) { f32x4 v0, v1;
;                     if (IN32) { const float* xi = Xin32 + off + bj * HALF; v0 = *(const f32x4*)xi; v1 = *(const f32x4*)(xi + 4); }
;                     else { const u32x4 w = *(const u32x4*)(XB + off + bj * HALF);
;                         if (RESID_F16) { const f32x2p_t a = unpk2h(w.x), b = unpk2h(w.y), c2 = unpk2h(w.z), d = unpk2h(w.w); v0 = (f32x4){a.x, a.y, b.x, b.y}; v1 = (f32x4){c2.x, c2.y, d.x, d.y}; }
;                         else { v0 = (f32x4){__builtin_bit_cast(float, w.x << 16), __builtin_bit_cast(float, w.x & 0xffff0000u), __builtin_bit_cast(float, w.y << 16), __builtin_bit_cast(float, w.y & 0xffff0000u)};
;                                v1 = (f32x4){__builtin_bit_cast(float, w.z << 16), __builtin_bit_cast(float, w.z & 0xffff0000u), __builtin_bit_cast(float, w.w << 16), __builtin_bit_cast(float, w.w & 0xffff0000u)}; } }
;                     v0 = v0 + acc[ai][bj][m][0]; v1 = v1 + acc[ai][bj][m][1];
;                     if (OUT32) { float* xp = Xout32 + off + bj * HALF; __builtin_nontemporal_store(v0, (f32x4*)xp); __builtin_nontemporal_store(v1, (f32x4*)(xp + 4)); }
;                     s += (v0[0] * v0[0] + v0[1] * v0[1]) + (v0[2] * v0[2] + v0[3] * v0[3]) + (v1[0] * v1[0] + v1[1] * v1[1]) + (v1[2] * v1[2] + v1[3] * v1[3]);
;                     u32x4 w; if (RESID_F16) { w.x = pk2h(v0[0], v0[1]); w.y = pk2h(v0[2], v0[3]); w.z = pk2h(v1[0], v1[1]); w.w = pk2h(v1[2], v1[3]); } else { w.x = cvt_pk_bf16(v0[0], v0[1]); w.y = cvt_pk_bf16(v0[2], v0[3]); w.z = cvt_pk_bf16(v1[0], v1[1]); w.w = cvt_pk_bf16(v1[2], v1[3]); }
;                     *(u32x4*)(XB + off + bj * HALF) = w; }
;                 s = fq_sum(s);
;                 if (fq == 0) SS[(size_t)(row0 + ai * HALF + m * 16) * 16 + u.pn * 4 + wc] = s;
;                 asm volatile("" ::: "memory"); }
.LBB0_773:
	s_lshl_b32 s4, s52, 8
	v_mov_b32_e32 v140, v147
	v_mov_b32_e32 v143, v146
	s_add_i32 s4, s4, s46
	s_lshl_b32 s26, s51, 2
	v_add_u32_e32 v142, s4, v140
	s_lshl_b32 s4, s51, 8
	s_or_b32 s4, s4, s47
	v_lshl_add_u32 v140, v143, 3, s4
	v_cmp_eq_u32_e32 vcc, 0, v143
	v_ashrrev_i32_e32 v143, 31, v142
	v_lshlrev_b64 v[144:145], 11, v[142:143]
	v_ashrrev_i32_e32 v141, 31, v140
	v_lshl_add_u64 v[144:145], s[8:9], 0, v[144:145]
	v_lshl_add_u64 v[144:145], v[140:141], 1, v[144:145]
	v_mov_b32_e32 v182, 0x8000
	v_mov_b32_e32 v183, 0
	v_mov_b32_e32 v184, 0x40000
	v_mov_b32_e32 v185, 0
	global_load_dwordx4 v[196:199], v[144:145], off
	global_load_dwordx4 v[200:203], v[144:145], off offset:256
	v_lshl_add_u64 v[186:187], v[144:145], 0, v[182:183]
	global_load_dwordx4 v[204:207], v[186:187], off
	global_load_dwordx4 v[208:211], v[186:187], off offset:256
	v_lshl_add_u64 v[188:189], v[186:187], 0, v[182:183]
	global_load_dwordx4 v[212:215], v[188:189], off
	global_load_dwordx4 v[216:219], v[188:189], off offset:256
	v_lshl_add_u64 v[186:187], v[188:189], 0, v[182:183]
	global_load_dwordx4 v[220:223], v[186:187], off
	global_load_dwordx4 v[224:227], v[186:187], off offset:256
	s_ashr_i32 s27, s26, 31
	s_waitcnt vmcnt(7)
	v_lshlrev_b32_e32 v154, 16, v196
	v_and_b32_e32 v155, 0xffff0000, v196
	v_lshlrev_b32_e32 v150, 16, v197
	v_and_b32_e32 v151, 0xffff0000, v197
	v_lshlrev_b32_e32 v156, 16, v198
	v_and_b32_e32 v157, 0xffff0000, v198
	v_lshlrev_b32_e32 v152, 16, v199
	v_and_b32_e32 v153, 0xffff0000, v199
	v_pk_add_f32 v[128:129], v[128:129], v[150:151]
	v_pk_add_f32 v[126:127], v[126:127], v[154:155]
	v_pk_add_f32 v[150:151], v[124:125], v[152:153]
	v_pk_add_f32 v[124:125], v[122:123], v[156:157]
	v_mul_f32_e32 v122, v127, v127
	v_mul_f32_e32 v123, v129, v129
	v_fmac_f32_e32 v122, v126, v126
	v_fmac_f32_e32 v123, v128, v128
	v_add_f32_e32 v122, v122, v123
	v_mul_f32_e32 v123, v125, v125
	v_fmac_f32_e32 v123, v124, v124
	v_add_f32_e32 v122, v123, v122
	v_mul_f32_e32 v123, v151, v151
	v_fmac_f32_e32 v123, v150, v150
	v_add_f32_e32 v152, v123, v122
	v_cvt_pk_bf16_f32 v122, v126, v127
	v_cvt_pk_bf16_f32 v123, v128, v129
	v_cvt_pk_bf16_f32 v124, v124, v125
	v_cvt_pk_bf16_f32 v125, v150, v151
	global_store_dwordx4 v[144:145], v[122:125], off nt
	s_waitcnt vmcnt(7)
	v_lshlrev_b32_e32 v126, 16, v200
	v_and_b32_e32 v127, 0xffff0000, v200
	v_lshlrev_b32_e32 v122, 16, v201
	v_and_b32_e32 v123, 0xffff0000, v201
	v_lshlrev_b32_e32 v128, 16, v202
	v_and_b32_e32 v129, 0xffff0000, v202
	v_lshlrev_b32_e32 v124, 16, v203
	v_and_b32_e32 v125, 0xffff0000, v203
	v_lshl_add_u64 v[186:187], v[144:145], 0, v[184:185]
	global_load_dwordx4 v[196:199], v[186:187], off
	global_load_dwordx4 v[200:203], v[186:187], off offset:256
	v_pk_add_f32 v[120:121], v[120:121], v[122:123]
	v_pk_add_f32 v[118:119], v[118:119], v[126:127]
	v_pk_add_f32 v[122:123], v[116:117], v[124:125]
	v_pk_add_f32 v[116:117], v[114:115], v[128:129]
	v_mul_f32_e32 v114, v119, v119
	v_mul_f32_e32 v115, v121, v121
	v_fmac_f32_e32 v114, v118, v118
	v_fmac_f32_e32 v115, v120, v120
	v_add_f32_e32 v114, v114, v115
	v_mul_f32_e32 v115, v117, v117
	v_fmac_f32_e32 v115, v116, v116
	v_add_f32_e32 v114, v115, v114
	v_mul_f32_e32 v115, v123, v123
	v_fmac_f32_e32 v115, v122, v122
	v_add_f32_e32 v114, v115, v114
	v_add_f32_e32 v124, v152, v114
	v_cvt_pk_bf16_f32 v114, v118, v119
	v_cvt_pk_bf16_f32 v115, v120, v121
	v_cvt_pk_bf16_f32 v116, v116, v117
	v_cvt_pk_bf16_f32 v117, v122, v123
	global_store_dwordx4 v[144:145], v[114:117], off offset:256 nt
	s_nop 1
	v_mov_b32_e32 v114, v124
	s_nop 1
	v_permlane32_swap_b32_e32 v124, v114
	v_add_f32_e32 v114, v124, v114
	v_mov_b32_e32 v115, v114
	s_nop 1
	v_permlane16_swap_b32_e32 v114, v115
	s_and_saveexec_b64 s[38:39], vcc
	s_cbranch_execz .LBB0_775
	v_add_f32_e32 v116, v114, v115
	v_lshlrev_b64 v[114:115], 6, v[142:143]
	v_lshl_add_u64 v[114:115], s[10:11], 0, v[114:115]
	v_lshl_add_u64 v[114:115], s[26:27], 2, v[114:115]
	s_lshl_b32 s86, s45, 2
	v_lshl_add_u64 v[114:115], v[114:115], 0, s[86:87]
	global_store_dword v[114:115], v116, off
.LBB0_775:
	s_or_b64 exec, exec, s[38:39]
	v_add_u32_e32 v114, 16, v142
	v_ashrrev_i32_e32 v115, 31, v114
	v_lshlrev_b64 v[116:117], 11, v[114:115]
	v_lshl_add_u64 v[116:117], s[8:9], 0, v[116:117]
	v_lshl_add_u64 v[120:121], v[140:141], 1, v[116:117]
	s_waitcnt vmcnt(10)
	v_lshlrev_b32_e32 v122, 16, v204
	v_and_b32_e32 v123, 0xffff0000, v204
	v_lshlrev_b32_e32 v116, 16, v205
	v_and_b32_e32 v117, 0xffff0000, v205
	v_lshlrev_b32_e32 v124, 16, v206
	v_and_b32_e32 v125, 0xffff0000, v206
	v_lshlrev_b32_e32 v118, 16, v207
	v_and_b32_e32 v119, 0xffff0000, v207
	v_pk_add_f32 v[116:117], v[112:113], v[116:117]
	v_pk_add_f32 v[122:123], v[110:111], v[122:123]
	v_pk_add_f32 v[118:119], v[108:109], v[118:119]
	v_pk_add_f32 v[124:125], v[106:107], v[124:125]
	v_cvt_pk_bf16_f32 v106, v122, v123
	v_cvt_pk_bf16_f32 v107, v116, v117
	v_mul_f32_e32 v123, v123, v123
	v_cvt_pk_bf16_f32 v108, v124, v125
	v_cvt_pk_bf16_f32 v109, v118, v119
	v_mul_f32_e32 v117, v117, v117
	v_mul_f32_e32 v125, v125, v125
	v_fmac_f32_e32 v123, v122, v122
	v_fmac_f32_e32 v117, v116, v116
	v_mul_f32_e32 v119, v119, v119
	v_fmac_f32_e32 v125, v124, v124
	global_store_dwordx4 v[120:121], v[106:109], off nt
	v_fmac_f32_e32 v119, v118, v118
	s_nop 0
	v_add_f32_e32 v106, v123, v117
	v_add_f32_e32 v106, v125, v106
	v_add_f32_e32 v116, v119, v106
	s_waitcnt vmcnt(10)
	v_lshlrev_b32_e32 v106, 16, v208
	v_and_b32_e32 v107, 0xffff0000, v208
	v_lshlrev_b32_e32 v108, 16, v209
	v_and_b32_e32 v109, 0xffff0000, v209
	v_lshlrev_b32_e32 v110, 16, v210
	v_and_b32_e32 v111, 0xffff0000, v210
	v_pk_add_f32 v[104:105], v[104:105], v[108:109]
	v_pk_add_f32 v[102:103], v[102:103], v[106:107]
	v_lshlrev_b32_e32 v112, 16, v211
	v_and_b32_e32 v113, 0xffff0000, v211
	v_lshl_add_u64 v[188:189], v[120:121], 0, v[184:185]
	global_load_dwordx4 v[204:207], v[188:189], off
	global_load_dwordx4 v[208:211], v[188:189], off offset:256
	v_pk_add_f32 v[108:109], v[98:99], v[110:111]
	v_mul_f32_e32 v110, v103, v103
	v_mul_f32_e32 v111, v105, v105
	v_pk_add_f32 v[106:107], v[100:101], v[112:113]
	v_mul_f32_e32 v112, v109, v109
	v_cvt_pk_bf16_f32 v98, v102, v103
	v_fmac_f32_e32 v110, v102, v102
	v_fmac_f32_e32 v111, v104, v104
	v_mul_f32_e32 v113, v107, v107
	v_cvt_pk_bf16_f32 v99, v104, v105
	v_cvt_pk_bf16_f32 v100, v108, v109
	v_cvt_pk_bf16_f32 v101, v106, v107
	v_fmac_f32_e32 v112, v108, v108
	global_store_dwordx4 v[120:121], v[98:101], off offset:256 nt
	v_fmac_f32_e32 v113, v106, v106
	s_nop 0
	v_add_f32_e32 v98, v110, v111
	v_add_f32_e32 v98, v112, v98
	v_add_f32_e32 v98, v113, v98
	v_add_f32_e32 v98, v116, v98
	v_mov_b32_e32 v99, v98
	s_nop 1
	v_permlane32_swap_b32_e32 v98, v99
	v_add_f32_e32 v98, v98, v99
	v_mov_b32_e32 v99, v98
	s_nop 1
	v_permlane16_swap_b32_e32 v98, v99
	s_and_saveexec_b64 s[38:39], vcc
	s_cbranch_execz .LBB0_777
;     __device__ __forceinline__ void operator()(f32x4 (&acc)[2][2][4][2], const Unit& u, int ui, int wr, int wc, int fr_, int fq_) const {
;     ...
;         const int row0 = u.pm * BM + wr * 64 + fr, col0 = u.pn * BM + wc * 32 + 8 * fq;
; #pragma unroll
;         for (int ai = 0; ai < 2; ++ai)
; #pragma unroll
;             for (int m = 0; m < 4; ++m) { const size_t off = (size_t)(row0 + ai * HALF + m * 16) * 1024 + col0; float s = 0.f;
; #pragma unroll
;                 for (int bj = 0; bj < 2; ++bj) { f32x4 v0, v1;
;                     if (IN32) { const float* xi = Xin32 + off + bj * HALF; v0 = *(const f32x4*)xi; v1 = *(const f32x4*)(xi + 4); }
;                     else { const u32x4 w = *(const u32x4*)(XB + off + bj * HALF);
;                         if (RESID_F16) { const f32x2p_t a = unpk2h(w.x), b = unpk2h(w.y), c2 = unpk2h(w.z), d = unpk2h(w.w); v0 = (f32x4){a.x, a.y, b.x, b.y}; v1 = (f32x4){c2.x, c2.y, d.x, d.y}; }
;                         else { v0 = (f32x4){__builtin_bit_cast(float, w.x << 16), __builtin_bit_cast(float, w.x & 0xffff0000u), __builtin_bit_cast(float, w.y << 16), __builtin_bit_cast(float, w.y & 0xffff0000u)};
;                                v1 = (f32x4){__builtin_bit_cast(float, w.z << 16), __builtin_bit_cast(float, w.z & 0xffff0000u), __builtin_bit_cast(float, w.w << 16), __builtin_bit_cast(float, w.w & 0xffff0000u)}; } }
;                     v0 = v0 + acc[ai][bj][m][0]; v1 = v1 + acc[ai][bj][m][1];
;                     if (OUT32) { float* xp = Xout32 + off + bj * HALF; __builtin_nontemporal_store(v0, (f32x4*)xp); __builtin_nontemporal_store(v1, (f32x4*)(xp + 4)); }
;                     s += (v0[0] * v0[0] + v0[1] * v0[1]) + (v0[2] * v0[2] + v0[3] * v0[3]) + (v1[0] * v1[0] + v1[1] * v1[1]) + (v1[2] * v1[2] + v1[3] * v1[3]);
;                     u32x4 w; if (RESID_F16) { w.x = pk2h(v0[0], v0[1]); w.y = pk2h(v0[2], v0[3]); w.z = pk2h(v1[0], v1[1]); w.w = pk2h(v1[2], v1[3]); } else { w.x = cvt_pk_bf16(v0[0], v0[1]); w.y = cvt_pk_bf16(v0[2], v0[3]); w.z = cvt_pk_bf16(v1[0], v1[1]); w.w = cvt_pk_bf16(v1[2], v1[3]); }
;                     *(u32x4*)(XB + off + bj * HALF) = w; }
;                 s = fq_sum(s);
;                 if (fq == 0) SS[(size_t)(row0 + ai * HALF + m * 16) * 16 + u.pn * 4 + wc] = s;
;                 asm volatile("" ::: "memory"); }
	v_add_f32_e32 v100, v98, v99
	v_lshlrev_b64 v[98:99], 6, v[114:115]
	v_lshl_add_u64 v[98:99], s[10:11], 0, v[98:99]
	v_lshl_add_u64 v[98:99], s[26:27], 2, v[98:99]
	s_lshl_b32 s86, s45, 2
	v_lshl_add_u64 v[98:99], v[98:99], 0, s[86:87]
	global_store_dword v[98:99], v100, off
.LBB0_777:
	s_or_b64 exec, exec, s[38:39]
	v_add_u32_e32 v98, 32, v142
	v_ashrrev_i32_e32 v99, 31, v98
	v_lshlrev_b64 v[100:101], 11, v[98:99]
	v_lshl_add_u64 v[100:101], s[8:9], 0, v[100:101]
	v_lshl_add_u64 v[104:105], v[140:141], 1, v[100:101]
	s_waitcnt vmcnt(13)
	v_lshlrev_b32_e32 v106, 16, v212
	v_and_b32_e32 v107, 0xffff0000, v212
	v_lshlrev_b32_e32 v100, 16, v213
	v_and_b32_e32 v101, 0xffff0000, v213
	v_lshlrev_b32_e32 v108, 16, v214
	v_and_b32_e32 v109, 0xffff0000, v214
	v_lshlrev_b32_e32 v102, 16, v215
	v_and_b32_e32 v103, 0xffff0000, v215
	v_pk_add_f32 v[100:101], v[96:97], v[100:101]
	v_pk_add_f32 v[106:107], v[94:95], v[106:107]
	v_pk_add_f32 v[102:103], v[92:93], v[102:103]
	v_pk_add_f32 v[108:109], v[90:91], v[108:109]
	v_cvt_pk_bf16_f32 v90, v106, v107
	v_cvt_pk_bf16_f32 v91, v100, v101
	v_mul_f32_e32 v107, v107, v107
	v_cvt_pk_bf16_f32 v92, v108, v109
	v_cvt_pk_bf16_f32 v93, v102, v103
	v_mul_f32_e32 v101, v101, v101
	v_mul_f32_e32 v109, v109, v109
	v_fmac_f32_e32 v107, v106, v106
	v_fmac_f32_e32 v101, v100, v100
	v_mul_f32_e32 v103, v103, v103
	v_fmac_f32_e32 v109, v108, v108
	global_store_dwordx4 v[104:105], v[90:93], off nt
	v_fmac_f32_e32 v103, v102, v102
	s_nop 0
	v_add_f32_e32 v90, v107, v101
	v_add_f32_e32 v90, v109, v90
	v_add_f32_e32 v100, v103, v90
	s_waitcnt vmcnt(13)
	v_lshlrev_b32_e32 v90, 16, v216
	v_and_b32_e32 v91, 0xffff0000, v216
	v_lshlrev_b32_e32 v92, 16, v217
	v_and_b32_e32 v93, 0xffff0000, v217
	v_lshlrev_b32_e32 v94, 16, v218
	v_and_b32_e32 v95, 0xffff0000, v218
	v_pk_add_f32 v[88:89], v[88:89], v[92:93]
	v_pk_add_f32 v[86:87], v[86:87], v[90:91]
	v_lshlrev_b32_e32 v96, 16, v219
	v_and_b32_e32 v97, 0xffff0000, v219
	v_lshl_add_u64 v[186:187], v[104:105], 0, v[184:185]
	global_load_dwordx4 v[212:215], v[186:187], off
	global_load_dwordx4 v[216:219], v[186:187], off offset:256
	v_pk_add_f32 v[92:93], v[82:83], v[94:95]
	v_mul_f32_e32 v94, v87, v87
	v_mul_f32_e32 v95, v89, v89
	v_pk_add_f32 v[90:91], v[84:85], v[96:97]
	v_mul_f32_e32 v96, v93, v93
	v_cvt_pk_bf16_f32 v82, v86, v87
	v_fmac_f32_e32 v94, v86, v86
	v_fmac_f32_e32 v95, v88, v88
	v_mul_f32_e32 v97, v91, v91
	v_cvt_pk_bf16_f32 v83, v88, v89
	v_cvt_pk_bf16_f32 v84, v92, v93
	v_cvt_pk_bf16_f32 v85, v90, v91
	v_fmac_f32_e32 v96, v92, v92
	global_store_dwordx4 v[104:105], v[82:85], off offset:256 nt
	v_fmac_f32_e32 v97, v90, v90
	s_nop 0
	v_add_f32_e32 v82, v94, v95
	v_add_f32_e32 v82, v96, v82
	v_add_f32_e32 v82, v97, v82
	v_add_f32_e32 v82, v100, v82
	v_mov_b32_e32 v83, v82
	s_nop 1
	v_permlane32_swap_b32_e32 v82, v83
	v_add_f32_e32 v82, v82, v83
	v_mov_b32_e32 v83, v82
	s_nop 1
	v_permlane16_swap_b32_e32 v82, v83
	s_and_saveexec_b64 s[38:39], vcc
	s_cbranch_execz .LBB0_779
	v_add_f32_e32 v84, v82, v83
	v_lshlrev_b64 v[82:83], 6, v[98:99]
	v_lshl_add_u64 v[82:83], s[10:11], 0, v[82:83]
	v_lshl_add_u64 v[82:83], s[26:27], 2, v[82:83]
	s_lshl_b32 s86, s45, 2
	v_lshl_add_u64 v[82:83], v[82:83], 0, s[86:87]
	global_store_dword v[82:83], v84, off
.LBB0_779:
	s_or_b64 exec, exec, s[38:39]
	v_add_u32_e32 v82, 48, v142
	v_ashrrev_i32_e32 v83, 31, v82
	v_lshlrev_b64 v[84:85], 11, v[82:83]
	v_lshl_add_u64 v[84:85], s[8:9], 0, v[84:85]
	v_lshl_add_u64 v[88:89], v[140:141], 1, v[84:85]
	s_waitcnt vmcnt(16)
	v_lshlrev_b32_e32 v90, 16, v220
	v_and_b32_e32 v91, 0xffff0000, v220
	v_lshlrev_b32_e32 v84, 16, v221
	v_and_b32_e32 v85, 0xffff0000, v221
	v_lshlrev_b32_e32 v92, 16, v222
	v_and_b32_e32 v93, 0xffff0000, v222
	v_lshlrev_b32_e32 v86, 16, v223
	v_and_b32_e32 v87, 0xffff0000, v223
	v_pk_add_f32 v[84:85], v[80:81], v[84:85]
	v_pk_add_f32 v[90:91], v[78:79], v[90:91]
	v_pk_add_f32 v[86:87], v[76:77], v[86:87]
	v_pk_add_f32 v[92:93], v[74:75], v[92:93]
	v_cvt_pk_bf16_f32 v74, v90, v91
	v_cvt_pk_bf16_f32 v75, v84, v85
	v_mul_f32_e32 v91, v91, v91
	v_cvt_pk_bf16_f32 v76, v92, v93
	v_cvt_pk_bf16_f32 v77, v86, v87
	v_mul_f32_e32 v85, v85, v85
	v_mul_f32_e32 v93, v93, v93
	v_fmac_f32_e32 v91, v90, v90
	v_fmac_f32_e32 v85, v84, v84
	v_mul_f32_e32 v87, v87, v87
	v_fmac_f32_e32 v93, v92, v92
	global_store_dwordx4 v[88:89], v[74:77], off nt
	v_fmac_f32_e32 v87, v86, v86
	s_nop 0
	v_add_f32_e32 v74, v91, v85
	v_add_f32_e32 v74, v93, v74
	v_add_f32_e32 v84, v87, v74
	s_waitcnt vmcnt(16)
	v_lshlrev_b32_e32 v74, 16, v224
	v_and_b32_e32 v75, 0xffff0000, v224
	v_lshlrev_b32_e32 v76, 16, v225
	v_and_b32_e32 v77, 0xffff0000, v225
	v_lshlrev_b32_e32 v78, 16, v226
	v_and_b32_e32 v79, 0xffff0000, v226
	v_pk_add_f32 v[72:73], v[72:73], v[76:77]
	v_pk_add_f32 v[70:71], v[70:71], v[74:75]
	v_lshlrev_b32_e32 v80, 16, v227
	v_and_b32_e32 v81, 0xffff0000, v227
	v_lshl_add_u64 v[188:189], v[88:89], 0, v[184:185]
	global_load_dwordx4 v[220:223], v[188:189], off
	global_load_dwordx4 v[224:227], v[188:189], off offset:256
	v_pk_add_f32 v[76:77], v[66:67], v[78:79]
	v_mul_f32_e32 v78, v71, v71
	v_mul_f32_e32 v79, v73, v73
	v_pk_add_f32 v[74:75], v[68:69], v[80:81]
	v_mul_f32_e32 v80, v77, v77
	v_cvt_pk_bf16_f32 v66, v70, v71
	v_fmac_f32_e32 v78, v70, v70
	v_fmac_f32_e32 v79, v72, v72
	v_mul_f32_e32 v81, v75, v75
	v_cvt_pk_bf16_f32 v67, v72, v73
	v_cvt_pk_bf16_f32 v68, v76, v77
	v_cvt_pk_bf16_f32 v69, v74, v75
	v_fmac_f32_e32 v80, v76, v76
	global_store_dwordx4 v[88:89], v[66:69], off offset:256 nt
	v_fmac_f32_e32 v81, v74, v74
	s_nop 0
	v_add_f32_e32 v66, v78, v79
	v_add_f32_e32 v66, v80, v66
	v_add_f32_e32 v66, v81, v66
	v_add_f32_e32 v66, v84, v66
	v_mov_b32_e32 v67, v66
	s_nop 1
	v_permlane32_swap_b32_e32 v66, v67
	v_add_f32_e32 v66, v66, v67
	v_mov_b32_e32 v67, v66
	s_nop 1
	v_permlane16_swap_b32_e32 v66, v67
	s_and_saveexec_b64 s[38:39], vcc
	s_cbranch_execz .LBB0_781
	v_add_f32_e32 v68, v66, v67
	v_lshlrev_b64 v[66:67], 6, v[82:83]
	v_lshl_add_u64 v[66:67], s[10:11], 0, v[66:67]
	v_lshl_add_u64 v[66:67], s[26:27], 2, v[66:67]
	s_lshl_b32 s86, s45, 2
	v_lshl_add_u64 v[66:67], v[66:67], 0, s[86:87]
	global_store_dword v[66:67], v68, off
;     __device__ __forceinline__ void operator()(f32x4 (&acc)[2][2][4][2], const Unit& u, int ui, int wr, int wc, int fr_, int fq_) const {
;     ...
;         const int row0 = u.pm * BM + wr * 64 + fr, col0 = u.pn * BM + wc * 32 + 8 * fq;
; #pragma unroll
;         for (int ai = 0; ai < 2; ++ai)
; #pragma unroll
;             for (int m = 0; m < 4; ++m) { const size_t off = (size_t)(row0 + ai * HALF + m * 16) * 1024 + col0; float s = 0.f;
; #pragma unroll
;                 for (int bj = 0; bj < 2; ++bj) { f32x4 v0, v1;
;                     if (IN32) { const float* xi = Xin32 + off + bj * HALF; v0 = *(const f32x4*)xi; v1 = *(const f32x4*)(xi + 4); }
;                     else { const u32x4 w = *(const u32x4*)(XB + off + bj * HALF);
;                         if (RESID_F16) { const f32x2p_t a = unpk2h(w.x), b = unpk2h(w.y), c2 = unpk2h(w.z), d = unpk2h(w.w); v0 = (f32x4){a.x, a.y, b.x, b.y}; v1 = (f32x4){c2.x, c2.y, d.x, d.y}; }
;                         else { v0 = (f32x4){__builtin_bit_cast(float, w.x << 16), __builtin_bit_cast(float, w.x & 0xffff0000u), __builtin_bit_cast(float, w.y << 16), __builtin_bit_cast(float, w.y & 0xffff0000u)};
;                                v1 = (f32x4){__builtin_bit_cast(float, w.z << 16), __builtin_bit_cast(float, w.z & 0xffff0000u), __builtin_bit_cast(float, w.w << 16), __builtin_bit_cast(float, w.w & 0xffff0000u)}; } }
;                     v0 = v0 + acc[ai][bj][m][0]; v1 = v1 + acc[ai][bj][m][1];
;                     if (OUT32) { float* xp = Xout32 + off + bj * HALF; __builtin_nontemporal_store(v0, (f32x4*)xp); __builtin_nontemporal_store(v1, (f32x4*)(xp + 4)); }
;                     s += (v0[0] * v0[0] + v0[1] * v0[1]) + (v0[2] * v0[2] + v0[3] * v0[3]) + (v1[0] * v1[0] + v1[1] * v1[1]) + (v1[2] * v1[2] + v1[3] * v1[3]);
;                     u32x4 w; if (RESID_F16) { w.x = pk2h(v0[0], v0[1]); w.y = pk2h(v0[2], v0[3]); w.z = pk2h(v1[0], v1[1]); w.w = pk2h(v1[2], v1[3]); } else { w.x = cvt_pk_bf16(v0[0], v0[1]); w.y = cvt_pk_bf16(v0[2], v0[3]); w.z = cvt_pk_bf16(v1[0], v1[1]); w.w = cvt_pk_bf16(v1[2], v1[3]); }
;                     *(u32x4*)(XB + off + bj * HALF) = w; }
;                 s = fq_sum(s);
;                 if (fq == 0) SS[(size_t)(row0 + ai * HALF + m * 16) * 16 + u.pn * 4 + wc] = s;
;                 asm volatile("" ::: "memory"); }
.LBB0_781:
	s_or_b64 exec, exec, s[38:39]
	v_add_u32_e32 v66, 0x80, v142
	v_ashrrev_i32_e32 v67, 31, v66
	v_lshlrev_b64 v[68:69], 11, v[66:67]
	v_lshl_add_u64 v[68:69], s[8:9], 0, v[68:69]
	v_lshl_add_u64 v[72:73], v[140:141], 1, v[68:69]
	s_waitcnt vmcnt(18)
	v_lshlrev_b32_e32 v74, 16, v196
	v_and_b32_e32 v75, 0xffff0000, v196
	v_lshlrev_b32_e32 v68, 16, v197
	v_and_b32_e32 v69, 0xffff0000, v197
	v_lshlrev_b32_e32 v76, 16, v198
	v_and_b32_e32 v77, 0xffff0000, v198
	v_lshlrev_b32_e32 v70, 16, v199
	v_and_b32_e32 v71, 0xffff0000, v199
	v_pk_add_f32 v[68:69], v[64:65], v[68:69]
	v_pk_add_f32 v[74:75], v[62:63], v[74:75]
	v_pk_add_f32 v[70:71], v[60:61], v[70:71]
	v_pk_add_f32 v[76:77], v[58:59], v[76:77]
	v_cvt_pk_bf16_f32 v58, v74, v75
	v_cvt_pk_bf16_f32 v59, v68, v69
	v_mul_f32_e32 v75, v75, v75
	v_cvt_pk_bf16_f32 v60, v76, v77
	v_cvt_pk_bf16_f32 v61, v70, v71
	v_mul_f32_e32 v69, v69, v69
	v_mul_f32_e32 v77, v77, v77
	v_fmac_f32_e32 v75, v74, v74
	v_fmac_f32_e32 v69, v68, v68
	v_mul_f32_e32 v71, v71, v71
	v_fmac_f32_e32 v77, v76, v76
	global_store_dwordx4 v[72:73], v[58:61], off nt
	v_fmac_f32_e32 v71, v70, v70
	s_nop 0
	v_add_f32_e32 v58, v75, v69
	v_add_f32_e32 v58, v77, v58
	v_add_f32_e32 v68, v71, v58
	s_waitcnt vmcnt(18)
	v_lshlrev_b32_e32 v58, 16, v200
	v_and_b32_e32 v59, 0xffff0000, v200
	v_lshlrev_b32_e32 v60, 16, v201
	v_and_b32_e32 v61, 0xffff0000, v201
	v_lshlrev_b32_e32 v62, 16, v202
	v_and_b32_e32 v63, 0xffff0000, v202
	v_pk_add_f32 v[56:57], v[56:57], v[60:61]
	v_pk_add_f32 v[54:55], v[54:55], v[58:59]
	v_lshlrev_b32_e32 v64, 16, v203
	v_and_b32_e32 v65, 0xffff0000, v203
	v_pk_add_f32 v[60:61], v[50:51], v[62:63]
	v_mul_f32_e32 v62, v55, v55
	v_mul_f32_e32 v63, v57, v57
	v_pk_add_f32 v[58:59], v[52:53], v[64:65]
	v_mul_f32_e32 v64, v61, v61
	v_cvt_pk_bf16_f32 v50, v54, v55
	v_fmac_f32_e32 v62, v54, v54
	v_fmac_f32_e32 v63, v56, v56
	v_mul_f32_e32 v65, v59, v59
	v_cvt_pk_bf16_f32 v51, v56, v57
	v_cvt_pk_bf16_f32 v52, v60, v61
	v_cvt_pk_bf16_f32 v53, v58, v59
	v_fmac_f32_e32 v64, v60, v60
	global_store_dwordx4 v[72:73], v[50:53], off offset:256 nt
	v_fmac_f32_e32 v65, v58, v58
	s_nop 0
	v_add_f32_e32 v50, v62, v63
	v_add_f32_e32 v50, v64, v50
	v_add_f32_e32 v50, v65, v50
	v_add_f32_e32 v50, v68, v50
	v_mov_b32_e32 v51, v50
	s_nop 1
	v_permlane32_swap_b32_e32 v50, v51
	v_add_f32_e32 v50, v50, v51
	v_mov_b32_e32 v51, v50
	s_nop 1
	v_permlane16_swap_b32_e32 v50, v51
	s_and_saveexec_b64 s[38:39], vcc
	s_cbranch_execz .LBB0_783
	v_add_f32_e32 v52, v50, v51
	v_lshlrev_b64 v[50:51], 6, v[66:67]
	v_lshl_add_u64 v[50:51], s[10:11], 0, v[50:51]
	v_lshl_add_u64 v[50:51], s[26:27], 2, v[50:51]
	s_lshl_b32 s86, s45, 2
	v_lshl_add_u64 v[50:51], v[50:51], 0, s[86:87]
	global_store_dword v[50:51], v52, off
.LBB0_783:
	s_or_b64 exec, exec, s[38:39]
	v_add_u32_e32 v50, 0x90, v142
	v_ashrrev_i32_e32 v51, 31, v50
	v_lshlrev_b64 v[52:53], 11, v[50:51]
	v_lshl_add_u64 v[52:53], s[8:9], 0, v[52:53]
	v_lshl_add_u64 v[56:57], v[140:141], 1, v[52:53]
	s_waitcnt vmcnt(16)
	v_lshlrev_b32_e32 v58, 16, v204
	v_and_b32_e32 v59, 0xffff0000, v204
	v_lshlrev_b32_e32 v52, 16, v205
	v_and_b32_e32 v53, 0xffff0000, v205
	v_lshlrev_b32_e32 v60, 16, v206
	v_and_b32_e32 v61, 0xffff0000, v206
	v_lshlrev_b32_e32 v54, 16, v207
	v_and_b32_e32 v55, 0xffff0000, v207
	v_pk_add_f32 v[52:53], v[48:49], v[52:53]
	v_pk_add_f32 v[58:59], v[46:47], v[58:59]
	v_pk_add_f32 v[54:55], v[44:45], v[54:55]
	v_pk_add_f32 v[60:61], v[42:43], v[60:61]
	v_cvt_pk_bf16_f32 v42, v58, v59
	v_cvt_pk_bf16_f32 v43, v52, v53
	v_mul_f32_e32 v59, v59, v59
	v_cvt_pk_bf16_f32 v44, v60, v61
	v_cvt_pk_bf16_f32 v45, v54, v55
	v_mul_f32_e32 v53, v53, v53
	v_mul_f32_e32 v61, v61, v61
	v_fmac_f32_e32 v59, v58, v58
	v_fmac_f32_e32 v53, v52, v52
	v_mul_f32_e32 v55, v55, v55
	v_fmac_f32_e32 v61, v60, v60
	global_store_dwordx4 v[56:57], v[42:45], off nt
	v_fmac_f32_e32 v55, v54, v54
	s_nop 0
	v_add_f32_e32 v42, v59, v53
	v_add_f32_e32 v42, v61, v42
	v_add_f32_e32 v52, v55, v42
	s_waitcnt vmcnt(16)
	v_lshlrev_b32_e32 v42, 16, v208
	v_and_b32_e32 v43, 0xffff0000, v208
	v_lshlrev_b32_e32 v44, 16, v209
	v_and_b32_e32 v45, 0xffff0000, v209
	v_lshlrev_b32_e32 v46, 16, v210
	v_and_b32_e32 v47, 0xffff0000, v210
	v_pk_add_f32 v[40:41], v[40:41], v[44:45]
	v_pk_add_f32 v[38:39], v[38:39], v[42:43]
	v_lshlrev_b32_e32 v48, 16, v211
	v_and_b32_e32 v49, 0xffff0000, v211
	v_pk_add_f32 v[44:45], v[34:35], v[46:47]
	v_mul_f32_e32 v46, v39, v39
	v_mul_f32_e32 v47, v41, v41
	v_pk_add_f32 v[42:43], v[36:37], v[48:49]
	v_mul_f32_e32 v48, v45, v45
	v_cvt_pk_bf16_f32 v34, v38, v39
	v_fmac_f32_e32 v46, v38, v38
	v_fmac_f32_e32 v47, v40, v40
	v_mul_f32_e32 v49, v43, v43
	v_cvt_pk_bf16_f32 v35, v40, v41
	v_cvt_pk_bf16_f32 v36, v44, v45
	v_cvt_pk_bf16_f32 v37, v42, v43
	v_fmac_f32_e32 v48, v44, v44
	global_store_dwordx4 v[56:57], v[34:37], off offset:256 nt
	v_fmac_f32_e32 v49, v42, v42
	s_nop 0
	v_add_f32_e32 v34, v46, v47
	v_add_f32_e32 v34, v48, v34
	v_add_f32_e32 v34, v49, v34
	v_add_f32_e32 v34, v52, v34
	v_mov_b32_e32 v35, v34
	s_nop 1
	v_permlane32_swap_b32_e32 v34, v35
	v_add_f32_e32 v34, v34, v35
	v_mov_b32_e32 v35, v34
	s_nop 1
	v_permlane16_swap_b32_e32 v34, v35
	s_and_saveexec_b64 s[38:39], vcc
	s_cbranch_execz .LBB0_785
	v_add_f32_e32 v36, v34, v35
	v_lshlrev_b64 v[34:35], 6, v[50:51]
	v_lshl_add_u64 v[34:35], s[10:11], 0, v[34:35]
	v_lshl_add_u64 v[34:35], s[26:27], 2, v[34:35]
	s_lshl_b32 s86, s45, 2
	v_lshl_add_u64 v[34:35], v[34:35], 0, s[86:87]
	global_store_dword v[34:35], v36, off
;     __device__ __forceinline__ void operator()(f32x4 (&acc)[2][2][4][2], const Unit& u, int ui, int wr, int wc, int fr_, int fq_) const {
;     ...
;         const int row0 = u.pm * BM + wr * 64 + fr, col0 = u.pn * BM + wc * 32 + 8 * fq;
; #pragma unroll
;         for (int ai = 0; ai < 2; ++ai)
; #pragma unroll
;             for (int m = 0; m < 4; ++m) { const size_t off = (size_t)(row0 + ai * HALF + m * 16) * 1024 + col0; float s = 0.f;
; #pragma unroll
;                 for (int bj = 0; bj < 2; ++bj) { f32x4 v0, v1;
;                     if (IN32) { const float* xi = Xin32 + off + bj * HALF; v0 = *(const f32x4*)xi; v1 = *(const f32x4*)(xi + 4); }
;                     else { const u32x4 w = *(const u32x4*)(XB + off + bj * HALF);
;                         if (RESID_F16) { const f32x2p_t a = unpk2h(w.x), b = unpk2h(w.y), c2 = unpk2h(w.z), d = unpk2h(w.w); v0 = (f32x4){a.x, a.y, b.x, b.y}; v1 = (f32x4){c2.x, c2.y, d.x, d.y}; }
;                         else { v0 = (f32x4){__builtin_bit_cast(float, w.x << 16), __builtin_bit_cast(float, w.x & 0xffff0000u), __builtin_bit_cast(float, w.y << 16), __builtin_bit_cast(float, w.y & 0xffff0000u)};
;                                v1 = (f32x4){__builtin_bit_cast(float, w.z << 16), __builtin_bit_cast(float, w.z & 0xffff0000u), __builtin_bit_cast(float, w.w << 16), __builtin_bit_cast(float, w.w & 0xffff0000u)}; } }
;                     v0 = v0 + acc[ai][bj][m][0]; v1 = v1 + acc[ai][bj][m][1];
;                     if (OUT32) { float* xp = Xout32 + off + bj * HALF; __builtin_nontemporal_store(v0, (f32x4*)xp); __builtin_nontemporal_store(v1, (f32x4*)(xp + 4)); }
;                     s += (v0[0] * v0[0] + v0[1] * v0[1]) + (v0[2] * v0[2] + v0[3] * v0[3]) + (v1[0] * v1[0] + v1[1] * v1[1]) + (v1[2] * v1[2] + v1[3] * v1[3]);
;                     u32x4 w; if (RESID_F16) { w.x = pk2h(v0[0], v0[1]); w.y = pk2h(v0[2], v0[3]); w.z = pk2h(v1[0], v1[1]); w.w = pk2h(v1[2], v1[3]); } else { w.x = cvt_pk_bf16(v0[0], v0[1]); w.y = cvt_pk_bf16(v0[2], v0[3]); w.z = cvt_pk_bf16(v1[0], v1[1]); w.w = cvt_pk_bf16(v1[2], v1[3]); }
;                     *(u32x4*)(XB + off + bj * HALF) = w; }
;                 s = fq_sum(s);
;                 if (fq == 0) SS[(size_t)(row0 + ai * HALF + m * 16) * 16 + u.pn * 4 + wc] = s;
;                 asm volatile("" ::: "memory"); }
.LBB0_785:
	s_or_b64 exec, exec, s[38:39]
	v_add_u32_e32 v34, 0xa0, v142
	v_ashrrev_i32_e32 v35, 31, v34
	v_lshlrev_b64 v[36:37], 11, v[34:35]
	v_lshl_add_u64 v[36:37], s[8:9], 0, v[36:37]
	v_lshl_add_u64 v[40:41], v[140:141], 1, v[36:37]
	s_waitcnt vmcnt(14)
	v_lshlrev_b32_e32 v42, 16, v212
	v_and_b32_e32 v43, 0xffff0000, v212
	v_lshlrev_b32_e32 v36, 16, v213
	v_and_b32_e32 v37, 0xffff0000, v213
	v_lshlrev_b32_e32 v44, 16, v214
	v_and_b32_e32 v45, 0xffff0000, v214
	v_lshlrev_b32_e32 v38, 16, v215
	v_and_b32_e32 v39, 0xffff0000, v215
	v_pk_add_f32 v[36:37], v[32:33], v[36:37]
	v_pk_add_f32 v[42:43], v[30:31], v[42:43]
	v_pk_add_f32 v[38:39], v[28:29], v[38:39]
	v_pk_add_f32 v[44:45], v[26:27], v[44:45]
	v_cvt_pk_bf16_f32 v26, v42, v43
	v_cvt_pk_bf16_f32 v27, v36, v37
	v_mul_f32_e32 v43, v43, v43
	v_cvt_pk_bf16_f32 v28, v44, v45
	v_cvt_pk_bf16_f32 v29, v38, v39
	v_mul_f32_e32 v37, v37, v37
	v_mul_f32_e32 v45, v45, v45
	v_fmac_f32_e32 v43, v42, v42
	v_fmac_f32_e32 v37, v36, v36
	v_mul_f32_e32 v39, v39, v39
	v_fmac_f32_e32 v45, v44, v44
	global_store_dwordx4 v[40:41], v[26:29], off nt
	v_fmac_f32_e32 v39, v38, v38
	s_nop 0
	v_add_f32_e32 v26, v43, v37
	v_add_f32_e32 v26, v45, v26
	v_add_f32_e32 v36, v39, v26
	s_waitcnt vmcnt(14)
	v_lshlrev_b32_e32 v26, 16, v216
	v_and_b32_e32 v27, 0xffff0000, v216
	v_lshlrev_b32_e32 v28, 16, v217
	v_and_b32_e32 v29, 0xffff0000, v217
	v_lshlrev_b32_e32 v30, 16, v218
	v_and_b32_e32 v31, 0xffff0000, v218
	v_pk_add_f32 v[24:25], v[24:25], v[28:29]
	v_pk_add_f32 v[22:23], v[22:23], v[26:27]
	v_lshlrev_b32_e32 v32, 16, v219
	v_and_b32_e32 v33, 0xffff0000, v219
	v_pk_add_f32 v[28:29], v[18:19], v[30:31]
	v_mul_f32_e32 v30, v23, v23
	v_mul_f32_e32 v31, v25, v25
	v_pk_add_f32 v[26:27], v[20:21], v[32:33]
	v_mul_f32_e32 v32, v29, v29
	v_cvt_pk_bf16_f32 v18, v22, v23
	v_fmac_f32_e32 v30, v22, v22
	v_fmac_f32_e32 v31, v24, v24
	v_mul_f32_e32 v33, v27, v27
	v_cvt_pk_bf16_f32 v19, v24, v25
	v_cvt_pk_bf16_f32 v20, v28, v29
	v_cvt_pk_bf16_f32 v21, v26, v27
	v_fmac_f32_e32 v32, v28, v28
	global_store_dwordx4 v[40:41], v[18:21], off offset:256 nt
	v_fmac_f32_e32 v33, v26, v26
	s_nop 0
	v_add_f32_e32 v18, v30, v31
	v_add_f32_e32 v18, v32, v18
	v_add_f32_e32 v18, v33, v18
	v_add_f32_e32 v18, v36, v18
	v_mov_b32_e32 v19, v18
	s_nop 1
	v_permlane32_swap_b32_e32 v18, v19
	v_add_f32_e32 v18, v18, v19
	v_mov_b32_e32 v19, v18
	s_nop 1
	v_permlane16_swap_b32_e32 v18, v19
	s_and_saveexec_b64 s[38:39], vcc
	s_cbranch_execz .LBB0_787
	v_add_f32_e32 v20, v18, v19
	v_lshlrev_b64 v[18:19], 6, v[34:35]
	v_lshl_add_u64 v[18:19], s[10:11], 0, v[18:19]
	v_lshl_add_u64 v[18:19], s[26:27], 2, v[18:19]
	s_lshl_b32 s86, s45, 2
	v_lshl_add_u64 v[18:19], v[18:19], 0, s[86:87]
	global_store_dword v[18:19], v20, off
.LBB0_787:
	s_or_b64 exec, exec, s[38:39]
	v_add_u32_e32 v18, 0xb0, v142
	v_ashrrev_i32_e32 v19, 31, v18
	v_lshlrev_b64 v[20:21], 11, v[18:19]
	v_lshl_add_u64 v[20:21], s[8:9], 0, v[20:21]
	v_lshl_add_u64 v[24:25], v[140:141], 1, v[20:21]
	s_waitcnt vmcnt(12)
	v_lshlrev_b32_e32 v26, 16, v220
	v_and_b32_e32 v27, 0xffff0000, v220
	v_lshlrev_b32_e32 v20, 16, v221
	v_and_b32_e32 v21, 0xffff0000, v221
	v_lshlrev_b32_e32 v28, 16, v222
	v_and_b32_e32 v29, 0xffff0000, v222
	v_lshlrev_b32_e32 v22, 16, v223
	v_and_b32_e32 v23, 0xffff0000, v223
	v_pk_add_f32 v[20:21], v[16:17], v[20:21]
	v_pk_add_f32 v[26:27], v[14:15], v[26:27]
	v_pk_add_f32 v[22:23], v[12:13], v[22:23]
	v_pk_add_f32 v[28:29], v[10:11], v[28:29]
	v_cvt_pk_bf16_f32 v10, v26, v27
	v_cvt_pk_bf16_f32 v11, v20, v21
	v_mul_f32_e32 v27, v27, v27
	v_cvt_pk_bf16_f32 v12, v28, v29
	v_cvt_pk_bf16_f32 v13, v22, v23
	v_mul_f32_e32 v21, v21, v21
	v_mul_f32_e32 v29, v29, v29
	v_fmac_f32_e32 v27, v26, v26
	v_fmac_f32_e32 v21, v20, v20
	v_mul_f32_e32 v23, v23, v23
	v_fmac_f32_e32 v29, v28, v28
	global_store_dwordx4 v[24:25], v[10:13], off nt
	v_fmac_f32_e32 v23, v22, v22
	s_nop 0
	v_add_f32_e32 v10, v27, v21
	v_add_f32_e32 v10, v29, v10
	v_add_f32_e32 v20, v23, v10
	s_waitcnt vmcnt(12)
	v_lshlrev_b32_e32 v10, 16, v224
	v_and_b32_e32 v11, 0xffff0000, v224
	v_lshlrev_b32_e32 v12, 16, v225
	v_and_b32_e32 v13, 0xffff0000, v225
	v_lshlrev_b32_e32 v14, 16, v226
	v_and_b32_e32 v15, 0xffff0000, v226
	v_pk_add_f32 v[8:9], v[8:9], v[12:13]
	v_pk_add_f32 v[6:7], v[6:7], v[10:11]
	v_lshlrev_b32_e32 v16, 16, v227
	v_and_b32_e32 v17, 0xffff0000, v227
	v_pk_add_f32 v[12:13], v[2:3], v[14:15]
	v_mul_f32_e32 v14, v7, v7
	v_mul_f32_e32 v15, v9, v9
	v_pk_add_f32 v[10:11], v[4:5], v[16:17]
	v_mul_f32_e32 v16, v13, v13
	v_cvt_pk_bf16_f32 v2, v6, v7
	v_fmac_f32_e32 v14, v6, v6
	v_fmac_f32_e32 v15, v8, v8
	v_mul_f32_e32 v17, v11, v11
	v_cvt_pk_bf16_f32 v3, v8, v9
	v_cvt_pk_bf16_f32 v4, v12, v13
	v_cvt_pk_bf16_f32 v5, v10, v11
	v_fmac_f32_e32 v16, v12, v12
	global_store_dwordx4 v[24:25], v[2:5], off offset:256 nt
	v_fmac_f32_e32 v17, v10, v10
	s_nop 0
	v_add_f32_e32 v2, v14, v15
	v_add_f32_e32 v2, v16, v2
	v_add_f32_e32 v2, v17, v2
	v_add_f32_e32 v2, v20, v2
	v_mov_b32_e32 v3, v2
	s_nop 1
	v_permlane32_swap_b32_e32 v2, v3
	v_add_f32_e32 v2, v2, v3
	v_mov_b32_e32 v3, v2
	s_nop 1
	v_permlane16_swap_b32_e32 v2, v3
	s_and_saveexec_b64 s[38:39], vcc
	s_cbranch_execz .LBB0_789
	v_add_f32_e32 v4, v2, v3
	v_lshlrev_b64 v[2:3], 6, v[18:19]
	v_lshl_add_u64 v[2:3], s[10:11], 0, v[2:3]
	v_lshl_add_u64 v[2:3], s[26:27], 2, v[2:3]
	s_lshl_b32 s86, s45, 2
	v_lshl_add_u64 v[2:3], v[2:3], 0, s[86:87]
	global_store_dword v[2:3], v4, off

;     __device__ __forceinline__ void operator()(f32x4 (&acc)[2][2][4][2], const Unit& u, int ui, int wr, int wc, int fr_, int fq_) const {
;     ...
;             for (int m = 0; m < 4; ++m) { const float r = rtab[ui * 256 + ai * HALF + wr * 64 + m * 16 + fr];
; #pragma unroll
;                 for (int bj = 0; bj < 2; ++bj)
; #pragma unroll
;                     for (int n = 0; n < 2; ++n) acc[ai][bj][m][n] = acc[ai][bj][m][n] * r; }
.LBB0_905:
	s_lshl_b32 s4, s51, 10
	v_mov_b32_e32 v154, v144
	v_mov_b32_e32 v155, v145
	s_add_i32 s4, s47, s4
	s_mov_b64 s[24:25], -1
	v_lshl_add_u32 v156, v154, 2, s4
	ds_read2_b32 v[148:149], v156 offset1:16
	s_lshl_b32 s4, s50, 8
	s_add_i32 s4, s4, s43
	s_waitcnt lgkmcnt(0)
	v_pk_mul_f32 v[142:143], v[128:129], v[148:149] op_sel_hi:[1,0]
	v_pk_mul_f32 v[150:151], v[126:127], v[148:149] op_sel_hi:[1,0]
	v_pk_mul_f32 v[140:141], v[124:125], v[148:149] op_sel_hi:[1,0]
	v_pk_mul_f32 v[152:153], v[122:123], v[148:149] op_sel_hi:[1,0]
	v_pk_mul_f32 v[124:125], v[112:113], v[148:149] op_sel_hi:[1,0]
	v_pk_mul_f32 v[128:129], v[110:111], v[148:149] op_sel_hi:[1,0]
	v_pk_mul_f32 v[122:123], v[108:109], v[148:149] op_sel_hi:[1,0]
	v_pk_mul_f32 v[126:127], v[106:107], v[148:149] op_sel_hi:[1,0]
	v_mov_b32_e32 v148, v149
	v_pk_mul_f32 v[108:109], v[120:121], v[148:149] op_sel_hi:[1,0]
	v_pk_mul_f32 v[112:113], v[118:119], v[148:149] op_sel_hi:[1,0]
	v_pk_mul_f32 v[106:107], v[116:117], v[148:149] op_sel_hi:[1,0]
	v_pk_mul_f32 v[110:111], v[114:115], v[148:149] op_sel_hi:[1,0]
	v_pk_mul_f32 v[104:105], v[104:105], v[148:149] op_sel_hi:[1,0]
	v_pk_mul_f32 v[102:103], v[102:103], v[148:149] op_sel_hi:[1,0]
	v_pk_mul_f32 v[100:101], v[100:101], v[148:149] op_sel_hi:[1,0]
	v_pk_mul_f32 v[98:99], v[98:99], v[148:149] op_sel_hi:[1,0]
	ds_read2_b32 v[148:149], v156 offset0:32 offset1:48
	s_waitcnt lgkmcnt(0)
	v_pk_mul_f32 v[116:117], v[96:97], v[148:149] op_sel_hi:[1,0]
	v_pk_mul_f32 v[120:121], v[94:95], v[148:149] op_sel_hi:[1,0]
	v_pk_mul_f32 v[114:115], v[92:93], v[148:149] op_sel_hi:[1,0]
	v_pk_mul_f32 v[118:119], v[90:91], v[148:149] op_sel_hi:[1,0]
	v_pk_mul_f32 v[92:93], v[80:81], v[148:149] op_sel_hi:[1,0]
	v_pk_mul_f32 v[96:97], v[78:79], v[148:149] op_sel_hi:[1,0]
	v_pk_mul_f32 v[90:91], v[76:77], v[148:149] op_sel_hi:[1,0]
	v_pk_mul_f32 v[94:95], v[74:75], v[148:149] op_sel_hi:[1,0]
	v_mov_b32_e32 v148, v149
	v_pk_mul_f32 v[76:77], v[88:89], v[148:149] op_sel_hi:[1,0]
	v_pk_mul_f32 v[80:81], v[86:87], v[148:149] op_sel_hi:[1,0]
	v_pk_mul_f32 v[74:75], v[84:85], v[148:149] op_sel_hi:[1,0]
	v_pk_mul_f32 v[78:79], v[82:83], v[148:149] op_sel_hi:[1,0]
	v_pk_mul_f32 v[72:73], v[72:73], v[148:149] op_sel_hi:[1,0]
	v_pk_mul_f32 v[70:71], v[70:71], v[148:149] op_sel_hi:[1,0]
	v_pk_mul_f32 v[68:69], v[68:69], v[148:149] op_sel_hi:[1,0]
	v_pk_mul_f32 v[66:67], v[66:67], v[148:149] op_sel_hi:[1,0]
	ds_read2_b32 v[148:149], v156 offset0:128 offset1:144
	s_waitcnt lgkmcnt(0)
	v_pk_mul_f32 v[84:85], v[64:65], v[148:149] op_sel_hi:[1,0]
	v_pk_mul_f32 v[88:89], v[62:63], v[148:149] op_sel_hi:[1,0]
	v_pk_mul_f32 v[82:83], v[60:61], v[148:149] op_sel_hi:[1,0]
	v_pk_mul_f32 v[86:87], v[58:59], v[148:149] op_sel_hi:[1,0]
	v_pk_mul_f32 v[60:61], v[48:49], v[148:149] op_sel_hi:[1,0]
	v_pk_mul_f32 v[64:65], v[46:47], v[148:149] op_sel_hi:[1,0]
	v_pk_mul_f32 v[58:59], v[44:45], v[148:149] op_sel_hi:[1,0]
	v_pk_mul_f32 v[62:63], v[42:43], v[148:149] op_sel_hi:[1,0]
	v_mov_b32_e32 v148, v149
	v_pk_mul_f32 v[44:45], v[56:57], v[148:149] op_sel_hi:[1,0]
	v_pk_mul_f32 v[48:49], v[54:55], v[148:149] op_sel_hi:[1,0]
	v_pk_mul_f32 v[42:43], v[52:53], v[148:149] op_sel_hi:[1,0]
	v_pk_mul_f32 v[46:47], v[50:51], v[148:149] op_sel_hi:[1,0]
	v_pk_mul_f32 v[40:41], v[40:41], v[148:149] op_sel_hi:[1,0]
	v_pk_mul_f32 v[38:39], v[38:39], v[148:149] op_sel_hi:[1,0]
	v_pk_mul_f32 v[36:37], v[36:37], v[148:149] op_sel_hi:[1,0]
	v_pk_mul_f32 v[34:35], v[34:35], v[148:149] op_sel_hi:[1,0]
	ds_read2_b32 v[148:149], v156 offset0:160 offset1:176
	s_waitcnt lgkmcnt(0)
; __device__ __forceinline__ unsigned cvt_pk_bf16(float lo, float hi) { unsigned r; asm volatile("v_cvt_pk_bf16_f32 %0, %1, %2" : "=v"(r) : "v"(lo), "v"(hi)); return r; }
;     __device__ __forceinline__ void operator()(f32x4 (&acc)[2][2][4][2], const Unit& u, int ui, int wr, int wc, int fr_, int fq_) const {
;     ...
;             for (int m = 0; m < 4; ++m) { const float r = rtab[ui * 256 + ai * HALF + wr * 64 + m * 16 + fr];
; #pragma unroll
;                 for (int bj = 0; bj < 2; ++bj)
; #pragma unroll
;                     for (int n = 0; n < 2; ++n) acc[ai][bj][m][n] = acc[ai][bj][m][n] * r; }
;     ...
;         const int row0 = u.pm * BM + wr * 64 + fr, col0 = u.pn * BM + wc * 32 + 8 * fq;
; #pragma unroll
;         for (int ai = 0; ai < 2; ++ai)
; #pragma unroll
;             for (int m = 0; m < 4; ++m) {
; #pragma unroll
;                 for (int bj = 0; bj < 2; ++bj) { const f32x4 v0 = acc[ai][bj][m][0], v1 = acc[ai][bj][m][1]; u32x4 w;
;                     w.x = cvt_pk_bf16(v0[0], v0[1]); w.y = cvt_pk_bf16(v0[2], v0[3]); w.z = cvt_pk_bf16(v1[0], v1[1]); w.w = cvt_pk_bf16(v1[2], v1[3]);
;                     const int row = row0 + ai * HALF + m * 16;
;                     if (MODE == 0) {
;                         const int hd = (u.pn & 1) * 4 + bj * 2 + (wc >> 1), d = (wc & 1) * 32 + 8 * fq;
;                         *(u32x4*)(O + (size_t)(u.pn >> 1) * ((size_t)32768 * 512) + ((size_t)((row >> 13) * 8 + hd) * 8192 + (row & 8191)) * 64 + d) = w;
;                     } else *(u32x4*)(O + (size_t)row * ldc + col0 + bj * HALF) = w; } }
	v_pk_mul_f32 v[52:53], v[32:33], v[148:149] op_sel_hi:[1,0]
	v_pk_mul_f32 v[56:57], v[30:31], v[148:149] op_sel_hi:[1,0]
	v_pk_mul_f32 v[50:51], v[28:29], v[148:149] op_sel_hi:[1,0]
	v_pk_mul_f32 v[54:55], v[26:27], v[148:149] op_sel_hi:[1,0]
	v_pk_mul_f32 v[28:29], v[16:17], v[148:149] op_sel_hi:[1,0]
	v_pk_mul_f32 v[32:33], v[14:15], v[148:149] op_sel_hi:[1,0]
	v_pk_mul_f32 v[26:27], v[12:13], v[148:149] op_sel_hi:[1,0]
	v_pk_mul_f32 v[30:31], v[10:11], v[148:149] op_sel_hi:[1,0]
	v_mov_b32_e32 v148, v149
	v_pk_mul_f32 v[14:15], v[18:19], v[148:149] op_sel_hi:[1,0]
	v_add_u32_e32 v18, s4, v154
	s_lshl_b32 s4, s49, 8
	s_or_b32 s4, s4, s44
	v_ashrrev_i32_e32 v19, 31, v18
	v_pk_mul_f32 v[12:13], v[24:25], v[148:149] op_sel_hi:[1,0]
	v_lshl_add_u32 v24, v155, 3, s4
	v_lshlrev_b64 v[18:19], 10, v[18:19]
	v_ashrrev_i32_e32 v25, 31, v24
	v_lshl_add_u64 v[18:19], s[8:9], 0, v[18:19]
	v_pk_mul_f32 v[16:17], v[22:23], v[148:149] op_sel_hi:[1,0]
	v_pk_mul_f32 v[10:11], v[20:21], v[148:149] op_sel_hi:[1,0]
	v_cvt_pk_bf16_f32 v20, v150, v151
	v_cvt_pk_bf16_f32 v21, v142, v143
	v_cvt_pk_bf16_f32 v22, v152, v153
	v_cvt_pk_bf16_f32 v23, v140, v141
	v_lshl_add_u64 v[18:19], v[24:25], 1, v[18:19]
	s_mov_b64 s[4:5], 0x4000
	global_store_dwordx4 v[18:19], v[20:23], off nt
	v_lshl_add_u64 v[24:25], v[18:19], 0, s[4:5]
	s_movk_i32 s4, 0x4000
	v_cvt_pk_bf16_f32 v20, v128, v129
	v_cvt_pk_bf16_f32 v21, v124, v125
	v_cvt_pk_bf16_f32 v22, v126, v127
	v_cvt_pk_bf16_f32 v23, v122, v123
	global_store_dwordx4 v[18:19], v[20:23], off offset:256 nt
	v_pk_mul_f32 v[8:9], v[8:9], v[148:149] op_sel_hi:[1,0]
	v_pk_mul_f32 v[6:7], v[6:7], v[148:149] op_sel_hi:[1,0]
	v_cvt_pk_bf16_f32 v20, v112, v113
	v_cvt_pk_bf16_f32 v21, v108, v109
	v_cvt_pk_bf16_f32 v22, v110, v111
	v_cvt_pk_bf16_f32 v23, v106, v107
	v_add_co_u32_e32 v106, vcc, s4, v18
	s_mov_b64 s[4:5], 0x8000
	s_nop 0
	v_addc_co_u32_e32 v107, vcc, 0, v19, vcc
	global_store_dwordx4 v[106:107], v[20:23], off nt
	v_pk_mul_f32 v[4:5], v[4:5], v[148:149] op_sel_hi:[1,0]
	v_pk_mul_f32 v[2:3], v[2:3], v[148:149] op_sel_hi:[1,0]
	v_cvt_pk_bf16_f32 v20, v102, v103
	v_cvt_pk_bf16_f32 v21, v104, v105
	v_cvt_pk_bf16_f32 v22, v98, v99
	v_cvt_pk_bf16_f32 v23, v100, v101
	global_store_dwordx4 v[24:25], v[20:23], off offset:256 nt
	v_lshl_add_u64 v[24:25], v[18:19], 0, s[4:5]
	s_mov_b32 s4, 0x8000
	v_add_co_u32_e32 v98, vcc, s4, v18
	v_cvt_pk_bf16_f32 v20, v120, v121
	v_cvt_pk_bf16_f32 v21, v116, v117
	v_cvt_pk_bf16_f32 v22, v118, v119
	v_cvt_pk_bf16_f32 v23, v114, v115
	s_nop 1
	v_addc_co_u32_e32 v99, vcc, 0, v19, vcc
	s_mov_b64 s[4:5], 0xc000
	global_store_dwordx4 v[98:99], v[20:23], off nt
	s_nop 1
	v_cvt_pk_bf16_f32 v20, v96, v97
	v_cvt_pk_bf16_f32 v21, v92, v93
	v_cvt_pk_bf16_f32 v22, v94, v95
	v_cvt_pk_bf16_f32 v23, v90, v91
	global_store_dwordx4 v[24:25], v[20:23], off offset:256 nt
	v_lshl_add_u64 v[24:25], v[18:19], 0, s[4:5]
	s_mov_b32 s4, 0xc000
	v_cvt_pk_bf16_f32 v20, v80, v81
	v_cvt_pk_bf16_f32 v21, v76, v77
	v_cvt_pk_bf16_f32 v22, v78, v79
	v_cvt_pk_bf16_f32 v23, v74, v75
	v_add_co_u32_e32 v74, vcc, s4, v18
	s_mov_b64 s[4:5], 0x24000
	s_nop 0
	v_addc_co_u32_e32 v75, vcc, 0, v19, vcc
	global_store_dwordx4 v[74:75], v[20:23], off nt
	s_nop 1
	v_cvt_pk_bf16_f32 v20, v70, v71
	v_cvt_pk_bf16_f32 v21, v72, v73
	v_cvt_pk_bf16_f32 v22, v66, v67
	v_cvt_pk_bf16_f32 v23, v68, v69
	v_add_co_u32_e32 v66, vcc, s88, v18
	global_store_dwordx4 v[24:25], v[20:23], off offset:256 nt
	v_lshl_add_u64 v[24:25], v[18:19], 0, s[94:95]
	v_addc_co_u32_e32 v67, vcc, 0, v19, vcc
	v_cvt_pk_bf16_f32 v20, v88, v89
	v_cvt_pk_bf16_f32 v21, v84, v85
	v_cvt_pk_bf16_f32 v22, v86, v87
	v_cvt_pk_bf16_f32 v23, v82, v83
	global_store_dwordx4 v[66:67], v[20:23], off nt
	s_nop 1
	v_cvt_pk_bf16_f32 v20, v64, v65
	v_cvt_pk_bf16_f32 v21, v60, v61
	v_cvt_pk_bf16_f32 v22, v62, v63
	v_cvt_pk_bf16_f32 v23, v58, v59
	global_store_dwordx4 v[24:25], v[20:23], off offset:256 nt
	v_lshl_add_u64 v[24:25], v[18:19], 0, s[4:5]
	s_mov_b32 s4, 0x24000
	v_cvt_pk_bf16_f32 v20, v48, v49
	v_cvt_pk_bf16_f32 v21, v44, v45
	v_cvt_pk_bf16_f32 v22, v46, v47
	v_cvt_pk_bf16_f32 v23, v42, v43
	v_add_co_u32_e32 v42, vcc, s4, v18
	s_mov_b64 s[4:5], 0x28000
	s_nop 0
	v_addc_co_u32_e32 v43, vcc, 0, v19, vcc
	global_store_dwordx4 v[42:43], v[20:23], off nt
	s_nop 1
	v_cvt_pk_bf16_f32 v20, v38, v39
	v_cvt_pk_bf16_f32 v21, v40, v41
	v_cvt_pk_bf16_f32 v22, v34, v35
	v_cvt_pk_bf16_f32 v23, v36, v37
	global_store_dwordx4 v[24:25], v[20:23], off offset:256 nt
	v_lshl_add_u64 v[24:25], v[18:19], 0, s[4:5]
	s_mov_b32 s4, 0x28000
	v_add_co_u32_e32 v34, vcc, s4, v18
	v_cvt_pk_bf16_f32 v20, v56, v57
	v_cvt_pk_bf16_f32 v21, v52, v53
	v_cvt_pk_bf16_f32 v22, v54, v55
	v_cvt_pk_bf16_f32 v23, v50, v51
	s_nop 1
	v_addc_co_u32_e32 v35, vcc, 0, v19, vcc
	global_store_dwordx4 v[34:35], v[20:23], off nt
	s_mov_b64 s[4:5], 0x2c000
	s_nop 0
	v_cvt_pk_bf16_f32 v20, v32, v33
	v_cvt_pk_bf16_f32 v21, v28, v29
	v_cvt_pk_bf16_f32 v22, v30, v31
	v_cvt_pk_bf16_f32 v23, v26, v27
	global_store_dwordx4 v[24:25], v[20:23], off offset:256 nt
	s_nop 1
	v_cvt_pk_bf16_f32 v20, v16, v17
	v_cvt_pk_bf16_f32 v21, v12, v13
	v_cvt_pk_bf16_f32 v22, v14, v15
	v_cvt_pk_bf16_f32 v23, v10, v11
	v_lshl_add_u64 v[10:11], v[18:19], 0, s[4:5]
	s_mov_b32 s4, 0x2c000
	v_add_co_u32_e32 v12, vcc, s4, v18
	s_nop 1
	v_addc_co_u32_e32 v13, vcc, 0, v19, vcc
	s_andn2_b64 vcc, exec, s[6:7]
	global_store_dwordx4 v[12:13], v[20:23], off nt
	v_cvt_pk_bf16_f32 v6, v6, v7
	v_cvt_pk_bf16_f32 v7, v8, v9
	v_cvt_pk_bf16_f32 v8, v2, v3
	v_cvt_pk_bf16_f32 v9, v4, v5
	global_store_dwordx4 v[10:11], v[6:9], off offset:256 nt
	s_cbranch_vccnz .LBB0_894
	s_andn2_b64 vcc, exec, s[0:1]
	s_cbranch_vccnz .LBB0_893
	s_barrier
	s_branch .LBB0_893

; #define PG8_LAS __attribute__((address_space(3)))
;     __device__ __forceinline__ void operator()(f32x4 (&acc)[2][2][4][2], const Unit& u, int ui, int wr, int wc, int fr_, int fq_) const {
;     ...
;                     if (kb > 0) { c62 = *(const PG8_LAS f32x4*)(exch + (((kb - 1) * 2 + 0) * 256 + bj * HALF + 32 * wc + 8 * fq + 4 * n)); c63 = *(const PG8_LAS f32x4*)(exch + (((kb - 1) * 2 + 1) * 256 + bj * HALF + 32 * wc + 8 * fq + 4 * n)); }
; #pragma unroll
;                     for (int m = 3; m >= 0; --m) { f32x4 cur = acc[ai][bj][m][n], res;
; #pragma unroll
;                         for (int j = 0; j < 4; ++j) { const float c = cur[j]; const float pv = (m > 0) ? acc[ai][bj][m > 0 ? m - 1 : 0][n][j] : (fr == 15 ? c63[j] : c62[j]); float t1, t2;
;                             asm volatile("s_nop 1\n\tv_mov_b32_dpp %0, %3 row_ror:1 row_mask:0xf bank_mask:0xf\n\tv_mov_b32_dpp %1, %3 row_ror:2 row_mask:0xf bank_mask:0xf\n\t"
;                                          "v_mov_b32_dpp %0, %2 row_shr:1 row_mask:0xf bank_mask:0xf\n\tv_mov_b32_dpp %1, %2 row_shr:2 row_mask:0xf bank_mask:0xf"
;                                          : "=&v"(t1), "=&v"(t2) : "v"(c), "v"(pv));
;                             res[j] = bb[j] + w0[j] * t2 + w1[j] * t1 + w2[j] * c; }
;                         asm volatile("" : "+v"(res[0]), "+v"(res[1]), "+v"(res[2]), "+v"(res[3]));
;                         acc[ai][bj][m][n] = res; } }
.LBB0_1200:
	v_pk_mul_f32 v[76:77], v[6:7], v[190:191]
	v_pk_mul_f32 v[72:73], v[10:11], v[192:193]
	v_pk_mul_f32 v[4:5], v[4:5], v[188:189] op_sel_hi:[1,0]
	v_pk_mul_f32 v[2:3], v[2:3], v[188:189]
	v_pk_mul_f32 v[74:75], v[8:9], v[190:191] op_sel_hi:[1,0]
	v_mov_b32_e32 v7, v248
	v_fmac_f32_dpp v7, v50, v234 row_shr:2 row_mask:0xf bank_mask:0xf
	v_fmac_f32_dpp v7, v2, v234 row_shl:14 row_mask:0xf bank_mask:0xf
	v_fmac_f32_dpp v7, v50, v240 row_shr:1 row_mask:0xf bank_mask:0xf
	v_fmac_f32_dpp v7, v2, v240 row_shl:15 row_mask:0xf bank_mask:0xf
	v_fmac_f32_e32 v7, v50, v244
	v_mov_b32_e32 v6, v249
	v_fmac_f32_dpp v6, v51, v235 row_shr:2 row_mask:0xf bank_mask:0xf
	v_fmac_f32_dpp v6, v3, v235 row_shl:14 row_mask:0xf bank_mask:0xf
	v_fmac_f32_dpp v6, v51, v241 row_shr:1 row_mask:0xf bank_mask:0xf
	v_fmac_f32_dpp v6, v3, v241 row_shl:15 row_mask:0xf bank_mask:0xf
	v_fmac_f32_e32 v6, v51, v245
	v_mov_b32_e32 v46, v192
	v_mov_b32_e32 v47, v192
	v_pk_mul_f32 v[64:65], v[12:13], v[46:47]
	v_mov_b32_e32 v8, v250
	v_fmac_f32_dpp v8, v52, v236 row_shr:2 row_mask:0xf bank_mask:0xf
	v_fmac_f32_dpp v8, v4, v236 row_shl:14 row_mask:0xf bank_mask:0xf
	v_fmac_f32_dpp v8, v52, v242 row_shr:1 row_mask:0xf bank_mask:0xf
	v_fmac_f32_dpp v8, v4, v242 row_shl:15 row_mask:0xf bank_mask:0xf
	v_fmac_f32_e32 v8, v52, v246
	v_mov_b32_e32 v9, v251
	v_fmac_f32_dpp v9, v53, v237 row_shr:2 row_mask:0xf bank_mask:0xf
	v_fmac_f32_dpp v9, v5, v237 row_shl:14 row_mask:0xf bank_mask:0xf
	v_fmac_f32_dpp v9, v53, v243 row_shr:1 row_mask:0xf bank_mask:0xf
	v_fmac_f32_dpp v9, v5, v243 row_shl:15 row_mask:0xf bank_mask:0xf
	v_fmac_f32_e32 v9, v53, v247
	v_mov_b32_e32 v11, v248
	v_fmac_f32_dpp v11, v2, v234 row_shr:2 row_mask:0xf bank_mask:0xf
	v_fmac_f32_dpp v11, v76, v234 row_shl:14 row_mask:0xf bank_mask:0xf
	v_fmac_f32_dpp v11, v2, v240 row_shr:1 row_mask:0xf bank_mask:0xf
	v_fmac_f32_dpp v11, v76, v240 row_shl:15 row_mask:0xf bank_mask:0xf
	v_fmac_f32_e32 v11, v2, v244
	s_waitcnt lgkmcnt(0)
	v_cndmask_b32_e64 v17, v45, v17, s[8:9]
	v_mov_b32_e32 v2, v3
	v_mov_b32_e32 v10, v249
	s_nop 0
	v_fmac_f32_dpp v10, v2, v235 row_shr:2 row_mask:0xf bank_mask:0xf
	v_fmac_f32_dpp v10, v77, v235 row_shl:14 row_mask:0xf bank_mask:0xf
	v_fmac_f32_dpp v10, v2, v241 row_shr:1 row_mask:0xf bank_mask:0xf
	v_fmac_f32_dpp v10, v77, v241 row_shl:15 row_mask:0xf bank_mask:0xf
	v_fmac_f32_e32 v10, v2, v245
	v_mov_b32_e32 v12, v250
	v_fmac_f32_dpp v12, v4, v236 row_shr:2 row_mask:0xf bank_mask:0xf
	v_fmac_f32_dpp v12, v74, v236 row_shl:14 row_mask:0xf bank_mask:0xf
	v_fmac_f32_dpp v12, v4, v242 row_shr:1 row_mask:0xf bank_mask:0xf
	v_fmac_f32_dpp v12, v74, v242 row_shl:15 row_mask:0xf bank_mask:0xf
	v_fmac_f32_e32 v12, v4, v246
	v_mov_b32_e32 v4, v5
	v_mov_b32_e32 v13, v251
	s_nop 0
	v_fmac_f32_dpp v13, v4, v237 row_shr:2 row_mask:0xf bank_mask:0xf
	v_fmac_f32_dpp v13, v75, v237 row_shl:14 row_mask:0xf bank_mask:0xf
	v_fmac_f32_dpp v13, v4, v243 row_shr:1 row_mask:0xf bank_mask:0xf
	v_fmac_f32_dpp v13, v75, v243 row_shl:15 row_mask:0xf bank_mask:0xf
	v_fmac_f32_e32 v13, v4, v247
	v_mov_b32_e32 v47, v248
	v_fmac_f32_dpp v47, v76, v234 row_shr:2 row_mask:0xf bank_mask:0xf
	v_fmac_f32_dpp v47, v72, v234 row_shl:14 row_mask:0xf bank_mask:0xf
	v_fmac_f32_dpp v47, v76, v240 row_shr:1 row_mask:0xf bank_mask:0xf
	v_fmac_f32_dpp v47, v72, v240 row_shl:15 row_mask:0xf bank_mask:0xf
	v_fmac_f32_e32 v47, v76, v244
	v_mov_b32_e32 v46, v249
	v_fmac_f32_dpp v46, v77, v235 row_shr:2 row_mask:0xf bank_mask:0xf
	v_fmac_f32_dpp v46, v73, v235 row_shl:14 row_mask:0xf bank_mask:0xf
	v_fmac_f32_dpp v46, v77, v241 row_shr:1 row_mask:0xf bank_mask:0xf
	v_fmac_f32_dpp v46, v73, v241 row_shl:15 row_mask:0xf bank_mask:0xf
	v_fmac_f32_e32 v46, v77, v245
	v_mov_b32_e32 v50, v250
	v_fmac_f32_dpp v50, v74, v236 row_shr:2 row_mask:0xf bank_mask:0xf
	v_fmac_f32_dpp v50, v64, v236 row_shl:14 row_mask:0xf bank_mask:0xf
	v_fmac_f32_dpp v50, v74, v242 row_shr:1 row_mask:0xf bank_mask:0xf
	v_fmac_f32_dpp v50, v64, v242 row_shl:15 row_mask:0xf bank_mask:0xf
	v_fmac_f32_e32 v50, v74, v246
	v_mov_b32_e32 v51, v251
	v_fmac_f32_dpp v51, v75, v237 row_shr:2 row_mask:0xf bank_mask:0xf
	v_fmac_f32_dpp v51, v65, v237 row_shl:14 row_mask:0xf bank_mask:0xf
	v_fmac_f32_dpp v51, v75, v243 row_shr:1 row_mask:0xf bank_mask:0xf
	v_fmac_f32_dpp v51, v65, v243 row_shl:15 row_mask:0xf bank_mask:0xf
	v_fmac_f32_e32 v51, v75, v247
	v_cndmask_b32_e64 v4, v43, v15, s[8:9]
	v_cndmask_b32_e64 v3, v42, v14, s[8:9]
	v_cndmask_b32_e64 v2, v44, v16, s[8:9]
	v_mov_b32_e32 v252, v248
	v_fmac_f32_dpp v252, v72, v234 row_shr:2 row_mask:0xf bank_mask:0xf
	v_fmac_f32_dpp v252, v3, v234 row_shl:14 row_mask:0xf bank_mask:0xf
	v_fmac_f32_dpp v252, v72, v240 row_shr:1 row_mask:0xf bank_mask:0xf
	v_fmac_f32_dpp v252, v3, v240 row_shl:15 row_mask:0xf bank_mask:0xf
	v_fmac_f32_e32 v252, v72, v244
	v_mov_b32_e32 v231, v249
	v_fmac_f32_dpp v231, v73, v235 row_shr:2 row_mask:0xf bank_mask:0xf
	v_fmac_f32_dpp v231, v4, v235 row_shl:14 row_mask:0xf bank_mask:0xf
	v_fmac_f32_dpp v231, v73, v241 row_shr:1 row_mask:0xf bank_mask:0xf
	v_fmac_f32_dpp v231, v4, v241 row_shl:15 row_mask:0xf bank_mask:0xf
	v_fmac_f32_e32 v231, v73, v245
	v_mov_b32_e32 v15, v250
	v_fmac_f32_dpp v15, v64, v236 row_shr:2 row_mask:0xf bank_mask:0xf
	v_fmac_f32_dpp v15, v2, v236 row_shl:14 row_mask:0xf bank_mask:0xf
	v_fmac_f32_dpp v15, v64, v242 row_shr:1 row_mask:0xf bank_mask:0xf
	v_fmac_f32_dpp v15, v2, v242 row_shl:15 row_mask:0xf bank_mask:0xf
	v_fmac_f32_e32 v15, v64, v246
	v_mov_b32_e32 v27, v231
	v_mov_b32_e32 v26, v252
	v_mov_b32_e32 v28, v251
	v_fmac_f32_dpp v28, v65, v237 row_shr:2 row_mask:0xf bank_mask:0xf
; __device__ __forceinline__ unsigned cvt_pk_bf16(float lo, float hi) { unsigned r; asm volatile("v_cvt_pk_bf16_f32 %0, %1, %2" : "=v"(r) : "v"(lo), "v"(hi)); return r; }
;     __device__ __forceinline__ void operator()(f32x4 (&acc)[2][2][4][2], const Unit& u, int ui, int wr, int wc, int fr_, int fq_) const {
;     ...
;         const int row0 = u.pm * BM + wr * 64 + fr;
; #pragma unroll
;         for (int ai = 0; ai < 2; ++ai)
; #pragma unroll
;             for (int m = 0; m < 4; ++m) { float gv[8];
; #pragma unroll
;                 for (int n = 0; n < 2; ++n)
; #pragma unroll
;                     for (int j = 0; j < 4; ++j) { const float g = acc[ai][0][m][n][j], up = acc[ai][1][m][n][j]; gv[n * 4 + j] = g * __builtin_amdgcn_rcpf(1.0f + __builtin_amdgcn_exp2f(g * -1.4426950408889634f)) * up; }
;                 u32x4 w; w.x = cvt_pk_bf16(gv[0], gv[1]); w.y = cvt_pk_bf16(gv[2], gv[3]); w.z = cvt_pk_bf16(gv[4], gv[5]); w.w = cvt_pk_bf16(gv[6], gv[7]);
;                 *(u32x4*)(G + (size_t)(row0 + ai * HALF + m * 16) * 2816 + fbase) = w; asm volatile("" ::: "memory"); }
	v_fmac_f32_dpp v28, v17, v237 row_shl:14 row_mask:0xf bank_mask:0xf
	v_fmac_f32_dpp v28, v65, v243 row_shr:1 row_mask:0xf bank_mask:0xf
	v_fmac_f32_dpp v28, v17, v243 row_shl:15 row_mask:0xf bank_mask:0xf
	v_fmac_f32_e32 v28, v65, v247
	v_mul_f32_e32 v22, s98, v123
	v_mul_f32_e32 v2, s98, v223
	v_mul_f32_e32 v3, s98, v224
	v_exp_f32_e32 v2, v2
	v_exp_f32_e32 v3, v3
	v_mul_f32_e32 v4, s98, v221
	v_mul_f32_e32 v5, s98, v222
	v_mul_f32_e32 v16, s98, v126
	v_mul_f32_e32 v17, s98, v122
	v_exp_f32_e32 v22, v22
	v_mul_f32_e32 v23, s98, v124
	v_exp_f32_e32 v4, v4
	v_exp_f32_e32 v5, v5
	v_exp_f32_e32 v16, v16
	v_exp_f32_e32 v17, v17
	v_exp_f32_e32 v23, v23
	v_add_f32_e32 v2, 1.0, v2
	v_add_f32_e32 v3, 1.0, v3
	v_add_f32_e32 v22, 1.0, v22
	v_rcp_f32_e32 v2, v2
	v_rcp_f32_e32 v3, v3
	v_add_f32_e32 v4, 1.0, v4
	v_add_f32_e32 v5, 1.0, v5
	v_add_f32_e32 v16, 1.0, v16
	v_add_f32_e32 v17, 1.0, v17
	v_rcp_f32_e32 v22, v22
	v_add_f32_e32 v23, 1.0, v23
	v_rcp_f32_e32 v4, v4
	v_rcp_f32_e32 v5, v5
	v_rcp_f32_e32 v16, v16
	v_rcp_f32_e32 v17, v17
	v_rcp_f32_e32 v23, v23
	s_lshl_b32 s0, s76, 8
	v_mul_f32_e32 v2, v223, v2
	v_mul_f32_e32 v3, v224, v3
	v_mul_f32_e32 v22, v123, v22
	s_add_i32 s0, s0, s68
	v_mul_f32_e32 v2, v2, v97
	v_mul_f32_e32 v3, v3, v96
	v_mul_f32_e32 v4, v221, v4
	v_mul_f32_e32 v5, v222, v5
	v_mul_f32_e32 v16, v126, v16
	v_mul_f32_e32 v17, v122, v17
	v_mul_f32_e32 v25, v22, v59
	v_mul_f32_e32 v22, v124, v23
	v_add_u32_e32 v14, s0, v210
	v_mul_f32_e32 v4, v4, v95
	v_mul_f32_e32 v5, v5, v94
	v_mul_f32_e32 v16, v16, v62
	v_mul_f32_e32 v17, v17, v58
	v_mul_f32_e32 v29, v22, v60
	v_cvt_pk_bf16_f32 v22, v2, v3
	v_mov_b64_e32 v[2:3], s[38:39]
	v_cvt_pk_bf16_f32 v23, v4, v5
	v_cvt_pk_bf16_f32 v24, v16, v17
	v_mad_i64_i32 v[16:17], s[0:1], v14, s83, v[2:3]
	v_lshlrev_b64 v[4:5], 1, v[186:187]
	v_lshl_add_u64 v[16:17], v[16:17], 0, v[4:5]
	v_cvt_pk_bf16_f32 v25, v25, v29
	global_store_dwordx4 v[16:17], v[22:25], off nt
	v_mul_f32_e32 v29, s98, v218
	v_exp_f32_e32 v29, v29
	v_mul_f32_e32 v22, s98, v217
	v_exp_f32_e32 v22, v22
	v_mul_f32_e32 v23, s98, v219
	v_exp_f32_e32 v23, v23
	v_mul_f32_e32 v24, s98, v225
	v_add_f32_e32 v22, 1.0, v22
	v_rcp_f32_e32 v22, v22
	v_add_f32_e32 v23, 1.0, v23
	v_rcp_f32_e32 v23, v23
	v_exp_f32_e32 v24, v24
	v_mul_f32_e32 v22, v217, v22
	v_mul_f32_e32 v25, v22, v108
	v_mul_f32_e32 v22, v219, v23
	v_add_f32_e32 v23, 1.0, v24
	v_mul_f32_e32 v34, s98, v220
	v_rcp_f32_e32 v23, v23
	v_mul_f32_e32 v24, s98, v144
	v_exp_f32_e32 v34, v34
	v_exp_f32_e32 v24, v24
	v_add_f32_e32 v16, 1.0, v29
	v_mul_f32_e32 v29, v22, v109
	v_mul_f32_e32 v22, v225, v23
	v_mul_f32_e32 v23, s98, v145
	v_add_f32_e32 v17, 1.0, v34
	v_mul_f32_e32 v34, v22, v69
	v_add_f32_e32 v22, 1.0, v24
	v_exp_f32_e32 v23, v23
	v_mul_f32_e32 v24, s98, v226
	v_exp_f32_e32 v24, v24
	v_rcp_f32_e32 v22, v22
	v_add_f32_e32 v23, 1.0, v23
	v_rcp_f32_e32 v16, v16
	v_rcp_f32_e32 v23, v23
	v_add_f32_e32 v24, 1.0, v24
	v_rcp_f32_e32 v17, v17
	v_rcp_f32_e32 v24, v24
	v_mul_f32_e32 v22, v144, v22
	v_mul_f32_e32 v16, v218, v16
	v_mul_f32_e32 v35, v22, v67
	v_mul_f32_e32 v22, v145, v23
	v_mul_f32_e32 v16, v16, v127
	v_mul_f32_e32 v17, v220, v17
	v_mul_f32_e32 v36, v22, v68
	v_mul_f32_e32 v22, v226, v24
	v_mul_f32_e32 v17, v17, v125
	v_mul_f32_e32 v37, v22, v70
	v_cvt_pk_bf16_f32 v22, v16, v17
	v_add_u32_e32 v16, 16, v14
	v_mad_i64_i32 v[16:17], s[0:1], v16, s83, v[2:3]
	v_lshl_add_u64 v[16:17], v[16:17], 0, v[4:5]
	v_cvt_pk_bf16_f32 v23, v25, v29
	v_cvt_pk_bf16_f32 v24, v34, v35
	v_cvt_pk_bf16_f32 v25, v36, v37
	global_store_dwordx4 v[16:17], v[22:25], off nt
	v_mul_f32_e32 v29, s98, v213
	v_exp_f32_e32 v29, v29
	v_mul_f32_e32 v22, s98, v154
	v_exp_f32_e32 v22, v22
	v_mul_f32_e32 v23, s98, v214
	v_exp_f32_e32 v23, v23
	v_mul_f32_e32 v24, s98, v142
	v_add_f32_e32 v22, 1.0, v22
	v_rcp_f32_e32 v22, v22
	v_add_f32_e32 v23, 1.0, v23
	v_rcp_f32_e32 v23, v23
	v_exp_f32_e32 v24, v24
	v_mul_f32_e32 v22, v154, v22
	v_mul_f32_e32 v25, v22, v100
	v_mul_f32_e32 v22, v214, v23
	v_add_f32_e32 v23, 1.0, v24
	v_mul_f32_e32 v34, s98, v216
	v_rcp_f32_e32 v23, v23
	v_mul_f32_e32 v24, s98, v136
	v_exp_f32_e32 v34, v34
	v_exp_f32_e32 v24, v24
	v_add_f32_e32 v16, 1.0, v29
	v_mul_f32_e32 v29, v22, v101
	v_mul_f32_e32 v22, v142, v23
	v_mul_f32_e32 v23, s98, v137
	v_add_f32_e32 v17, 1.0, v34
	v_mul_f32_e32 v34, v22, v56
	v_add_f32_e32 v22, 1.0, v24
	v_exp_f32_e32 v23, v23
	v_mul_f32_e32 v24, s98, v143
	v_exp_f32_e32 v24, v24
	v_rcp_f32_e32 v22, v22
	v_add_f32_e32 v23, 1.0, v23
	v_rcp_f32_e32 v16, v16
	v_rcp_f32_e32 v23, v23
	v_add_f32_e32 v24, 1.0, v24
	v_rcp_f32_e32 v17, v17
	v_rcp_f32_e32 v24, v24
	v_mul_f32_e32 v22, v136, v22
	v_mul_f32_e32 v16, v213, v16
	v_mul_f32_e32 v30, v22, v30
	v_mul_f32_e32 v22, v137, v23
	v_mul_f32_e32 v16, v16, v107
	v_mul_f32_e32 v17, v216, v17
	v_mul_f32_e32 v31, v22, v31
	v_mul_f32_e32 v22, v143, v24
	v_mul_f32_e32 v17, v17, v105
	v_mul_f32_e32 v35, v22, v66
	v_cvt_pk_bf16_f32 v22, v16, v17
	v_add_u32_e32 v16, 32, v14
	v_mad_i64_i32 v[16:17], s[0:1], v16, s83, v[2:3]
	v_cvt_pk_bf16_f32 v23, v25, v29
	v_cvt_pk_bf16_f32 v24, v34, v30
	v_lshl_add_u64 v[16:17], v[16:17], 0, v[4:5]
	v_cvt_pk_bf16_f32 v25, v31, v35
	global_store_dwordx4 v[16:17], v[22:25], off nt
	v_mul_f32_e32 v29, s98, v211
	v_exp_f32_e32 v29, v29
	v_mul_f32_e32 v24, s98, v133
	v_exp_f32_e32 v24, v24
	v_mul_f32_e32 v25, s98, v131
	v_exp_f32_e32 v25, v25
	v_mul_f32_e32 v30, s98, v212
	v_add_f32_e32 v24, 1.0, v24
	v_rcp_f32_e32 v24, v24
	v_exp_f32_e32 v30, v30
	v_add_f32_e32 v16, 1.0, v29
	v_mul_f32_e32 v22, s98, v152
	v_mul_f32_e32 v24, v133, v24
	v_mul_f32_e32 v20, v24, v20
	v_add_f32_e32 v24, 1.0, v25
; __device__ __forceinline__ unsigned cvt_pk_bf16(float lo, float hi) { unsigned r; asm volatile("v_cvt_pk_bf16_f32 %0, %1, %2" : "=v"(r) : "v"(lo), "v"(hi)); return r; }
;     __device__ __forceinline__ void operator()(f32x4 (&acc)[2][2][4][2], const Unit& u, int ui, int wr, int wc, int fr_, int fq_) const {
;     ...
;         const int row0 = u.pm * BM + wr * 64 + fr;
; #pragma unroll
;         for (int ai = 0; ai < 2; ++ai)
; #pragma unroll
;             for (int m = 0; m < 4; ++m) { float gv[8];
; #pragma unroll
;                 for (int n = 0; n < 2; ++n)
; #pragma unroll
;                     for (int j = 0; j < 4; ++j) { const float g = acc[ai][0][m][n][j], up = acc[ai][1][m][n][j]; gv[n * 4 + j] = g * __builtin_amdgcn_rcpf(1.0f + __builtin_amdgcn_exp2f(g * -1.4426950408889634f)) * up; }
;                 u32x4 w; w.x = cvt_pk_bf16(gv[0], gv[1]); w.y = cvt_pk_bf16(gv[2], gv[3]); w.z = cvt_pk_bf16(gv[4], gv[5]); w.w = cvt_pk_bf16(gv[6], gv[7]);
;                 *(u32x4*)(G + (size_t)(row0 + ai * HALF + m * 16) * 2816 + fbase) = w; asm volatile("" ::: "memory"); }
	v_mul_f32_e32 v25, s98, v132
	v_mul_f32_e32 v23, s98, v153
	v_exp_f32_e32 v25, v25
	v_mul_f32_e32 v29, s98, v135
	v_exp_f32_e32 v22, v22
	v_exp_f32_e32 v23, v23
	v_exp_f32_e32 v29, v29
	v_add_f32_e32 v17, 1.0, v30
	v_rcp_f32_e32 v24, v24
	v_add_f32_e32 v25, 1.0, v25
	v_rcp_f32_e32 v16, v16
	v_rcp_f32_e32 v17, v17
	v_add_f32_e32 v22, 1.0, v22
	v_add_f32_e32 v23, 1.0, v23
	v_rcp_f32_e32 v25, v25
	v_add_f32_e32 v29, 1.0, v29
	v_rcp_f32_e32 v22, v22
	v_rcp_f32_e32 v23, v23
	v_rcp_f32_e32 v29, v29
	v_mul_f32_e32 v24, v131, v24
	v_mul_f32_e32 v16, v211, v16
	v_mul_f32_e32 v17, v212, v17
	v_mul_f32_e32 v18, v24, v18
	v_mul_f32_e32 v24, v132, v25
	v_mul_f32_e32 v16, v16, v104
	v_mul_f32_e32 v17, v17, v103
	v_mul_f32_e32 v22, v152, v22
	v_mul_f32_e32 v23, v153, v23
	v_mul_f32_e32 v19, v24, v19
	v_mul_f32_e32 v24, v135, v29
	v_mul_f32_e32 v22, v22, v98
	v_mul_f32_e32 v23, v23, v99
	v_mul_f32_e32 v21, v24, v21
	v_cvt_pk_bf16_f32 v16, v16, v17
	v_cvt_pk_bf16_f32 v17, v22, v23
	v_cvt_pk_bf16_f32 v18, v20, v18
	v_add_u32_e32 v20, 48, v14
	v_cvt_pk_bf16_f32 v19, v19, v21
	v_mad_i64_i32 v[20:21], s[0:1], v20, s83, v[2:3]
	v_lshl_add_u64 v[20:21], v[20:21], 0, v[4:5]
	global_store_dwordx4 v[20:21], v[16:19], off nt
	v_mul_f32_e32 v22, s98, v102
	v_mul_f32_e32 v21, s98, v106
	v_mul_f32_e32 v16, s98, v134
	v_mul_f32_e32 v17, s98, v130
	v_mul_f32_e32 v18, s98, v32
	v_exp_f32_e32 v16, v16
	v_exp_f32_e32 v17, v17
	v_exp_f32_e32 v18, v18
	v_mul_f32_e32 v19, s98, v33
	v_exp_f32_e32 v22, v22
	v_exp_f32_e32 v19, v19
	v_exp_f32_e32 v21, v21
	v_mul_f32_e32 v23, s98, v48
	v_exp_f32_e32 v23, v23
	v_mul_f32_e32 v24, s98, v49
	v_add_f32_e32 v16, 1.0, v16
	v_add_f32_e32 v17, 1.0, v17
	v_add_f32_e32 v18, 1.0, v18
	v_add_f32_e32 v22, 1.0, v22
	v_exp_f32_e32 v24, v24
	v_rcp_f32_e32 v16, v16
	v_rcp_f32_e32 v17, v17
	v_rcp_f32_e32 v18, v18
	v_add_f32_e32 v19, 1.0, v19
	v_add_f32_e32 v21, 1.0, v21
	v_rcp_f32_e32 v22, v22
	v_rcp_f32_e32 v19, v19
	v_rcp_f32_e32 v21, v21
	v_add_f32_e32 v23, 1.0, v23
	v_rcp_f32_e32 v23, v23
	v_add_f32_e32 v24, 1.0, v24
	v_mul_f32_e32 v16, v134, v16
	v_mul_f32_e32 v17, v130, v17
	v_mul_f32_e32 v18, v32, v18
	v_mul_f32_e32 v22, v102, v22
	v_rcp_f32_e32 v24, v24
	v_mul_f32_e32 v16, v16, v78
	v_mul_f32_e32 v17, v17, v55
	v_mul_f32_e32 v18, v18, v54
	v_mul_f32_e32 v19, v33, v19
	v_mul_f32_e32 v21, v106, v21
	v_mul_f32_e32 v22, v22, v27
	v_mul_f32_e32 v19, v19, v57
	v_mul_f32_e32 v21, v21, v26
	v_cvt_pk_bf16_f32 v16, v16, v17
	v_cvt_pk_bf16_f32 v17, v18, v19
	v_cvt_pk_bf16_f32 v18, v21, v22
	v_mul_f32_e32 v22, s98, v215
	v_add_u32_e32 v20, 0x80, v14
	v_mul_f32_e32 v23, v48, v23
	v_exp_f32_e32 v22, v22
	v_mul_f32_e32 v15, v23, v15
	v_mul_f32_e32 v23, v49, v24
	v_mad_i64_i32 v[20:21], s[0:1], v20, s83, v[2:3]
	v_mul_f32_e32 v23, v23, v28
	v_cvt_pk_bf16_f32 v19, v15, v23
	v_lshl_add_u64 v[20:21], v[20:21], 0, v[4:5]
	v_mul_f32_e32 v15, s98, v151
	v_exp_f32_e32 v15, v15
	global_store_dwordx4 v[20:21], v[16:19], off nt
	v_mul_f32_e32 v20, s98, v118
	v_mul_f32_e32 v21, s98, v119
	v_mul_f32_e32 v17, s98, v150
	v_mul_f32_e32 v18, s98, v155
	v_mul_f32_e32 v19, s98, v120
	v_add_f32_e32 v16, 1.0, v22
	v_exp_f32_e32 v17, v17
	v_exp_f32_e32 v18, v18
	v_exp_f32_e32 v19, v19
	v_exp_f32_e32 v20, v20
	v_exp_f32_e32 v21, v21
	v_mul_f32_e32 v22, s98, v121
	v_exp_f32_e32 v22, v22
	v_add_f32_e32 v15, 1.0, v15
	v_rcp_f32_e32 v15, v15
	v_rcp_f32_e32 v16, v16
	v_add_f32_e32 v17, 1.0, v17
	v_add_f32_e32 v18, 1.0, v18
	v_add_f32_e32 v19, 1.0, v19
	v_add_f32_e32 v20, 1.0, v20
	v_add_f32_e32 v21, 1.0, v21
	v_rcp_f32_e32 v17, v17
	v_rcp_f32_e32 v18, v18
	v_rcp_f32_e32 v19, v19
	v_rcp_f32_e32 v20, v20
	v_rcp_f32_e32 v21, v21
	v_add_f32_e32 v22, 1.0, v22
	v_rcp_f32_e32 v22, v22
	v_mul_f32_e32 v15, v151, v15
	v_mul_f32_e32 v16, v215, v16
	v_mul_f32_e32 v15, v15, v93
	v_mul_f32_e32 v16, v16, v92
	v_mul_f32_e32 v17, v150, v17
	v_mul_f32_e32 v18, v155, v18
	v_mul_f32_e32 v19, v120, v19
	v_mul_f32_e32 v20, v118, v20
; __device__ __forceinline__ unsigned cvt_pk_bf16(float lo, float hi) { unsigned r; asm volatile("v_cvt_pk_bf16_f32 %0, %1, %2" : "=v"(r) : "v"(lo), "v"(hi)); return r; }
;     __device__ __forceinline__ void operator()(f32x4 (&acc)[2][2][4][2], const Unit& u, int ui, int wr, int wc, int fr_, int fq_) const {
;     ...
;         const int row0 = u.pm * BM + wr * 64 + fr;
; #pragma unroll
;         for (int ai = 0; ai < 2; ++ai)
; #pragma unroll
;             for (int m = 0; m < 4; ++m) { float gv[8];
; #pragma unroll
;                 for (int n = 0; n < 2; ++n)
; #pragma unroll
;                     for (int j = 0; j < 4; ++j) { const float g = acc[ai][0][m][n][j], up = acc[ai][1][m][n][j]; gv[n * 4 + j] = g * __builtin_amdgcn_rcpf(1.0f + __builtin_amdgcn_exp2f(g * -1.4426950408889634f)) * up; }
;                 u32x4 w; w.x = cvt_pk_bf16(gv[0], gv[1]); w.y = cvt_pk_bf16(gv[2], gv[3]); w.z = cvt_pk_bf16(gv[4], gv[5]); w.w = cvt_pk_bf16(gv[6], gv[7]);
;                 *(u32x4*)(G + (size_t)(row0 + ai * HALF + m * 16) * 2816 + fbase) = w; asm volatile("" ::: "memory"); }
	v_mul_f32_e32 v21, v119, v21
	v_mul_f32_e32 v17, v17, v90
	v_mul_f32_e32 v18, v18, v91
	v_mul_f32_e32 v19, v19, v47
	v_mul_f32_e32 v20, v20, v46
	v_mul_f32_e32 v21, v21, v50
	v_mul_f32_e32 v22, v121, v22
	v_cvt_pk_bf16_f32 v16, v15, v16
	v_add_u32_e32 v15, 0x90, v14
	v_mul_f32_e32 v22, v22, v51
	v_cvt_pk_bf16_f32 v17, v17, v18
	v_cvt_pk_bf16_f32 v18, v19, v20
	v_cvt_pk_bf16_f32 v19, v21, v22
	v_mad_i64_i32 v[20:21], s[0:1], v15, s83, v[2:3]
	v_lshl_add_u64 v[20:21], v[20:21], 0, v[4:5]
	global_store_dwordx4 v[20:21], v[16:19], off nt
	v_mul_f32_e32 v20, s98, v114
	v_exp_f32_e32 v20, v20
	v_mul_f32_e32 v19, s98, v116
	v_exp_f32_e32 v19, v19
	v_mul_f32_e32 v15, s98, v147
	v_exp_f32_e32 v15, v15
	v_mul_f32_e32 v22, s98, v149
	v_add_f32_e32 v19, 1.0, v19
	v_rcp_f32_e32 v19, v19
	v_mul_f32_e32 v17, s98, v146
	v_mul_f32_e32 v21, s98, v117
	v_exp_f32_e32 v22, v22
	v_mul_f32_e32 v19, v116, v19
	v_mul_f32_e32 v19, v19, v11
	v_add_f32_e32 v11, 1.0, v20
	v_mul_f32_e32 v20, s98, v115
	v_exp_f32_e32 v20, v20
	v_exp_f32_e32 v17, v17
	v_mul_f32_e32 v18, s98, v148
	v_exp_f32_e32 v21, v21
	v_exp_f32_e32 v18, v18
	v_add_f32_e32 v15, 1.0, v15
	v_rcp_f32_e32 v11, v11
	v_add_f32_e32 v20, 1.0, v20
	v_rcp_f32_e32 v15, v15
	v_add_f32_e32 v16, 1.0, v22
	v_add_f32_e32 v17, 1.0, v17
	v_rcp_f32_e32 v20, v20
	v_add_f32_e32 v21, 1.0, v21
	v_rcp_f32_e32 v16, v16
	v_rcp_f32_e32 v17, v17
	v_add_f32_e32 v18, 1.0, v18
	v_rcp_f32_e32 v21, v21
	v_rcp_f32_e32 v18, v18
	v_mul_f32_e32 v11, v114, v11
	v_mul_f32_e32 v15, v147, v15
	v_mul_f32_e32 v22, v11, v10
	v_mul_f32_e32 v10, v115, v20
	v_mul_f32_e32 v15, v15, v89
	v_mul_f32_e32 v16, v149, v16
	v_mul_f32_e32 v17, v146, v17
	v_mul_f32_e32 v20, v10, v12
	v_mul_f32_e32 v10, v117, v21
	v_mul_f32_e32 v16, v16, v88
	v_mul_f32_e32 v17, v17, v84
	v_mul_f32_e32 v18, v148, v18
	v_mul_f32_e32 v13, v10, v13
	v_cvt_pk_bf16_f32 v10, v15, v16
	v_add_u32_e32 v15, 0xa0, v14
	v_mul_f32_e32 v18, v18, v85
	v_cvt_pk_bf16_f32 v11, v17, v18
	v_mad_i64_i32 v[16:17], s[0:1], v15, s83, v[2:3]
	v_mul_f32_e32 v15, s98, v139
	v_exp_f32_e32 v15, v15
	v_lshl_add_u64 v[16:17], v[16:17], 0, v[4:5]
	v_cvt_pk_bf16_f32 v12, v19, v22
	v_cvt_pk_bf16_f32 v13, v20, v13
	global_store_dwordx4 v[16:17], v[10:13], off nt
	v_mul_f32_e32 v16, s98, v110
	v_exp_f32_e32 v16, v16
	v_add_f32_e32 v10, 1.0, v15
	v_mul_f32_e32 v15, s98, v112
	v_exp_f32_e32 v15, v15
	v_mul_f32_e32 v18, s98, v141
	v_mul_f32_e32 v17, s98, v113
	v_exp_f32_e32 v18, v18
	v_add_f32_e32 v15, 1.0, v15
	v_rcp_f32_e32 v15, v15
	v_exp_f32_e32 v17, v17
	v_mul_f32_e32 v12, s98, v138
	v_mul_f32_e32 v13, s98, v140
	v_mul_f32_e32 v15, v112, v15
	v_mul_f32_e32 v15, v15, v7
	v_add_f32_e32 v7, 1.0, v16
	v_mul_f32_e32 v16, s98, v111
	v_exp_f32_e32 v16, v16
	v_exp_f32_e32 v12, v12
	v_exp_f32_e32 v13, v13
	v_rcp_f32_e32 v7, v7
	v_add_f32_e32 v16, 1.0, v16
	v_rcp_f32_e32 v10, v10
	v_add_f32_e32 v11, 1.0, v18
	v_rcp_f32_e32 v16, v16
	v_add_f32_e32 v17, 1.0, v17
	v_rcp_f32_e32 v11, v11
	v_rcp_f32_e32 v17, v17
	v_add_f32_e32 v12, 1.0, v12
	v_add_f32_e32 v13, 1.0, v13
	v_mul_f32_e32 v7, v110, v7
	v_mul_f32_e32 v10, v139, v10
	v_rcp_f32_e32 v12, v12
	v_rcp_f32_e32 v13, v13
	v_mul_f32_e32 v18, v7, v6
	v_mul_f32_e32 v6, v111, v16
	v_mul_f32_e32 v10, v10, v87
	v_mul_f32_e32 v11, v141, v11
	v_mul_f32_e32 v16, v6, v8
	v_mul_f32_e32 v6, v113, v17
	v_mul_f32_e32 v11, v11, v86
	v_mul_f32_e32 v9, v6, v9
	v_cvt_pk_bf16_f32 v6, v10, v11
	v_add_u32_e32 v10, 0xb0, v14
	v_mad_i64_i32 v[2:3], s[0:1], v10, s83, v[2:3]
	v_mul_f32_e32 v12, v138, v12
	v_mul_f32_e32 v13, v140, v13
	v_lshl_add_u64 v[2:3], v[2:3], 0, v[4:5]
	v_mul_f32_e32 v12, v12, v82
	v_mul_f32_e32 v13, v13, v83
	v_cvt_pk_bf16_f32 v7, v12, v13
	v_cvt_pk_bf16_f32 v8, v15, v18
	v_cvt_pk_bf16_f32 v9, v16, v9
	global_store_dwordx4 v[2:3], v[6:9], off nt
	s_andn2_b64 vcc, exec, s[6:7]
	s_mov_b64 s[0:1], -1
	s_cbranch_vccnz .LBB0_1171
	s_andn2_b64 vcc, exec, s[16:17]
	s_cbranch_vccnz .LBB0_1170
	s_barrier
	s_branch .LBB0_1170

;     __device__ __forceinline__ void operator()(f32x4 (&acc)[2][2][4][2], const Unit& u, int ui, int wr, int wc, int fr_, int fq_) const {
;     ...
;         const int row0 = u.pm * BM + wr * 64 + fr, col0 = u.pn * BM + wc * 32 + 8 * fq;
; #pragma unroll
;         for (int ai = 0; ai < 2; ++ai)
; #pragma unroll
;             for (int m = 0; m < 4; ++m) { const size_t off = (size_t)(row0 + ai * HALF + m * 16) * 1024 + col0; float s = 0.f;
; #pragma unroll
;                 for (int bj = 0; bj < 2; ++bj) { f32x4 v0, v1;
;                     if (IN32) { const float* xi = Xin32 + off + bj * HALF; v0 = *(const f32x4*)xi; v1 = *(const f32x4*)(xi + 4); }
;                     else { const u32x4 w = *(const u32x4*)(XB + off + bj * HALF);
;                         if (RESID_F16) { const f32x2p_t a = unpk2h(w.x), b = unpk2h(w.y), c2 = unpk2h(w.z), d = unpk2h(w.w); v0 = (f32x4){a.x, a.y, b.x, b.y}; v1 = (f32x4){c2.x, c2.y, d.x, d.y}; }
;                         else { v0 = (f32x4){__builtin_bit_cast(float, w.x << 16), __builtin_bit_cast(float, w.x & 0xffff0000u), __builtin_bit_cast(float, w.y << 16), __builtin_bit_cast(float, w.y & 0xffff0000u)};
;                                v1 = (f32x4){__builtin_bit_cast(float, w.z << 16), __builtin_bit_cast(float, w.z & 0xffff0000u), __builtin_bit_cast(float, w.w << 16), __builtin_bit_cast(float, w.w & 0xffff0000u)}; } }
;                     v0 = v0 + acc[ai][bj][m][0]; v1 = v1 + acc[ai][bj][m][1];
;                     if (OUT32) { float* xp = Xout32 + off + bj * HALF; __builtin_nontemporal_store(v0, (f32x4*)xp); __builtin_nontemporal_store(v1, (f32x4*)(xp + 4)); }
;                     s += (v0[0] * v0[0] + v0[1] * v0[1]) + (v0[2] * v0[2] + v0[3] * v0[3]) + (v1[0] * v1[0] + v1[1] * v1[1]) + (v1[2] * v1[2] + v1[3] * v1[3]);
;                     u32x4 w; if (RESID_F16) { w.x = pk2h(v0[0], v0[1]); w.y = pk2h(v0[2], v0[3]); w.z = pk2h(v1[0], v1[1]); w.w = pk2h(v1[2], v1[3]); } else { w.x = cvt_pk_bf16(v0[0], v0[1]); w.y = cvt_pk_bf16(v0[2], v0[3]); w.z = cvt_pk_bf16(v1[0], v1[1]); w.w = cvt_pk_bf16(v1[2], v1[3]); }
;                     *(u32x4*)(XB + off + bj * HALF) = w; }
;                 s = fq_sum(s);
;                 if (fq == 0) SS[(size_t)(row0 + ai * HALF + m * 16) * 16 + u.pn * 4 + wc] = s;
;                 asm volatile("" ::: "memory"); }
.LBB0_1301:
	s_lshl_b32 s4, s54, 8
	v_mov_b32_e32 v142, v149
	v_mov_b32_e32 v145, v148
	s_add_i32 s4, s4, s36
	s_lshl_b32 s24, s53, 2
	v_add_u32_e32 v144, s4, v142
	s_lshl_b32 s4, s53, 8
	s_or_b32 s4, s4, s43
	v_lshl_add_u32 v142, v145, 3, s4
	v_cmp_eq_u32_e32 vcc, 0, v145
	v_ashrrev_i32_e32 v145, 31, v144
	v_lshlrev_b64 v[146:147], 11, v[144:145]
	v_ashrrev_i32_e32 v143, 31, v142
	v_lshl_add_u64 v[146:147], s[12:13], 0, v[146:147]
	v_lshl_add_u64 v[146:147], v[142:143], 1, v[146:147]
	v_mov_b32_e32 v182, 0x8000
	v_mov_b32_e32 v183, 0
	v_mov_b32_e32 v184, 0x40000
	v_mov_b32_e32 v185, 0
	global_load_dwordx4 v[196:199], v[146:147], off
	global_load_dwordx4 v[200:203], v[146:147], off offset:256
	v_lshl_add_u64 v[186:187], v[146:147], 0, v[182:183]
	global_load_dwordx4 v[204:207], v[186:187], off
	global_load_dwordx4 v[208:211], v[186:187], off offset:256
	v_lshl_add_u64 v[188:189], v[186:187], 0, v[182:183]
	global_load_dwordx4 v[212:215], v[188:189], off
	global_load_dwordx4 v[216:219], v[188:189], off offset:256
	v_lshl_add_u64 v[186:187], v[188:189], 0, v[182:183]
	global_load_dwordx4 v[220:223], v[186:187], off
	global_load_dwordx4 v[224:227], v[186:187], off offset:256
	s_ashr_i32 s25, s24, 31
	s_waitcnt vmcnt(7)
	v_lshlrev_b32_e32 v156, 16, v196
	v_and_b32_e32 v157, 0xffff0000, v196
	v_lshlrev_b32_e32 v152, 16, v197
	v_and_b32_e32 v153, 0xffff0000, v197
	v_lshlrev_b32_e32 v158, 16, v198
	v_and_b32_e32 v159, 0xffff0000, v198
	v_lshlrev_b32_e32 v154, 16, v199
	v_and_b32_e32 v155, 0xffff0000, v199
	v_pk_add_f32 v[128:129], v[128:129], v[152:153]
	v_pk_add_f32 v[126:127], v[126:127], v[156:157]
	v_pk_add_f32 v[152:153], v[124:125], v[154:155]
	v_pk_add_f32 v[124:125], v[122:123], v[158:159]
	v_mul_f32_e32 v122, v127, v127
	v_mul_f32_e32 v123, v129, v129
	v_fmac_f32_e32 v122, v126, v126
	v_fmac_f32_e32 v123, v128, v128
	v_add_f32_e32 v122, v122, v123
	v_mul_f32_e32 v123, v125, v125
	v_fmac_f32_e32 v123, v124, v124
	v_add_f32_e32 v122, v123, v122
	v_mul_f32_e32 v123, v153, v153
	v_fmac_f32_e32 v123, v152, v152
	v_add_f32_e32 v154, v123, v122
	v_cvt_pk_bf16_f32 v122, v126, v127
	v_cvt_pk_bf16_f32 v123, v128, v129
	v_cvt_pk_bf16_f32 v124, v124, v125
	v_cvt_pk_bf16_f32 v125, v152, v153
	global_store_dwordx4 v[146:147], v[122:125], off nt
	s_waitcnt vmcnt(7)
	v_lshlrev_b32_e32 v126, 16, v200
	v_and_b32_e32 v127, 0xffff0000, v200
	v_lshlrev_b32_e32 v122, 16, v201
	v_and_b32_e32 v123, 0xffff0000, v201
	v_lshlrev_b32_e32 v128, 16, v202
	v_and_b32_e32 v129, 0xffff0000, v202
	v_lshlrev_b32_e32 v124, 16, v203
	v_and_b32_e32 v125, 0xffff0000, v203
	v_lshl_add_u64 v[186:187], v[146:147], 0, v[184:185]
	global_load_dwordx4 v[196:199], v[186:187], off
	global_load_dwordx4 v[200:203], v[186:187], off offset:256
	v_pk_add_f32 v[120:121], v[120:121], v[122:123]
	v_pk_add_f32 v[118:119], v[118:119], v[126:127]
	v_pk_add_f32 v[122:123], v[116:117], v[124:125]
	v_pk_add_f32 v[116:117], v[114:115], v[128:129]
	v_mul_f32_e32 v114, v119, v119
	v_mul_f32_e32 v115, v121, v121
	v_fmac_f32_e32 v114, v118, v118
	v_fmac_f32_e32 v115, v120, v120
	v_add_f32_e32 v114, v114, v115
	v_mul_f32_e32 v115, v117, v117
	v_fmac_f32_e32 v115, v116, v116
	v_add_f32_e32 v114, v115, v114
	v_mul_f32_e32 v115, v123, v123
	v_fmac_f32_e32 v115, v122, v122
	v_add_f32_e32 v114, v115, v114
	v_add_f32_e32 v124, v154, v114
	v_cvt_pk_bf16_f32 v114, v118, v119
	v_cvt_pk_bf16_f32 v115, v120, v121
	v_cvt_pk_bf16_f32 v116, v116, v117
	v_cvt_pk_bf16_f32 v117, v122, v123
	global_store_dwordx4 v[146:147], v[114:117], off offset:256 nt
	s_nop 1
	v_mov_b32_e32 v114, v124
	s_nop 1
	v_permlane32_swap_b32_e32 v124, v114
	v_add_f32_e32 v114, v124, v114
	v_mov_b32_e32 v115, v114
	s_nop 1
	v_permlane16_swap_b32_e32 v114, v115
	s_and_saveexec_b64 s[26:27], vcc
	s_cbranch_execz .LBB0_1303
	v_add_f32_e32 v116, v114, v115
	v_lshlrev_b64 v[114:115], 6, v[144:145]
	v_lshl_add_u64 v[114:115], s[16:17], 0, v[114:115]
	v_lshl_add_u64 v[114:115], s[24:25], 2, v[114:115]
	s_lshl_b32 s86, s33, 2
	v_lshl_add_u64 v[114:115], v[114:115], 0, s[86:87]
	global_store_dword v[114:115], v116, off
.LBB0_1303:
	s_or_b64 exec, exec, s[26:27]
	v_add_u32_e32 v114, 16, v144
	v_ashrrev_i32_e32 v115, 31, v114
	v_lshlrev_b64 v[116:117], 11, v[114:115]
	v_lshl_add_u64 v[116:117], s[12:13], 0, v[116:117]
	v_lshl_add_u64 v[120:121], v[142:143], 1, v[116:117]
	s_waitcnt vmcnt(10)
	v_lshlrev_b32_e32 v122, 16, v204
	v_and_b32_e32 v123, 0xffff0000, v204
	v_lshlrev_b32_e32 v116, 16, v205
	v_and_b32_e32 v117, 0xffff0000, v205
	v_lshlrev_b32_e32 v124, 16, v206
	v_and_b32_e32 v125, 0xffff0000, v206
	v_lshlrev_b32_e32 v118, 16, v207
	v_and_b32_e32 v119, 0xffff0000, v207
	v_pk_add_f32 v[116:117], v[112:113], v[116:117]
	v_pk_add_f32 v[122:123], v[110:111], v[122:123]
	v_pk_add_f32 v[118:119], v[108:109], v[118:119]
	v_pk_add_f32 v[124:125], v[106:107], v[124:125]
	v_cvt_pk_bf16_f32 v106, v122, v123
	v_cvt_pk_bf16_f32 v107, v116, v117
	v_mul_f32_e32 v123, v123, v123
	v_cvt_pk_bf16_f32 v108, v124, v125
	v_cvt_pk_bf16_f32 v109, v118, v119
	v_mul_f32_e32 v117, v117, v117
	v_mul_f32_e32 v125, v125, v125
	v_fmac_f32_e32 v123, v122, v122
	v_fmac_f32_e32 v117, v116, v116
	v_mul_f32_e32 v119, v119, v119
	v_fmac_f32_e32 v125, v124, v124
	global_store_dwordx4 v[120:121], v[106:109], off nt
	v_fmac_f32_e32 v119, v118, v118
	s_nop 0
	v_add_f32_e32 v106, v123, v117
	v_add_f32_e32 v106, v125, v106
	v_add_f32_e32 v116, v119, v106
	s_waitcnt vmcnt(10)
	v_lshlrev_b32_e32 v106, 16, v208
	v_and_b32_e32 v107, 0xffff0000, v208
	v_lshlrev_b32_e32 v108, 16, v209
	v_and_b32_e32 v109, 0xffff0000, v209
	v_lshlrev_b32_e32 v110, 16, v210
	v_and_b32_e32 v111, 0xffff0000, v210
	v_pk_add_f32 v[104:105], v[104:105], v[108:109]
	v_pk_add_f32 v[102:103], v[102:103], v[106:107]
	v_lshlrev_b32_e32 v112, 16, v211
	v_and_b32_e32 v113, 0xffff0000, v211
	v_lshl_add_u64 v[188:189], v[120:121], 0, v[184:185]
	global_load_dwordx4 v[204:207], v[188:189], off
	global_load_dwordx4 v[208:211], v[188:189], off offset:256
	v_pk_add_f32 v[108:109], v[98:99], v[110:111]
	v_mul_f32_e32 v110, v103, v103
	v_mul_f32_e32 v111, v105, v105
	v_pk_add_f32 v[106:107], v[100:101], v[112:113]
	v_mul_f32_e32 v112, v109, v109
	v_cvt_pk_bf16_f32 v98, v102, v103
	v_fmac_f32_e32 v110, v102, v102
	v_fmac_f32_e32 v111, v104, v104
	v_mul_f32_e32 v113, v107, v107
	v_cvt_pk_bf16_f32 v99, v104, v105
	v_cvt_pk_bf16_f32 v100, v108, v109
	v_cvt_pk_bf16_f32 v101, v106, v107
	v_fmac_f32_e32 v112, v108, v108
	global_store_dwordx4 v[120:121], v[98:101], off offset:256 nt
	v_fmac_f32_e32 v113, v106, v106
	s_nop 0
	v_add_f32_e32 v98, v110, v111
	v_add_f32_e32 v98, v112, v98
	v_add_f32_e32 v98, v113, v98
	v_add_f32_e32 v98, v116, v98
	v_mov_b32_e32 v99, v98
	s_nop 1
	v_permlane32_swap_b32_e32 v98, v99
	v_add_f32_e32 v98, v98, v99
	v_mov_b32_e32 v99, v98
	s_nop 1
	v_permlane16_swap_b32_e32 v98, v99
	s_and_saveexec_b64 s[26:27], vcc
	s_cbranch_execz .LBB0_1305
;     __device__ __forceinline__ void operator()(f32x4 (&acc)[2][2][4][2], const Unit& u, int ui, int wr, int wc, int fr_, int fq_) const {
;     ...
;         const int row0 = u.pm * BM + wr * 64 + fr, col0 = u.pn * BM + wc * 32 + 8 * fq;
; #pragma unroll
;         for (int ai = 0; ai < 2; ++ai)
; #pragma unroll
;             for (int m = 0; m < 4; ++m) { const size_t off = (size_t)(row0 + ai * HALF + m * 16) * 1024 + col0; float s = 0.f;
; #pragma unroll
;                 for (int bj = 0; bj < 2; ++bj) { f32x4 v0, v1;
;                     if (IN32) { const float* xi = Xin32 + off + bj * HALF; v0 = *(const f32x4*)xi; v1 = *(const f32x4*)(xi + 4); }
;                     else { const u32x4 w = *(const u32x4*)(XB + off + bj * HALF);
;                         if (RESID_F16) { const f32x2p_t a = unpk2h(w.x), b = unpk2h(w.y), c2 = unpk2h(w.z), d = unpk2h(w.w); v0 = (f32x4){a.x, a.y, b.x, b.y}; v1 = (f32x4){c2.x, c2.y, d.x, d.y}; }
;                         else { v0 = (f32x4){__builtin_bit_cast(float, w.x << 16), __builtin_bit_cast(float, w.x & 0xffff0000u), __builtin_bit_cast(float, w.y << 16), __builtin_bit_cast(float, w.y & 0xffff0000u)};
;                                v1 = (f32x4){__builtin_bit_cast(float, w.z << 16), __builtin_bit_cast(float, w.z & 0xffff0000u), __builtin_bit_cast(float, w.w << 16), __builtin_bit_cast(float, w.w & 0xffff0000u)}; } }
;                     v0 = v0 + acc[ai][bj][m][0]; v1 = v1 + acc[ai][bj][m][1];
;                     if (OUT32) { float* xp = Xout32 + off + bj * HALF; __builtin_nontemporal_store(v0, (f32x4*)xp); __builtin_nontemporal_store(v1, (f32x4*)(xp + 4)); }
;                     s += (v0[0] * v0[0] + v0[1] * v0[1]) + (v0[2] * v0[2] + v0[3] * v0[3]) + (v1[0] * v1[0] + v1[1] * v1[1]) + (v1[2] * v1[2] + v1[3] * v1[3]);
;                     u32x4 w; if (RESID_F16) { w.x = pk2h(v0[0], v0[1]); w.y = pk2h(v0[2], v0[3]); w.z = pk2h(v1[0], v1[1]); w.w = pk2h(v1[2], v1[3]); } else { w.x = cvt_pk_bf16(v0[0], v0[1]); w.y = cvt_pk_bf16(v0[2], v0[3]); w.z = cvt_pk_bf16(v1[0], v1[1]); w.w = cvt_pk_bf16(v1[2], v1[3]); }
;                     *(u32x4*)(XB + off + bj * HALF) = w; }
;                 s = fq_sum(s);
;                 if (fq == 0) SS[(size_t)(row0 + ai * HALF + m * 16) * 16 + u.pn * 4 + wc] = s;
;                 asm volatile("" ::: "memory"); }
	v_add_f32_e32 v100, v98, v99
	v_lshlrev_b64 v[98:99], 6, v[114:115]
	v_lshl_add_u64 v[98:99], s[16:17], 0, v[98:99]
	v_lshl_add_u64 v[98:99], s[24:25], 2, v[98:99]
	s_lshl_b32 s86, s33, 2
	v_lshl_add_u64 v[98:99], v[98:99], 0, s[86:87]
	global_store_dword v[98:99], v100, off
.LBB0_1305:
	s_or_b64 exec, exec, s[26:27]
	v_add_u32_e32 v98, 32, v144
	v_ashrrev_i32_e32 v99, 31, v98
	v_lshlrev_b64 v[100:101], 11, v[98:99]
	v_lshl_add_u64 v[100:101], s[12:13], 0, v[100:101]
	v_lshl_add_u64 v[104:105], v[142:143], 1, v[100:101]
	s_waitcnt vmcnt(13)
	v_lshlrev_b32_e32 v106, 16, v212
	v_and_b32_e32 v107, 0xffff0000, v212
	v_lshlrev_b32_e32 v100, 16, v213
	v_and_b32_e32 v101, 0xffff0000, v213
	v_lshlrev_b32_e32 v108, 16, v214
	v_and_b32_e32 v109, 0xffff0000, v214
	v_lshlrev_b32_e32 v102, 16, v215
	v_and_b32_e32 v103, 0xffff0000, v215
	v_pk_add_f32 v[100:101], v[96:97], v[100:101]
	v_pk_add_f32 v[106:107], v[94:95], v[106:107]
	v_pk_add_f32 v[102:103], v[92:93], v[102:103]
	v_pk_add_f32 v[108:109], v[90:91], v[108:109]
	v_cvt_pk_bf16_f32 v90, v106, v107
	v_cvt_pk_bf16_f32 v91, v100, v101
	v_mul_f32_e32 v107, v107, v107
	v_cvt_pk_bf16_f32 v92, v108, v109
	v_cvt_pk_bf16_f32 v93, v102, v103
	v_mul_f32_e32 v101, v101, v101
	v_mul_f32_e32 v109, v109, v109
	v_fmac_f32_e32 v107, v106, v106
	v_fmac_f32_e32 v101, v100, v100
	v_mul_f32_e32 v103, v103, v103
	v_fmac_f32_e32 v109, v108, v108
	global_store_dwordx4 v[104:105], v[90:93], off nt
	v_fmac_f32_e32 v103, v102, v102
	s_nop 0
	v_add_f32_e32 v90, v107, v101
	v_add_f32_e32 v90, v109, v90
	v_add_f32_e32 v100, v103, v90
	s_waitcnt vmcnt(13)
	v_lshlrev_b32_e32 v90, 16, v216
	v_and_b32_e32 v91, 0xffff0000, v216
	v_lshlrev_b32_e32 v92, 16, v217
	v_and_b32_e32 v93, 0xffff0000, v217
	v_lshlrev_b32_e32 v94, 16, v218
	v_and_b32_e32 v95, 0xffff0000, v218
	v_pk_add_f32 v[88:89], v[88:89], v[92:93]
	v_pk_add_f32 v[86:87], v[86:87], v[90:91]
	v_lshlrev_b32_e32 v96, 16, v219
	v_and_b32_e32 v97, 0xffff0000, v219
	v_lshl_add_u64 v[186:187], v[104:105], 0, v[184:185]
	global_load_dwordx4 v[212:215], v[186:187], off
	global_load_dwordx4 v[216:219], v[186:187], off offset:256
	v_pk_add_f32 v[92:93], v[82:83], v[94:95]
	v_mul_f32_e32 v94, v87, v87
	v_mul_f32_e32 v95, v89, v89
	v_pk_add_f32 v[90:91], v[84:85], v[96:97]
	v_mul_f32_e32 v96, v93, v93
	v_cvt_pk_bf16_f32 v82, v86, v87
	v_fmac_f32_e32 v94, v86, v86
	v_fmac_f32_e32 v95, v88, v88
	v_mul_f32_e32 v97, v91, v91
	v_cvt_pk_bf16_f32 v83, v88, v89
	v_cvt_pk_bf16_f32 v84, v92, v93
	v_cvt_pk_bf16_f32 v85, v90, v91
	v_fmac_f32_e32 v96, v92, v92
	global_store_dwordx4 v[104:105], v[82:85], off offset:256 nt
	v_fmac_f32_e32 v97, v90, v90
	s_nop 0
	v_add_f32_e32 v82, v94, v95
	v_add_f32_e32 v82, v96, v82
	v_add_f32_e32 v82, v97, v82
	v_add_f32_e32 v82, v100, v82
	v_mov_b32_e32 v83, v82
	s_nop 1
	v_permlane32_swap_b32_e32 v82, v83
	v_add_f32_e32 v82, v82, v83
	v_mov_b32_e32 v83, v82
	s_nop 1
	v_permlane16_swap_b32_e32 v82, v83
	s_and_saveexec_b64 s[26:27], vcc
	s_cbranch_execz .LBB0_1307
	v_add_f32_e32 v84, v82, v83
	v_lshlrev_b64 v[82:83], 6, v[98:99]
	v_lshl_add_u64 v[82:83], s[16:17], 0, v[82:83]
	v_lshl_add_u64 v[82:83], s[24:25], 2, v[82:83]
	s_lshl_b32 s86, s33, 2
	v_lshl_add_u64 v[82:83], v[82:83], 0, s[86:87]
	global_store_dword v[82:83], v84, off
.LBB0_1307:
	s_or_b64 exec, exec, s[26:27]
	v_add_u32_e32 v82, 48, v144
	v_ashrrev_i32_e32 v83, 31, v82
	v_lshlrev_b64 v[84:85], 11, v[82:83]
	v_lshl_add_u64 v[84:85], s[12:13], 0, v[84:85]
	v_lshl_add_u64 v[88:89], v[142:143], 1, v[84:85]
	s_waitcnt vmcnt(16)
	v_lshlrev_b32_e32 v90, 16, v220
	v_and_b32_e32 v91, 0xffff0000, v220
	v_lshlrev_b32_e32 v84, 16, v221
	v_and_b32_e32 v85, 0xffff0000, v221
	v_lshlrev_b32_e32 v92, 16, v222
	v_and_b32_e32 v93, 0xffff0000, v222
	v_lshlrev_b32_e32 v86, 16, v223
	v_and_b32_e32 v87, 0xffff0000, v223
	v_pk_add_f32 v[84:85], v[80:81], v[84:85]
	v_pk_add_f32 v[90:91], v[78:79], v[90:91]
	v_pk_add_f32 v[86:87], v[76:77], v[86:87]
	v_pk_add_f32 v[92:93], v[74:75], v[92:93]
	v_cvt_pk_bf16_f32 v74, v90, v91
	v_cvt_pk_bf16_f32 v75, v84, v85
	v_mul_f32_e32 v91, v91, v91
	v_cvt_pk_bf16_f32 v76, v92, v93
	v_cvt_pk_bf16_f32 v77, v86, v87
	v_mul_f32_e32 v85, v85, v85
	v_mul_f32_e32 v93, v93, v93
	v_fmac_f32_e32 v91, v90, v90
	v_fmac_f32_e32 v85, v84, v84
	v_mul_f32_e32 v87, v87, v87
	v_fmac_f32_e32 v93, v92, v92
	global_store_dwordx4 v[88:89], v[74:77], off nt
	v_fmac_f32_e32 v87, v86, v86
	s_nop 0
	v_add_f32_e32 v74, v91, v85
	v_add_f32_e32 v74, v93, v74
	v_add_f32_e32 v84, v87, v74
	s_waitcnt vmcnt(16)
	v_lshlrev_b32_e32 v74, 16, v224
	v_and_b32_e32 v75, 0xffff0000, v224
	v_lshlrev_b32_e32 v76, 16, v225
	v_and_b32_e32 v77, 0xffff0000, v225
	v_lshlrev_b32_e32 v78, 16, v226
	v_and_b32_e32 v79, 0xffff0000, v226
	v_pk_add_f32 v[72:73], v[72:73], v[76:77]
	v_pk_add_f32 v[70:71], v[70:71], v[74:75]
	v_lshlrev_b32_e32 v80, 16, v227
	v_and_b32_e32 v81, 0xffff0000, v227
	v_lshl_add_u64 v[188:189], v[88:89], 0, v[184:185]
	global_load_dwordx4 v[220:223], v[188:189], off
	global_load_dwordx4 v[224:227], v[188:189], off offset:256
	v_pk_add_f32 v[76:77], v[66:67], v[78:79]
	v_mul_f32_e32 v78, v71, v71
	v_mul_f32_e32 v79, v73, v73
	v_pk_add_f32 v[74:75], v[68:69], v[80:81]
	v_mul_f32_e32 v80, v77, v77
	v_cvt_pk_bf16_f32 v66, v70, v71
	v_fmac_f32_e32 v78, v70, v70
	v_fmac_f32_e32 v79, v72, v72
	v_mul_f32_e32 v81, v75, v75
	v_cvt_pk_bf16_f32 v67, v72, v73
	v_cvt_pk_bf16_f32 v68, v76, v77
	v_cvt_pk_bf16_f32 v69, v74, v75
	v_fmac_f32_e32 v80, v76, v76
	global_store_dwordx4 v[88:89], v[66:69], off offset:256 nt
	v_fmac_f32_e32 v81, v74, v74
	s_nop 0
	v_add_f32_e32 v66, v78, v79
	v_add_f32_e32 v66, v80, v66
	v_add_f32_e32 v66, v81, v66
	v_add_f32_e32 v66, v84, v66
	v_mov_b32_e32 v67, v66
	s_nop 1
	v_permlane32_swap_b32_e32 v66, v67
	v_add_f32_e32 v66, v66, v67
	v_mov_b32_e32 v67, v66
	s_nop 1
	v_permlane16_swap_b32_e32 v66, v67
	s_and_saveexec_b64 s[26:27], vcc
	s_cbranch_execz .LBB0_1309
	v_add_f32_e32 v68, v66, v67
	v_lshlrev_b64 v[66:67], 6, v[82:83]
	v_lshl_add_u64 v[66:67], s[16:17], 0, v[66:67]
	v_lshl_add_u64 v[66:67], s[24:25], 2, v[66:67]
	s_lshl_b32 s86, s33, 2
	v_lshl_add_u64 v[66:67], v[66:67], 0, s[86:87]
	global_store_dword v[66:67], v68, off
;     __device__ __forceinline__ void operator()(f32x4 (&acc)[2][2][4][2], const Unit& u, int ui, int wr, int wc, int fr_, int fq_) const {
;     ...
;         const int row0 = u.pm * BM + wr * 64 + fr, col0 = u.pn * BM + wc * 32 + 8 * fq;
; #pragma unroll
;         for (int ai = 0; ai < 2; ++ai)
; #pragma unroll
;             for (int m = 0; m < 4; ++m) { const size_t off = (size_t)(row0 + ai * HALF + m * 16) * 1024 + col0; float s = 0.f;
; #pragma unroll
;                 for (int bj = 0; bj < 2; ++bj) { f32x4 v0, v1;
;                     if (IN32) { const float* xi = Xin32 + off + bj * HALF; v0 = *(const f32x4*)xi; v1 = *(const f32x4*)(xi + 4); }
;                     else { const u32x4 w = *(const u32x4*)(XB + off + bj * HALF);
;                         if (RESID_F16) { const f32x2p_t a = unpk2h(w.x), b = unpk2h(w.y), c2 = unpk2h(w.z), d = unpk2h(w.w); v0 = (f32x4){a.x, a.y, b.x, b.y}; v1 = (f32x4){c2.x, c2.y, d.x, d.y}; }
;                         else { v0 = (f32x4){__builtin_bit_cast(float, w.x << 16), __builtin_bit_cast(float, w.x & 0xffff0000u), __builtin_bit_cast(float, w.y << 16), __builtin_bit_cast(float, w.y & 0xffff0000u)};
;                                v1 = (f32x4){__builtin_bit_cast(float, w.z << 16), __builtin_bit_cast(float, w.z & 0xffff0000u), __builtin_bit_cast(float, w.w << 16), __builtin_bit_cast(float, w.w & 0xffff0000u)}; } }
;                     v0 = v0 + acc[ai][bj][m][0]; v1 = v1 + acc[ai][bj][m][1];
;                     if (OUT32) { float* xp = Xout32 + off + bj * HALF; __builtin_nontemporal_store(v0, (f32x4*)xp); __builtin_nontemporal_store(v1, (f32x4*)(xp + 4)); }
;                     s += (v0[0] * v0[0] + v0[1] * v0[1]) + (v0[2] * v0[2] + v0[3] * v0[3]) + (v1[0] * v1[0] + v1[1] * v1[1]) + (v1[2] * v1[2] + v1[3] * v1[3]);
;                     u32x4 w; if (RESID_F16) { w.x = pk2h(v0[0], v0[1]); w.y = pk2h(v0[2], v0[3]); w.z = pk2h(v1[0], v1[1]); w.w = pk2h(v1[2], v1[3]); } else { w.x = cvt_pk_bf16(v0[0], v0[1]); w.y = cvt_pk_bf16(v0[2], v0[3]); w.z = cvt_pk_bf16(v1[0], v1[1]); w.w = cvt_pk_bf16(v1[2], v1[3]); }
;                     *(u32x4*)(XB + off + bj * HALF) = w; }
;                 s = fq_sum(s);
;                 if (fq == 0) SS[(size_t)(row0 + ai * HALF + m * 16) * 16 + u.pn * 4 + wc] = s;
;                 asm volatile("" ::: "memory"); }
.LBB0_1309:
	s_or_b64 exec, exec, s[26:27]
	v_add_u32_e32 v66, 0x80, v144
	v_ashrrev_i32_e32 v67, 31, v66
	v_lshlrev_b64 v[68:69], 11, v[66:67]
	v_lshl_add_u64 v[68:69], s[12:13], 0, v[68:69]
	v_lshl_add_u64 v[72:73], v[142:143], 1, v[68:69]
	s_waitcnt vmcnt(18)
	v_lshlrev_b32_e32 v74, 16, v196
	v_and_b32_e32 v75, 0xffff0000, v196
	v_lshlrev_b32_e32 v68, 16, v197
	v_and_b32_e32 v69, 0xffff0000, v197
	v_lshlrev_b32_e32 v76, 16, v198
	v_and_b32_e32 v77, 0xffff0000, v198
	v_lshlrev_b32_e32 v70, 16, v199
	v_and_b32_e32 v71, 0xffff0000, v199
	v_pk_add_f32 v[68:69], v[64:65], v[68:69]
	v_pk_add_f32 v[74:75], v[62:63], v[74:75]
	v_pk_add_f32 v[70:71], v[60:61], v[70:71]
	v_pk_add_f32 v[76:77], v[58:59], v[76:77]
	v_cvt_pk_bf16_f32 v58, v74, v75
	v_cvt_pk_bf16_f32 v59, v68, v69
	v_mul_f32_e32 v75, v75, v75
	v_cvt_pk_bf16_f32 v60, v76, v77
	v_cvt_pk_bf16_f32 v61, v70, v71
	v_mul_f32_e32 v69, v69, v69
	v_mul_f32_e32 v77, v77, v77
	v_fmac_f32_e32 v75, v74, v74
	v_fmac_f32_e32 v69, v68, v68
	v_mul_f32_e32 v71, v71, v71
	v_fmac_f32_e32 v77, v76, v76
	global_store_dwordx4 v[72:73], v[58:61], off nt
	v_fmac_f32_e32 v71, v70, v70
	s_nop 0
	v_add_f32_e32 v58, v75, v69
	v_add_f32_e32 v58, v77, v58
	v_add_f32_e32 v68, v71, v58
	s_waitcnt vmcnt(18)
	v_lshlrev_b32_e32 v58, 16, v200
	v_and_b32_e32 v59, 0xffff0000, v200
	v_lshlrev_b32_e32 v60, 16, v201
	v_and_b32_e32 v61, 0xffff0000, v201
	v_lshlrev_b32_e32 v62, 16, v202
	v_and_b32_e32 v63, 0xffff0000, v202
	v_pk_add_f32 v[56:57], v[56:57], v[60:61]
	v_pk_add_f32 v[54:55], v[54:55], v[58:59]
	v_lshlrev_b32_e32 v64, 16, v203
	v_and_b32_e32 v65, 0xffff0000, v203
	v_pk_add_f32 v[60:61], v[50:51], v[62:63]
	v_mul_f32_e32 v62, v55, v55
	v_mul_f32_e32 v63, v57, v57
	v_pk_add_f32 v[58:59], v[52:53], v[64:65]
	v_mul_f32_e32 v64, v61, v61
	v_cvt_pk_bf16_f32 v50, v54, v55
	v_fmac_f32_e32 v62, v54, v54
	v_fmac_f32_e32 v63, v56, v56
	v_mul_f32_e32 v65, v59, v59
	v_cvt_pk_bf16_f32 v51, v56, v57
	v_cvt_pk_bf16_f32 v52, v60, v61
	v_cvt_pk_bf16_f32 v53, v58, v59
	v_fmac_f32_e32 v64, v60, v60
	global_store_dwordx4 v[72:73], v[50:53], off offset:256 nt
	v_fmac_f32_e32 v65, v58, v58
	s_nop 0
	v_add_f32_e32 v50, v62, v63
	v_add_f32_e32 v50, v64, v50
	v_add_f32_e32 v50, v65, v50
	v_add_f32_e32 v50, v68, v50
	v_mov_b32_e32 v51, v50
	s_nop 1
	v_permlane32_swap_b32_e32 v50, v51
	v_add_f32_e32 v50, v50, v51
	v_mov_b32_e32 v51, v50
	s_nop 1
	v_permlane16_swap_b32_e32 v50, v51
	s_and_saveexec_b64 s[26:27], vcc
	s_cbranch_execz .LBB0_1311
	v_add_f32_e32 v52, v50, v51
	v_lshlrev_b64 v[50:51], 6, v[66:67]
	v_lshl_add_u64 v[50:51], s[16:17], 0, v[50:51]
	v_lshl_add_u64 v[50:51], s[24:25], 2, v[50:51]
	s_lshl_b32 s86, s33, 2
	v_lshl_add_u64 v[50:51], v[50:51], 0, s[86:87]
	global_store_dword v[50:51], v52, off
.LBB0_1311:
	s_or_b64 exec, exec, s[26:27]
	v_add_u32_e32 v50, 0x90, v144
	v_ashrrev_i32_e32 v51, 31, v50
	v_lshlrev_b64 v[52:53], 11, v[50:51]
	v_lshl_add_u64 v[52:53], s[12:13], 0, v[52:53]
	v_lshl_add_u64 v[56:57], v[142:143], 1, v[52:53]
	s_waitcnt vmcnt(16)
	v_lshlrev_b32_e32 v58, 16, v204
	v_and_b32_e32 v59, 0xffff0000, v204
	v_lshlrev_b32_e32 v52, 16, v205
	v_and_b32_e32 v53, 0xffff0000, v205
	v_lshlrev_b32_e32 v60, 16, v206
	v_and_b32_e32 v61, 0xffff0000, v206
	v_lshlrev_b32_e32 v54, 16, v207
	v_and_b32_e32 v55, 0xffff0000, v207
	v_pk_add_f32 v[52:53], v[48:49], v[52:53]
	v_pk_add_f32 v[58:59], v[46:47], v[58:59]
	v_pk_add_f32 v[54:55], v[44:45], v[54:55]
	v_pk_add_f32 v[60:61], v[42:43], v[60:61]
	v_cvt_pk_bf16_f32 v42, v58, v59
	v_cvt_pk_bf16_f32 v43, v52, v53
	v_mul_f32_e32 v59, v59, v59
	v_cvt_pk_bf16_f32 v44, v60, v61
	v_cvt_pk_bf16_f32 v45, v54, v55
	v_mul_f32_e32 v53, v53, v53
	v_mul_f32_e32 v61, v61, v61
	v_fmac_f32_e32 v59, v58, v58
	v_fmac_f32_e32 v53, v52, v52
	v_mul_f32_e32 v55, v55, v55
	v_fmac_f32_e32 v61, v60, v60
	global_store_dwordx4 v[56:57], v[42:45], off nt
	v_fmac_f32_e32 v55, v54, v54
	s_nop 0
	v_add_f32_e32 v42, v59, v53
	v_add_f32_e32 v42, v61, v42
	v_add_f32_e32 v52, v55, v42
	s_waitcnt vmcnt(16)
	v_lshlrev_b32_e32 v42, 16, v208
	v_and_b32_e32 v43, 0xffff0000, v208
	v_lshlrev_b32_e32 v44, 16, v209
	v_and_b32_e32 v45, 0xffff0000, v209
	v_lshlrev_b32_e32 v46, 16, v210
	v_and_b32_e32 v47, 0xffff0000, v210
	v_pk_add_f32 v[40:41], v[40:41], v[44:45]
	v_pk_add_f32 v[38:39], v[38:39], v[42:43]
	v_lshlrev_b32_e32 v48, 16, v211
	v_and_b32_e32 v49, 0xffff0000, v211
	v_pk_add_f32 v[44:45], v[34:35], v[46:47]
	v_mul_f32_e32 v46, v39, v39
	v_mul_f32_e32 v47, v41, v41
	v_pk_add_f32 v[42:43], v[36:37], v[48:49]
	v_mul_f32_e32 v48, v45, v45
	v_cvt_pk_bf16_f32 v34, v38, v39
	v_fmac_f32_e32 v46, v38, v38
	v_fmac_f32_e32 v47, v40, v40
	v_mul_f32_e32 v49, v43, v43
	v_cvt_pk_bf16_f32 v35, v40, v41
	v_cvt_pk_bf16_f32 v36, v44, v45
	v_cvt_pk_bf16_f32 v37, v42, v43
	v_fmac_f32_e32 v48, v44, v44
	global_store_dwordx4 v[56:57], v[34:37], off offset:256 nt
	v_fmac_f32_e32 v49, v42, v42
	s_nop 0
	v_add_f32_e32 v34, v46, v47
	v_add_f32_e32 v34, v48, v34
	v_add_f32_e32 v34, v49, v34
	v_add_f32_e32 v34, v52, v34
	v_mov_b32_e32 v35, v34
	s_nop 1
	v_permlane32_swap_b32_e32 v34, v35
	v_add_f32_e32 v34, v34, v35
	v_mov_b32_e32 v35, v34
	s_nop 1
	v_permlane16_swap_b32_e32 v34, v35
	s_and_saveexec_b64 s[26:27], vcc
	s_cbranch_execz .LBB0_1313
	v_add_f32_e32 v36, v34, v35
	v_lshlrev_b64 v[34:35], 6, v[50:51]
	v_lshl_add_u64 v[34:35], s[16:17], 0, v[34:35]
	v_lshl_add_u64 v[34:35], s[24:25], 2, v[34:35]
	s_lshl_b32 s86, s33, 2
	v_lshl_add_u64 v[34:35], v[34:35], 0, s[86:87]
	global_store_dword v[34:35], v36, off
;     __device__ __forceinline__ void operator()(f32x4 (&acc)[2][2][4][2], const Unit& u, int ui, int wr, int wc, int fr_, int fq_) const {
;     ...
;         const int row0 = u.pm * BM + wr * 64 + fr, col0 = u.pn * BM + wc * 32 + 8 * fq;
; #pragma unroll
;         for (int ai = 0; ai < 2; ++ai)
; #pragma unroll
;             for (int m = 0; m < 4; ++m) { const size_t off = (size_t)(row0 + ai * HALF + m * 16) * 1024 + col0; float s = 0.f;
; #pragma unroll
;                 for (int bj = 0; bj < 2; ++bj) { f32x4 v0, v1;
;                     if (IN32) { const float* xi = Xin32 + off + bj * HALF; v0 = *(const f32x4*)xi; v1 = *(const f32x4*)(xi + 4); }
;                     else { const u32x4 w = *(const u32x4*)(XB + off + bj * HALF);
;                         if (RESID_F16) { const f32x2p_t a = unpk2h(w.x), b = unpk2h(w.y), c2 = unpk2h(w.z), d = unpk2h(w.w); v0 = (f32x4){a.x, a.y, b.x, b.y}; v1 = (f32x4){c2.x, c2.y, d.x, d.y}; }
;                         else { v0 = (f32x4){__builtin_bit_cast(float, w.x << 16), __builtin_bit_cast(float, w.x & 0xffff0000u), __builtin_bit_cast(float, w.y << 16), __builtin_bit_cast(float, w.y & 0xffff0000u)};
;                                v1 = (f32x4){__builtin_bit_cast(float, w.z << 16), __builtin_bit_cast(float, w.z & 0xffff0000u), __builtin_bit_cast(float, w.w << 16), __builtin_bit_cast(float, w.w & 0xffff0000u)}; } }
;                     v0 = v0 + acc[ai][bj][m][0]; v1 = v1 + acc[ai][bj][m][1];
;                     if (OUT32) { float* xp = Xout32 + off + bj * HALF; __builtin_nontemporal_store(v0, (f32x4*)xp); __builtin_nontemporal_store(v1, (f32x4*)(xp + 4)); }
;                     s += (v0[0] * v0[0] + v0[1] * v0[1]) + (v0[2] * v0[2] + v0[3] * v0[3]) + (v1[0] * v1[0] + v1[1] * v1[1]) + (v1[2] * v1[2] + v1[3] * v1[3]);
;                     u32x4 w; if (RESID_F16) { w.x = pk2h(v0[0], v0[1]); w.y = pk2h(v0[2], v0[3]); w.z = pk2h(v1[0], v1[1]); w.w = pk2h(v1[2], v1[3]); } else { w.x = cvt_pk_bf16(v0[0], v0[1]); w.y = cvt_pk_bf16(v0[2], v0[3]); w.z = cvt_pk_bf16(v1[0], v1[1]); w.w = cvt_pk_bf16(v1[2], v1[3]); }
;                     *(u32x4*)(XB + off + bj * HALF) = w; }
;                 s = fq_sum(s);
;                 if (fq == 0) SS[(size_t)(row0 + ai * HALF + m * 16) * 16 + u.pn * 4 + wc] = s;
;                 asm volatile("" ::: "memory"); }
.LBB0_1313:
	s_or_b64 exec, exec, s[26:27]
	v_add_u32_e32 v34, 0xa0, v144
	v_ashrrev_i32_e32 v35, 31, v34
	v_lshlrev_b64 v[36:37], 11, v[34:35]
	v_lshl_add_u64 v[36:37], s[12:13], 0, v[36:37]
	v_lshl_add_u64 v[40:41], v[142:143], 1, v[36:37]
	s_waitcnt vmcnt(14)
	v_lshlrev_b32_e32 v42, 16, v212
	v_and_b32_e32 v43, 0xffff0000, v212
	v_lshlrev_b32_e32 v36, 16, v213
	v_and_b32_e32 v37, 0xffff0000, v213
	v_lshlrev_b32_e32 v44, 16, v214
	v_and_b32_e32 v45, 0xffff0000, v214
	v_lshlrev_b32_e32 v38, 16, v215
	v_and_b32_e32 v39, 0xffff0000, v215
	v_pk_add_f32 v[36:37], v[32:33], v[36:37]
	v_pk_add_f32 v[42:43], v[30:31], v[42:43]
	v_pk_add_f32 v[38:39], v[28:29], v[38:39]
	v_pk_add_f32 v[44:45], v[26:27], v[44:45]
	v_cvt_pk_bf16_f32 v26, v42, v43
	v_cvt_pk_bf16_f32 v27, v36, v37
	v_mul_f32_e32 v43, v43, v43
	v_cvt_pk_bf16_f32 v28, v44, v45
	v_cvt_pk_bf16_f32 v29, v38, v39
	v_mul_f32_e32 v37, v37, v37
	v_mul_f32_e32 v45, v45, v45
	v_fmac_f32_e32 v43, v42, v42
	v_fmac_f32_e32 v37, v36, v36
	v_mul_f32_e32 v39, v39, v39
	v_fmac_f32_e32 v45, v44, v44
	global_store_dwordx4 v[40:41], v[26:29], off nt
	v_fmac_f32_e32 v39, v38, v38
	s_nop 0
	v_add_f32_e32 v26, v43, v37
	v_add_f32_e32 v26, v45, v26
	v_add_f32_e32 v36, v39, v26
	s_waitcnt vmcnt(14)
	v_lshlrev_b32_e32 v26, 16, v216
	v_and_b32_e32 v27, 0xffff0000, v216
	v_lshlrev_b32_e32 v28, 16, v217
	v_and_b32_e32 v29, 0xffff0000, v217
	v_lshlrev_b32_e32 v30, 16, v218
	v_and_b32_e32 v31, 0xffff0000, v218
	v_pk_add_f32 v[24:25], v[24:25], v[28:29]
	v_pk_add_f32 v[22:23], v[22:23], v[26:27]
	v_lshlrev_b32_e32 v32, 16, v219
	v_and_b32_e32 v33, 0xffff0000, v219
	v_pk_add_f32 v[28:29], v[18:19], v[30:31]
	v_mul_f32_e32 v30, v23, v23
	v_mul_f32_e32 v31, v25, v25
	v_pk_add_f32 v[26:27], v[20:21], v[32:33]
	v_mul_f32_e32 v32, v29, v29
	v_cvt_pk_bf16_f32 v18, v22, v23
	v_fmac_f32_e32 v30, v22, v22
	v_fmac_f32_e32 v31, v24, v24
	v_mul_f32_e32 v33, v27, v27
	v_cvt_pk_bf16_f32 v19, v24, v25
	v_cvt_pk_bf16_f32 v20, v28, v29
	v_cvt_pk_bf16_f32 v21, v26, v27
	v_fmac_f32_e32 v32, v28, v28
	global_store_dwordx4 v[40:41], v[18:21], off offset:256 nt
	v_fmac_f32_e32 v33, v26, v26
	s_nop 0
	v_add_f32_e32 v18, v30, v31
	v_add_f32_e32 v18, v32, v18
	v_add_f32_e32 v18, v33, v18
	v_add_f32_e32 v18, v36, v18
	v_mov_b32_e32 v19, v18
	s_nop 1
	v_permlane32_swap_b32_e32 v18, v19
	v_add_f32_e32 v18, v18, v19
	v_mov_b32_e32 v19, v18
	s_nop 1
	v_permlane16_swap_b32_e32 v18, v19
	s_and_saveexec_b64 s[26:27], vcc
	s_cbranch_execz .LBB0_1315
	v_add_f32_e32 v20, v18, v19
	v_lshlrev_b64 v[18:19], 6, v[34:35]
	v_lshl_add_u64 v[18:19], s[16:17], 0, v[18:19]
	v_lshl_add_u64 v[18:19], s[24:25], 2, v[18:19]
	s_lshl_b32 s86, s33, 2
	v_lshl_add_u64 v[18:19], v[18:19], 0, s[86:87]
	global_store_dword v[18:19], v20, off
.LBB0_1315:
	s_or_b64 exec, exec, s[26:27]
	v_add_u32_e32 v18, 0xb0, v144
	v_ashrrev_i32_e32 v19, 31, v18
	v_lshlrev_b64 v[20:21], 11, v[18:19]
	v_lshl_add_u64 v[20:21], s[12:13], 0, v[20:21]
	v_lshl_add_u64 v[24:25], v[142:143], 1, v[20:21]
	s_waitcnt vmcnt(12)
	v_lshlrev_b32_e32 v26, 16, v220
	v_and_b32_e32 v27, 0xffff0000, v220
	v_lshlrev_b32_e32 v20, 16, v221
	v_and_b32_e32 v21, 0xffff0000, v221
	v_lshlrev_b32_e32 v28, 16, v222
	v_and_b32_e32 v29, 0xffff0000, v222
	v_lshlrev_b32_e32 v22, 16, v223
	v_and_b32_e32 v23, 0xffff0000, v223
	v_pk_add_f32 v[20:21], v[16:17], v[20:21]
	v_pk_add_f32 v[26:27], v[14:15], v[26:27]
	v_pk_add_f32 v[22:23], v[12:13], v[22:23]
	v_pk_add_f32 v[28:29], v[10:11], v[28:29]
	v_cvt_pk_bf16_f32 v10, v26, v27
	v_cvt_pk_bf16_f32 v11, v20, v21
	v_mul_f32_e32 v27, v27, v27
	v_cvt_pk_bf16_f32 v12, v28, v29
	v_cvt_pk_bf16_f32 v13, v22, v23
	v_mul_f32_e32 v21, v21, v21
	v_mul_f32_e32 v29, v29, v29
	v_fmac_f32_e32 v27, v26, v26
	v_fmac_f32_e32 v21, v20, v20
	v_mul_f32_e32 v23, v23, v23
	v_fmac_f32_e32 v29, v28, v28
	global_store_dwordx4 v[24:25], v[10:13], off nt
	v_fmac_f32_e32 v23, v22, v22
	s_nop 0
	v_add_f32_e32 v10, v27, v21
	v_add_f32_e32 v10, v29, v10
	v_add_f32_e32 v20, v23, v10
	s_waitcnt vmcnt(12)
	v_lshlrev_b32_e32 v10, 16, v224
	v_and_b32_e32 v11, 0xffff0000, v224
	v_lshlrev_b32_e32 v12, 16, v225
	v_and_b32_e32 v13, 0xffff0000, v225
	v_lshlrev_b32_e32 v14, 16, v226
	v_and_b32_e32 v15, 0xffff0000, v226
	v_pk_add_f32 v[8:9], v[8:9], v[12:13]
	v_pk_add_f32 v[6:7], v[6:7], v[10:11]
	v_lshlrev_b32_e32 v16, 16, v227
	v_and_b32_e32 v17, 0xffff0000, v227
	v_pk_add_f32 v[12:13], v[2:3], v[14:15]
	v_mul_f32_e32 v14, v7, v7
	v_mul_f32_e32 v15, v9, v9
	v_pk_add_f32 v[10:11], v[4:5], v[16:17]
	v_mul_f32_e32 v16, v13, v13
	v_cvt_pk_bf16_f32 v2, v6, v7
	v_fmac_f32_e32 v14, v6, v6
	v_fmac_f32_e32 v15, v8, v8
	v_mul_f32_e32 v17, v11, v11
	v_cvt_pk_bf16_f32 v3, v8, v9
	v_cvt_pk_bf16_f32 v4, v12, v13
	v_cvt_pk_bf16_f32 v5, v10, v11
	v_fmac_f32_e32 v16, v12, v12
	global_store_dwordx4 v[24:25], v[2:5], off offset:256 nt
	v_fmac_f32_e32 v17, v10, v10
	s_nop 0
	v_add_f32_e32 v2, v14, v15
	v_add_f32_e32 v2, v16, v2
	v_add_f32_e32 v2, v17, v2
	v_add_f32_e32 v2, v20, v2
	v_mov_b32_e32 v3, v2
	s_nop 1
	v_permlane32_swap_b32_e32 v2, v3
	v_add_f32_e32 v2, v2, v3
	v_mov_b32_e32 v3, v2
	s_nop 1
	v_permlane16_swap_b32_e32 v2, v3
	s_and_saveexec_b64 s[26:27], vcc
	s_cbranch_execz .LBB0_1317
	v_add_f32_e32 v4, v2, v3
	v_lshlrev_b64 v[2:3], 6, v[18:19]
	v_lshl_add_u64 v[2:3], s[16:17], 0, v[2:3]
	v_lshl_add_u64 v[2:3], s[24:25], 2, v[2:3]
	s_lshl_b32 s86, s33, 2
	v_lshl_add_u64 v[2:3], v[2:3], 0, s[86:87]
	global_store_dword v[2:3], v4, off
